# speedup vs baseline: 1.0061x; 1.0001x over previous
; #define STAGE(Pp, BASE, br, kt) do { const u16* _g = (BASE) + ((long)(br) * K + (long)(kt) * BK); \
;     __builtin_amdgcn_global_load_lds((const unsigned*)(_g + voff0), (unsigned*)((char*)(Pp) + tb16), 16, 0, 0); \
;     __builtin_amdgcn_global_load_lds((const unsigned*)(_g + voff1), (unsigned*)((char*)(Pp) + tb16 + 8192), 16, 0, 0); } while (0)
; #define LDA(dst, b, h) _Pragma("unroll") for (int m = 0; m < 4; ++m) _Pragma("unroll") for (int k = 0; k < 2; ++k) \
;     dst[m][k] = *reinterpret_cast<const bf16x8*>((const char*)shm + aB + (((b) * 2 + (h)) * 16384 + (m * 2 + k) * 1024))
; #define LDB(dst, b, h) _Pragma("unroll") for (int n = 0; n < 2; ++n) _Pragma("unroll") for (int k = 0; k < 2; ++k) \
;     dst[n][k] = *reinterpret_cast<const bf16x8*>((const char*)shm + bB + (((b) * 2 + (h)) * 16384 + (n * 2 + k) * 1024))
; #define WAIT_V(n) asm volatile("s_waitcnt vmcnt(" #n ")" ::: "memory")
; #define WAIT_L(n) asm volatile("s_waitcnt lgkmcnt(" #n ")" ::: "memory")
; #define BAR __builtin_amdgcn_s_barrier()
; #define SCHED __builtin_amdgcn_sched_barrier(0)
; template <int MODE> ...
;     ...
;     for (int t = 0; t < nt - 2; t += 2) {
;       LDB(B0, 0, 0); LDB(B1, 0, 1); LDA(At, 0, 0); STAGE(SA(1, 1), A, brow + HALF, t + 1);
;       WAIT_L(0); BAR; MMA2(0, 0, 0, 1); BAR; SCHED;
;       LDA(At, 0, 1); STAGE(SB(0, 0), Bt, bcol, t + 2); STAGE(SB(0, 1), Bt, bcol + HALF, t + 2); STAGE(SA(0, 0), A, brow, t + 2);
;       WAIT_V(6); WAIT_L(0); BAR; MMA2(1, 0, 1, 1); BAR; SCHED;
.LBB0_154:
	s_add_u32 s71, s32, 0xc000
	s_mov_b32 m0, s71
	ds_read_b128 v[170:173], v149
	ds_read_b128 v[174:177], v149 offset:1024
	ds_read_b128 v[178:181], v149 offset:2048
	ds_read_b128 v[182:185], v149 offset:3072
	ds_read_b128 v[186:189], v149 offset:16384
	ds_read_b128 v[190:193], v149 offset:17408
	ds_read_b128 v[194:197], v149 offset:18432
	ds_read_b128 v[198:201], v149 offset:19456
	ds_read_b128 v[202:205], v151
	ds_read_b128 v[206:209], v151 offset:1024
	ds_read_b128 v[210:213], v151 offset:2048
	ds_read_b128 v[214:217], v151 offset:3072
	ds_read_b128 v[218:221], v151 offset:4096
	ds_read_b128 v[222:225], v151 offset:5120
	ds_read_b128 v[226:229], v151 offset:6144
	ds_read_b128 v[230:233], v151 offset:7168
	s_add_u32 s88, s74, s40
	s_addc_u32 s89, s75, s41
	global_load_lds_dwordx4 v142, s[88:89]
	s_add_u32 s71, s32, 0xe000
	s_mov_b32 m0, s71
	s_nop 0
	s_add_u32 s90, s74, s40
	s_addc_u32 s91, s75, s41
	global_load_lds_dwordx4 v144, s[90:91]
	s_waitcnt vmcnt(8)
	s_waitcnt lgkmcnt(0)
	s_setprio 1
	s_barrier
	v_mfma_f32_16x16x32_bf16 v[124:127], v[202:205], v[170:173], v[124:127]
	v_mfma_f32_16x16x32_bf16 v[120:123], v[202:205], v[178:181], v[120:123]
	v_mfma_f32_16x16x32_bf16 v[116:119], v[210:213], v[170:173], v[116:119]
	v_mfma_f32_16x16x32_bf16 v[112:115], v[210:213], v[178:181], v[112:115]
	v_mfma_f32_16x16x32_bf16 v[108:111], v[218:221], v[170:173], v[108:111]
	v_mfma_f32_16x16x32_bf16 v[104:107], v[218:221], v[178:181], v[104:107]
	v_mfma_f32_16x16x32_bf16 v[100:103], v[226:229], v[170:173], v[100:103]
	v_mfma_f32_16x16x32_bf16 v[96:99], v[226:229], v[178:181], v[96:99]
	v_mfma_f32_16x16x32_bf16 v[92:95], v[202:205], v[186:189], v[92:95]
	v_mfma_f32_16x16x32_bf16 v[88:91], v[202:205], v[194:197], v[88:91]
	v_mfma_f32_16x16x32_bf16 v[84:87], v[210:213], v[186:189], v[84:87]
	v_mfma_f32_16x16x32_bf16 v[80:83], v[210:213], v[194:197], v[80:83]
	v_mfma_f32_16x16x32_bf16 v[76:79], v[218:221], v[186:189], v[76:79]
	v_mfma_f32_16x16x32_bf16 v[72:75], v[218:221], v[194:197], v[72:75]
	v_mfma_f32_16x16x32_bf16 v[68:71], v[226:229], v[186:189], v[68:71]
	v_mfma_f32_16x16x32_bf16 v[64:67], v[226:229], v[194:197], v[64:67]
	v_mfma_f32_16x16x32_bf16 v[124:127], v[206:209], v[174:177], v[124:127]
	v_mfma_f32_16x16x32_bf16 v[120:123], v[206:209], v[182:185], v[120:123]
	v_mfma_f32_16x16x32_bf16 v[116:119], v[214:217], v[174:177], v[116:119]
	v_mfma_f32_16x16x32_bf16 v[112:115], v[214:217], v[182:185], v[112:115]
	v_mfma_f32_16x16x32_bf16 v[108:111], v[222:225], v[174:177], v[108:111]
	v_mfma_f32_16x16x32_bf16 v[104:107], v[222:225], v[182:185], v[104:107]
	v_mfma_f32_16x16x32_bf16 v[100:103], v[230:233], v[174:177], v[100:103]
	v_mfma_f32_16x16x32_bf16 v[96:99], v[230:233], v[182:185], v[96:99]
	v_mfma_f32_16x16x32_bf16 v[92:95], v[206:209], v[190:193], v[92:95]
	v_mfma_f32_16x16x32_bf16 v[88:91], v[206:209], v[198:201], v[88:91]
	v_mfma_f32_16x16x32_bf16 v[84:87], v[214:217], v[190:193], v[84:87]
	v_mfma_f32_16x16x32_bf16 v[80:83], v[214:217], v[198:201], v[80:83]
	v_mfma_f32_16x16x32_bf16 v[76:79], v[222:225], v[190:193], v[76:79]
	v_mfma_f32_16x16x32_bf16 v[72:75], v[222:225], v[198:201], v[72:75]
	v_mfma_f32_16x16x32_bf16 v[68:71], v[230:233], v[190:193], v[68:71]
	v_mfma_f32_16x16x32_bf16 v[64:67], v[230:233], v[198:201], v[64:67]
	s_barrier
	s_setprio 0
	s_add_u32 s71, s32, 0x10000
	s_mov_b32 m0, s71
	ds_read_b128 v[202:205], v151 offset:16384
	ds_read_b128 v[206:209], v151 offset:17408
	ds_read_b128 v[210:213], v151 offset:18432
	ds_read_b128 v[214:217], v151 offset:19456
	ds_read_b128 v[218:221], v151 offset:20480
	ds_read_b128 v[222:225], v151 offset:21504
	ds_read_b128 v[226:229], v151 offset:22528
	ds_read_b128 v[230:233], v151 offset:23552
	s_add_u32 s92, s74, s42
	s_addc_u32 s93, s75, s43
	global_load_lds_dwordx4 v138, s[92:93]
	s_add_u32 s71, s32, 0x12000
	s_mov_b32 m0, s71
	s_add_u32 s71, s32, 0x14000
	s_add_u32 s96, s74, s42
	s_addc_u32 s97, s75, s43
	global_load_lds_dwordx4 v140, s[96:97]
	s_mov_b32 m0, s71
	s_add_u32 s71, s32, 0x16000
	s_add_u32 s88, s74, s44
	s_addc_u32 s89, s75, s45
	global_load_lds_dwordx4 v138, s[88:89]
	s_mov_b32 m0, s71
	s_mov_b32 s71, s32
	s_add_u32 s90, s74, s44
	s_addc_u32 s91, s75, s45
	global_load_lds_dwordx4 v140, s[90:91]
	s_mov_b32 m0, s71
	s_add_u32 s71, s32, 0x2000
	s_add_u32 s92, s74, s48
	s_addc_u32 s93, s75, s49
	global_load_lds_dwordx4 v142, s[92:93]
	s_mov_b32 m0, s71
	s_nop 0
	s_add_u32 s96, s74, s48
	s_addc_u32 s97, s75, s49
	global_load_lds_dwordx4 v144, s[96:97]
	s_waitcnt vmcnt(8)
	s_waitcnt lgkmcnt(0)
	s_setprio 1
	s_barrier
; #define STAGE(Pp, BASE, br, kt) do { const u16* _g = (BASE) + ((long)(br) * K + (long)(kt) * BK); \
;     __builtin_amdgcn_global_load_lds((const unsigned*)(_g + voff0), (unsigned*)((char*)(Pp) + tb16), 16, 0, 0); \
;     __builtin_amdgcn_global_load_lds((const unsigned*)(_g + voff1), (unsigned*)((char*)(Pp) + tb16 + 8192), 16, 0, 0); } while (0)
; #define LDA(dst, b, h) _Pragma("unroll") for (int m = 0; m < 4; ++m) _Pragma("unroll") for (int k = 0; k < 2; ++k) \
;     dst[m][k] = *reinterpret_cast<const bf16x8*>((const char*)shm + aB + (((b) * 2 + (h)) * 16384 + (m * 2 + k) * 1024))
; #define LDB(dst, b, h) _Pragma("unroll") for (int n = 0; n < 2; ++n) _Pragma("unroll") for (int k = 0; k < 2; ++k) \
;     dst[n][k] = *reinterpret_cast<const bf16x8*>((const char*)shm + bB + (((b) * 2 + (h)) * 16384 + (n * 2 + k) * 1024))
; #define WAIT_V(n) asm volatile("s_waitcnt vmcnt(" #n ")" ::: "memory")
; #define WAIT_L(n) asm volatile("s_waitcnt lgkmcnt(" #n ")" ::: "memory")
; #define BAR __builtin_amdgcn_s_barrier()
; #define SCHED __builtin_amdgcn_sched_barrier(0)
; template <int MODE> ...
;     ...
;       WAIT_V(6); WAIT_L(0); BAR; MMA2(1, 0, 1, 1); BAR; SCHED;
;       LDB(B0, 1, 0); LDB(B1, 1, 1); LDA(At, 1, 0); STAGE(SA(0, 1), A, brow + HALF, t + 2);
;       WAIT_L(0); BAR; MMA2(0, 0, 0, 1); BAR; SCHED;
	v_mfma_f32_16x16x32_bf16 v[60:63], v[202:205], v[170:173], v[60:63]
	v_mfma_f32_16x16x32_bf16 v[56:59], v[202:205], v[178:181], v[56:59]
	v_mfma_f32_16x16x32_bf16 v[52:55], v[210:213], v[170:173], v[52:55]
	v_mfma_f32_16x16x32_bf16 v[48:51], v[210:213], v[178:181], v[48:51]
	v_mfma_f32_16x16x32_bf16 v[44:47], v[218:221], v[170:173], v[44:47]
	v_mfma_f32_16x16x32_bf16 v[40:43], v[218:221], v[178:181], v[40:43]
	v_mfma_f32_16x16x32_bf16 v[36:39], v[226:229], v[170:173], v[36:39]
	v_mfma_f32_16x16x32_bf16 v[32:35], v[226:229], v[178:181], v[32:35]
	v_mfma_f32_16x16x32_bf16 v[28:31], v[202:205], v[186:189], v[28:31]
	v_mfma_f32_16x16x32_bf16 v[24:27], v[202:205], v[194:197], v[24:27]
	v_mfma_f32_16x16x32_bf16 v[20:23], v[210:213], v[186:189], v[20:23]
	v_mfma_f32_16x16x32_bf16 v[16:19], v[210:213], v[194:197], v[16:19]
	v_mfma_f32_16x16x32_bf16 v[12:15], v[218:221], v[186:189], v[12:15]
	v_mfma_f32_16x16x32_bf16 v[8:11], v[218:221], v[194:197], v[8:11]
	v_mfma_f32_16x16x32_bf16 v[4:7], v[226:229], v[186:189], v[4:7]
	v_mfma_f32_16x16x32_bf16 v[0:3], v[226:229], v[194:197], v[0:3]
	v_mfma_f32_16x16x32_bf16 v[60:63], v[206:209], v[174:177], v[60:63]
	v_mfma_f32_16x16x32_bf16 v[56:59], v[206:209], v[182:185], v[56:59]
	v_mfma_f32_16x16x32_bf16 v[52:55], v[214:217], v[174:177], v[52:55]
	v_mfma_f32_16x16x32_bf16 v[48:51], v[214:217], v[182:185], v[48:51]
	v_mfma_f32_16x16x32_bf16 v[44:47], v[222:225], v[174:177], v[44:47]
	v_mfma_f32_16x16x32_bf16 v[40:43], v[222:225], v[182:185], v[40:43]
	v_mfma_f32_16x16x32_bf16 v[36:39], v[230:233], v[174:177], v[36:39]
	v_mfma_f32_16x16x32_bf16 v[32:35], v[230:233], v[182:185], v[32:35]
	v_mfma_f32_16x16x32_bf16 v[28:31], v[206:209], v[190:193], v[28:31]
	v_mfma_f32_16x16x32_bf16 v[24:27], v[206:209], v[198:201], v[24:27]
	v_mfma_f32_16x16x32_bf16 v[20:23], v[214:217], v[190:193], v[20:23]
	v_mfma_f32_16x16x32_bf16 v[16:19], v[214:217], v[198:201], v[16:19]
	v_mfma_f32_16x16x32_bf16 v[12:15], v[222:225], v[190:193], v[12:15]
	v_mfma_f32_16x16x32_bf16 v[8:11], v[222:225], v[198:201], v[8:11]
	v_mfma_f32_16x16x32_bf16 v[4:7], v[230:233], v[190:193], v[4:7]
	v_mfma_f32_16x16x32_bf16 v[0:3], v[230:233], v[198:201], v[0:3]
	s_barrier
	s_setprio 0
	s_add_u32 s71, s32, 0x4000
	s_mov_b32 m0, s71
	s_add_u32 s71, s32, 0x6000
	ds_read_b128 v[170:173], v149 offset:32768
	ds_read_b128 v[174:177], v149 offset:33792
	ds_read_b128 v[178:181], v149 offset:34816
	ds_read_b128 v[182:185], v149 offset:35840
	ds_read_b128 v[186:189], v149 offset:49152
	ds_read_b128 v[190:193], v149 offset:50176
	ds_read_b128 v[194:197], v149 offset:51200
	ds_read_b128 v[198:201], v149 offset:52224
	ds_read_b128 v[202:205], v151 offset:32768
	ds_read_b128 v[206:209], v151 offset:33792
	ds_read_b128 v[210:213], v151 offset:34816
	ds_read_b128 v[214:217], v151 offset:35840
	ds_read_b128 v[218:221], v151 offset:36864
	ds_read_b128 v[222:225], v151 offset:37888
	ds_read_b128 v[226:229], v151 offset:38912
	ds_read_b128 v[230:233], v151 offset:39936
	s_add_u32 s88, s74, s50
	s_addc_u32 s89, s75, s51
	global_load_lds_dwordx4 v142, s[88:89]
	s_mov_b32 m0, s71
	s_nop 0
	s_add_u32 s90, s74, s50
	s_addc_u32 s91, s75, s51
	global_load_lds_dwordx4 v144, s[90:91]
	s_waitcnt vmcnt(8)
	s_waitcnt lgkmcnt(0)
	s_setprio 1
	s_barrier
	v_mfma_f32_16x16x32_bf16 v[124:127], v[202:205], v[170:173], v[124:127]
	v_mfma_f32_16x16x32_bf16 v[120:123], v[202:205], v[178:181], v[120:123]
	v_mfma_f32_16x16x32_bf16 v[116:119], v[210:213], v[170:173], v[116:119]
	v_mfma_f32_16x16x32_bf16 v[112:115], v[210:213], v[178:181], v[112:115]
	v_mfma_f32_16x16x32_bf16 v[108:111], v[218:221], v[170:173], v[108:111]
	v_mfma_f32_16x16x32_bf16 v[104:107], v[218:221], v[178:181], v[104:107]
	v_mfma_f32_16x16x32_bf16 v[100:103], v[226:229], v[170:173], v[100:103]
	v_mfma_f32_16x16x32_bf16 v[96:99], v[226:229], v[178:181], v[96:99]
	v_mfma_f32_16x16x32_bf16 v[92:95], v[202:205], v[186:189], v[92:95]
	v_mfma_f32_16x16x32_bf16 v[88:91], v[202:205], v[194:197], v[88:91]
	v_mfma_f32_16x16x32_bf16 v[84:87], v[210:213], v[186:189], v[84:87]
	v_mfma_f32_16x16x32_bf16 v[80:83], v[210:213], v[194:197], v[80:83]
	v_mfma_f32_16x16x32_bf16 v[76:79], v[218:221], v[186:189], v[76:79]
	v_mfma_f32_16x16x32_bf16 v[72:75], v[218:221], v[194:197], v[72:75]
	v_mfma_f32_16x16x32_bf16 v[68:71], v[226:229], v[186:189], v[68:71]
	v_mfma_f32_16x16x32_bf16 v[64:67], v[226:229], v[194:197], v[64:67]
	v_mfma_f32_16x16x32_bf16 v[124:127], v[206:209], v[174:177], v[124:127]
	v_mfma_f32_16x16x32_bf16 v[120:123], v[206:209], v[182:185], v[120:123]
	v_mfma_f32_16x16x32_bf16 v[116:119], v[214:217], v[174:177], v[116:119]
	v_mfma_f32_16x16x32_bf16 v[112:115], v[214:217], v[182:185], v[112:115]
	v_mfma_f32_16x16x32_bf16 v[108:111], v[222:225], v[174:177], v[108:111]
	v_mfma_f32_16x16x32_bf16 v[104:107], v[222:225], v[182:185], v[104:107]
	v_mfma_f32_16x16x32_bf16 v[100:103], v[230:233], v[174:177], v[100:103]
	v_mfma_f32_16x16x32_bf16 v[96:99], v[230:233], v[182:185], v[96:99]
	v_mfma_f32_16x16x32_bf16 v[92:95], v[206:209], v[190:193], v[92:95]
	v_mfma_f32_16x16x32_bf16 v[88:91], v[206:209], v[198:201], v[88:91]
	v_mfma_f32_16x16x32_bf16 v[84:87], v[214:217], v[190:193], v[84:87]
	v_mfma_f32_16x16x32_bf16 v[80:83], v[214:217], v[198:201], v[80:83]
	v_mfma_f32_16x16x32_bf16 v[76:79], v[222:225], v[190:193], v[76:79]
	v_mfma_f32_16x16x32_bf16 v[72:75], v[222:225], v[198:201], v[72:75]
	v_mfma_f32_16x16x32_bf16 v[68:71], v[230:233], v[190:193], v[68:71]
	v_mfma_f32_16x16x32_bf16 v[64:67], v[230:233], v[198:201], v[64:67]
	s_barrier
; #define STAGE(Pp, BASE, br, kt) do { const u16* _g = (BASE) + ((long)(br) * K + (long)(kt) * BK); \
;     __builtin_amdgcn_global_load_lds((const unsigned*)(_g + voff0), (unsigned*)((char*)(Pp) + tb16), 16, 0, 0); \
;     __builtin_amdgcn_global_load_lds((const unsigned*)(_g + voff1), (unsigned*)((char*)(Pp) + tb16 + 8192), 16, 0, 0); } while (0)
; #define LDA(dst, b, h) _Pragma("unroll") for (int m = 0; m < 4; ++m) _Pragma("unroll") for (int k = 0; k < 2; ++k) \
;     dst[m][k] = *reinterpret_cast<const bf16x8*>((const char*)shm + aB + (((b) * 2 + (h)) * 16384 + (m * 2 + k) * 1024))
; #define LDB(dst, b, h) _Pragma("unroll") for (int n = 0; n < 2; ++n) _Pragma("unroll") for (int k = 0; k < 2; ++k) \
;     dst[n][k] = *reinterpret_cast<const bf16x8*>((const char*)shm + bB + (((b) * 2 + (h)) * 16384 + (n * 2 + k) * 1024))
; #define WAIT_V(n) asm volatile("s_waitcnt vmcnt(" #n ")" ::: "memory")
; #define WAIT_L(n) asm volatile("s_waitcnt lgkmcnt(" #n ")" ::: "memory")
; #define BAR __builtin_amdgcn_s_barrier()
; #define SCHED __builtin_amdgcn_sched_barrier(0)
; template <int MODE> ...
;     ...
;       LDA(At, 1, 1); STAGE(SB(1, 0), Bt, bcol, t + 3); STAGE(SB(1, 1), Bt, bcol + HALF, t + 3); STAGE(SA(1, 0), A, brow, t + 3);
;       WAIT_V(6); WAIT_L(0); BAR; MMA2(1, 0, 1, 1); BAR; SCHED;
;     }
;     {
;       LDB(B0, 0, 0); LDB(B1, 0, 1); LDA(At, 0, 0); STAGE(SA(1, 1), A, brow + HALF, nt - 1);
;       WAIT_L(0); BAR; MMA2(0, 0, 0, 1); BAR; SCHED;
	s_setprio 0
	s_add_u32 s71, s32, 0x18000
	s_mov_b32 m0, s71
	s_add_u32 s71, s32, 0x1a000
	ds_read_b128 v[202:205], v151 offset:49152
	ds_read_b128 v[206:209], v151 offset:50176
	ds_read_b128 v[210:213], v151 offset:51200
	ds_read_b128 v[214:217], v151 offset:52224
	ds_read_b128 v[218:221], v151 offset:53248
	ds_read_b128 v[222:225], v151 offset:54272
	ds_read_b128 v[226:229], v151 offset:55296
	ds_read_b128 v[230:233], v151 offset:56320
	s_add_u32 s92, s74, s60
	s_addc_u32 s93, s75, s61
	global_load_lds_dwordx4 v138, s[92:93]
	s_mov_b32 m0, s71
	s_add_u32 s71, s32, 0x1c000
	s_add_u32 s96, s74, s60
	s_addc_u32 s97, s75, s61
	global_load_lds_dwordx4 v140, s[96:97]
	s_mov_b32 m0, s71
	s_add_u32 s71, s32, 0x1e000
	s_add_u32 s88, s74, s62
	s_addc_u32 s89, s75, s63
	global_load_lds_dwordx4 v138, s[88:89]
	s_mov_b32 m0, s71
	s_add_u32 s71, s32, 0x8000
	s_add_u32 s90, s74, s62
	s_addc_u32 s91, s75, s63
	global_load_lds_dwordx4 v140, s[90:91]
	s_mov_b32 m0, s71
	s_add_u32 s71, s32, 0xa000
	s_add_u32 s92, s74, s64
	s_addc_u32 s93, s75, s65
	global_load_lds_dwordx4 v142, s[92:93]
	s_mov_b32 m0, s71
	s_nop 0
	s_add_u32 s96, s74, s64
	s_addc_u32 s97, s75, s65
	global_load_lds_dwordx4 v144, s[96:97]
	s_waitcnt vmcnt(8)
	s_waitcnt lgkmcnt(0)
	s_setprio 1
	s_barrier
	v_mfma_f32_16x16x32_bf16 v[60:63], v[202:205], v[170:173], v[60:63]
	v_mfma_f32_16x16x32_bf16 v[56:59], v[202:205], v[178:181], v[56:59]
	v_mfma_f32_16x16x32_bf16 v[52:55], v[210:213], v[170:173], v[52:55]
	v_mfma_f32_16x16x32_bf16 v[48:51], v[210:213], v[178:181], v[48:51]
	v_mfma_f32_16x16x32_bf16 v[44:47], v[218:221], v[170:173], v[44:47]
	v_mfma_f32_16x16x32_bf16 v[40:43], v[218:221], v[178:181], v[40:43]
	v_mfma_f32_16x16x32_bf16 v[36:39], v[226:229], v[170:173], v[36:39]
	v_mfma_f32_16x16x32_bf16 v[32:35], v[226:229], v[178:181], v[32:35]
	v_mfma_f32_16x16x32_bf16 v[28:31], v[202:205], v[186:189], v[28:31]
	v_mfma_f32_16x16x32_bf16 v[24:27], v[202:205], v[194:197], v[24:27]
	v_mfma_f32_16x16x32_bf16 v[20:23], v[210:213], v[186:189], v[20:23]
	v_mfma_f32_16x16x32_bf16 v[16:19], v[210:213], v[194:197], v[16:19]
	v_mfma_f32_16x16x32_bf16 v[12:15], v[218:221], v[186:189], v[12:15]
	v_mfma_f32_16x16x32_bf16 v[8:11], v[218:221], v[194:197], v[8:11]
	v_mfma_f32_16x16x32_bf16 v[4:7], v[226:229], v[186:189], v[4:7]
	v_mfma_f32_16x16x32_bf16 v[0:3], v[226:229], v[194:197], v[0:3]
	v_mfma_f32_16x16x32_bf16 v[60:63], v[206:209], v[174:177], v[60:63]
	v_mfma_f32_16x16x32_bf16 v[56:59], v[206:209], v[182:185], v[56:59]
	v_mfma_f32_16x16x32_bf16 v[52:55], v[214:217], v[174:177], v[52:55]
	v_mfma_f32_16x16x32_bf16 v[48:51], v[214:217], v[182:185], v[48:51]
	v_mfma_f32_16x16x32_bf16 v[44:47], v[222:225], v[174:177], v[44:47]
	v_mfma_f32_16x16x32_bf16 v[40:43], v[222:225], v[182:185], v[40:43]
	v_mfma_f32_16x16x32_bf16 v[36:39], v[230:233], v[174:177], v[36:39]
	v_mfma_f32_16x16x32_bf16 v[32:35], v[230:233], v[182:185], v[32:35]
	v_mfma_f32_16x16x32_bf16 v[28:31], v[206:209], v[190:193], v[28:31]
	v_mfma_f32_16x16x32_bf16 v[24:27], v[206:209], v[198:201], v[24:27]
	v_mfma_f32_16x16x32_bf16 v[20:23], v[214:217], v[190:193], v[20:23]
	v_mfma_f32_16x16x32_bf16 v[16:19], v[214:217], v[198:201], v[16:19]
	v_mfma_f32_16x16x32_bf16 v[12:15], v[222:225], v[190:193], v[12:15]
	v_mfma_f32_16x16x32_bf16 v[8:11], v[222:225], v[198:201], v[8:11]
	v_mfma_f32_16x16x32_bf16 v[4:7], v[230:233], v[190:193], v[4:7]
	v_mfma_f32_16x16x32_bf16 v[0:3], v[230:233], v[198:201], v[0:3]
	s_barrier
	s_setprio 0
	s_add_i32 s69, s69, 2
	s_add_u32 s74, s74, 0x100
	s_addc_u32 s75, s75, 0
	s_cmp_lt_u32 s69, 60
	s_cbranch_scc1 .LBB0_154
	s_add_u32 s72, s72, 0x1f80
	v_readfirstlane_b32 s69, v167
	s_addc_u32 s73, s73, 0
	s_mov_b32 m0, s69
	v_readfirstlane_b32 s69, v168
	ds_read_b128 v[138:141], v149
	ds_read_b128 v[142:145], v149 offset:1024
	ds_read_b128 v[170:173], v149 offset:2048
	ds_read_b128 v[174:177], v149 offset:3072
	ds_read_b128 v[178:181], v149 offset:16384
	ds_read_b128 v[182:185], v149 offset:17408
	ds_read_b128 v[186:189], v149 offset:18432
	ds_read_b128 v[190:193], v149 offset:19456
	ds_read_b128 v[194:197], v151
	ds_read_b128 v[198:201], v151 offset:1024
	ds_read_b128 v[202:205], v151 offset:2048
	ds_read_b128 v[206:209], v151 offset:3072
	ds_read_b128 v[210:213], v151 offset:4096
	ds_read_b128 v[214:217], v151 offset:5120
	ds_read_b128 v[218:221], v151 offset:6144
	ds_read_b128 v[222:225], v151 offset:7168
	global_load_lds_dwordx4 v134, s[72:73]
	s_mov_b32 m0, s69
	s_nop 0
	global_load_lds_dwordx4 v136, s[72:73]
	s_waitcnt vmcnt(8)
	s_waitcnt lgkmcnt(0)
	s_setprio 1
	s_barrier
; #define STAGE(Pp, BASE, br, kt) do { const u16* _g = (BASE) + ((long)(br) * K + (long)(kt) * BK); \
;     __builtin_amdgcn_global_load_lds((const unsigned*)(_g + voff0), (unsigned*)((char*)(Pp) + tb16), 16, 0, 0); \
;     __builtin_amdgcn_global_load_lds((const unsigned*)(_g + voff1), (unsigned*)((char*)(Pp) + tb16 + 8192), 16, 0, 0); } while (0)
; #define LDA(dst, b, h) _Pragma("unroll") for (int m = 0; m < 4; ++m) _Pragma("unroll") for (int k = 0; k < 2; ++k) \
;     dst[m][k] = *reinterpret_cast<const bf16x8*>((const char*)shm + aB + (((b) * 2 + (h)) * 16384 + (m * 2 + k) * 1024))
; #define LDB(dst, b, h) _Pragma("unroll") for (int n = 0; n < 2; ++n) _Pragma("unroll") for (int k = 0; k < 2; ++k) \
;     dst[n][k] = *reinterpret_cast<const bf16x8*>((const char*)shm + bB + (((b) * 2 + (h)) * 16384 + (n * 2 + k) * 1024))
; #define WAIT_V(n) asm volatile("s_waitcnt vmcnt(" #n ")" ::: "memory")
; #define WAIT_L(n) asm volatile("s_waitcnt lgkmcnt(" #n ")" ::: "memory")
; #define BAR __builtin_amdgcn_s_barrier()
; #define SCHED __builtin_amdgcn_sched_barrier(0)
; template <int MODE> ...
;     ...
;       LDB(B0, 0, 0); LDB(B1, 0, 1); LDA(At, 0, 0); STAGE(SA(1, 1), A, brow + HALF, nt - 1);
;       WAIT_L(0); BAR; MMA2(0, 0, 0, 1); BAR; SCHED;
;       LDA(At, 0, 1); WAIT_V(0); WAIT_L(0); BAR; MMA2(1, 0, 1, 1); BAR; SCHED;
;       LDB(B0, 1, 0); LDB(B1, 1, 1); LDA(At, 1, 0); WAIT_L(0); BAR; MMA2(0, 0, 0, 1); BAR; SCHED;
	v_mfma_f32_16x16x32_bf16 v[124:127], v[194:197], v[138:141], v[124:127]
	v_mfma_f32_16x16x32_bf16 v[120:123], v[194:197], v[170:173], v[120:123]
	v_mfma_f32_16x16x32_bf16 v[116:119], v[202:205], v[138:141], v[116:119]
	v_mfma_f32_16x16x32_bf16 v[112:115], v[202:205], v[170:173], v[112:115]
	v_mfma_f32_16x16x32_bf16 v[108:111], v[210:213], v[138:141], v[108:111]
	v_mfma_f32_16x16x32_bf16 v[104:107], v[210:213], v[170:173], v[104:107]
	v_mfma_f32_16x16x32_bf16 v[100:103], v[218:221], v[138:141], v[100:103]
	v_mfma_f32_16x16x32_bf16 v[96:99], v[218:221], v[170:173], v[96:99]
	v_mfma_f32_16x16x32_bf16 v[92:95], v[194:197], v[178:181], v[92:95]
	v_mfma_f32_16x16x32_bf16 v[88:91], v[194:197], v[186:189], v[88:91]
	v_mfma_f32_16x16x32_bf16 v[84:87], v[202:205], v[178:181], v[84:87]
	v_mfma_f32_16x16x32_bf16 v[80:83], v[202:205], v[186:189], v[80:83]
	v_mfma_f32_16x16x32_bf16 v[76:79], v[210:213], v[178:181], v[76:79]
	v_mfma_f32_16x16x32_bf16 v[72:75], v[210:213], v[186:189], v[72:75]
	v_mfma_f32_16x16x32_bf16 v[68:71], v[218:221], v[178:181], v[68:71]
	v_mfma_f32_16x16x32_bf16 v[64:67], v[218:221], v[186:189], v[64:67]
	v_mfma_f32_16x16x32_bf16 v[124:127], v[198:201], v[142:145], v[124:127]
	v_mfma_f32_16x16x32_bf16 v[120:123], v[198:201], v[174:177], v[120:123]
	v_mfma_f32_16x16x32_bf16 v[116:119], v[206:209], v[142:145], v[116:119]
	v_mfma_f32_16x16x32_bf16 v[112:115], v[206:209], v[174:177], v[112:115]
	v_mfma_f32_16x16x32_bf16 v[108:111], v[214:217], v[142:145], v[108:111]
	v_mfma_f32_16x16x32_bf16 v[104:107], v[214:217], v[174:177], v[104:107]
	v_mfma_f32_16x16x32_bf16 v[100:103], v[222:225], v[142:145], v[100:103]
	v_mfma_f32_16x16x32_bf16 v[96:99], v[222:225], v[174:177], v[96:99]
	v_mfma_f32_16x16x32_bf16 v[92:95], v[198:201], v[182:185], v[92:95]
	v_mfma_f32_16x16x32_bf16 v[88:91], v[198:201], v[190:193], v[88:91]
	v_mfma_f32_16x16x32_bf16 v[84:87], v[206:209], v[182:185], v[84:87]
	v_mfma_f32_16x16x32_bf16 v[80:83], v[206:209], v[190:193], v[80:83]
	v_mfma_f32_16x16x32_bf16 v[76:79], v[214:217], v[182:185], v[76:79]
	v_mfma_f32_16x16x32_bf16 v[72:75], v[214:217], v[190:193], v[72:75]
	v_mfma_f32_16x16x32_bf16 v[68:71], v[222:225], v[182:185], v[68:71]
	v_mfma_f32_16x16x32_bf16 v[64:67], v[222:225], v[190:193], v[64:67]
	s_barrier
	s_setprio 0
	ds_read_b128 v[194:197], v151 offset:16384
	ds_read_b128 v[198:201], v151 offset:17408
	ds_read_b128 v[202:205], v151 offset:18432
	ds_read_b128 v[206:209], v151 offset:19456
	ds_read_b128 v[210:213], v151 offset:20480
	ds_read_b128 v[214:217], v151 offset:21504
	ds_read_b128 v[218:221], v151 offset:22528
	ds_read_b128 v[222:225], v151 offset:23552
	s_waitcnt vmcnt(0)
	s_waitcnt lgkmcnt(0)
	s_setprio 1
	s_barrier
	v_mfma_f32_16x16x32_bf16 v[56:59], v[194:197], v[170:173], v[56:59]
	v_mfma_f32_16x16x32_bf16 v[52:55], v[202:205], v[138:141], v[52:55]
	v_mfma_f32_16x16x32_bf16 v[48:51], v[202:205], v[170:173], v[48:51]
	v_mfma_f32_16x16x32_bf16 v[44:47], v[210:213], v[138:141], v[44:47]
	v_mfma_f32_16x16x32_bf16 v[40:43], v[210:213], v[170:173], v[40:43]
	v_mfma_f32_16x16x32_bf16 v[36:39], v[218:221], v[138:141], v[36:39]
	v_mfma_f32_16x16x32_bf16 v[32:35], v[218:221], v[170:173], v[32:35]
	v_mfma_f32_16x16x32_bf16 v[28:31], v[194:197], v[178:181], v[28:31]
	v_mfma_f32_16x16x32_bf16 v[24:27], v[194:197], v[186:189], v[24:27]
	v_mfma_f32_16x16x32_bf16 v[20:23], v[202:205], v[178:181], v[20:23]
	v_mfma_f32_16x16x32_bf16 v[16:19], v[202:205], v[186:189], v[16:19]
	v_mfma_f32_16x16x32_bf16 v[12:15], v[210:213], v[178:181], v[12:15]
	v_mfma_f32_16x16x32_bf16 v[8:11], v[210:213], v[186:189], v[8:11]
	v_mfma_f32_16x16x32_bf16 v[4:7], v[218:221], v[178:181], v[4:7]
	v_mfma_f32_16x16x32_bf16 v[0:3], v[218:221], v[186:189], v[0:3]
	v_mfma_f32_16x16x32_bf16 v[60:63], v[194:197], v[138:141], v[60:63]
	v_mfma_f32_16x16x32_bf16 v[56:59], v[198:201], v[174:177], v[56:59]
	v_mfma_f32_16x16x32_bf16 v[52:55], v[206:209], v[142:145], v[52:55]
	v_mfma_f32_16x16x32_bf16 v[48:51], v[206:209], v[174:177], v[48:51]
	v_mfma_f32_16x16x32_bf16 v[44:47], v[214:217], v[142:145], v[44:47]
	v_mfma_f32_16x16x32_bf16 v[40:43], v[214:217], v[174:177], v[40:43]
	v_mfma_f32_16x16x32_bf16 v[36:39], v[222:225], v[142:145], v[36:39]
	v_mfma_f32_16x16x32_bf16 v[32:35], v[222:225], v[174:177], v[32:35]
	v_mfma_f32_16x16x32_bf16 v[28:31], v[198:201], v[182:185], v[28:31]
	v_mfma_f32_16x16x32_bf16 v[24:27], v[198:201], v[190:193], v[24:27]
	v_mfma_f32_16x16x32_bf16 v[20:23], v[206:209], v[182:185], v[20:23]
	v_mfma_f32_16x16x32_bf16 v[16:19], v[206:209], v[190:193], v[16:19]
	v_mfma_f32_16x16x32_bf16 v[12:15], v[214:217], v[182:185], v[12:15]
	v_mfma_f32_16x16x32_bf16 v[8:11], v[214:217], v[190:193], v[8:11]
	v_mfma_f32_16x16x32_bf16 v[4:7], v[222:225], v[182:185], v[4:7]
	v_mfma_f32_16x16x32_bf16 v[0:3], v[222:225], v[190:193], v[0:3]
	v_mfma_f32_16x16x32_bf16 v[226:229], v[198:201], v[142:145], v[60:63]
	s_barrier
	s_setprio 0
	ds_read_b128 v[138:141], v149 offset:32768
	ds_read_b128 v[142:145], v149 offset:33792
	ds_read_b128 v[170:173], v149 offset:34816
	ds_read_b128 v[174:177], v149 offset:35840
	ds_read_b128 v[178:181], v149 offset:49152
	ds_read_b128 v[182:185], v149 offset:50176
	ds_read_b128 v[186:189], v149 offset:51200
	ds_read_b128 v[190:193], v149 offset:52224
	ds_read_b128 v[60:63], v151 offset:32768
	ds_read_b128 v[194:197], v151 offset:33792
	ds_read_b128 v[198:201], v151 offset:34816
	ds_read_b128 v[202:205], v151 offset:35840
	ds_read_b128 v[206:209], v151 offset:36864
	ds_read_b128 v[210:213], v151 offset:37888
	ds_read_b128 v[214:217], v151 offset:38912
	ds_read_b128 v[218:221], v151 offset:39936
	s_waitcnt lgkmcnt(0)
	s_setprio 1
	s_barrier
; #define LDA(dst, b, h) _Pragma("unroll") for (int m = 0; m < 4; ++m) _Pragma("unroll") for (int k = 0; k < 2; ++k) \
;     dst[m][k] = *reinterpret_cast<const bf16x8*>((const char*)shm + aB + (((b) * 2 + (h)) * 16384 + (m * 2 + k) * 1024))
; #define LDB(dst, b, h) _Pragma("unroll") for (int n = 0; n < 2; ++n) _Pragma("unroll") for (int k = 0; k < 2; ++k) \
;     dst[n][k] = *reinterpret_cast<const bf16x8*>((const char*)shm + bB + (((b) * 2 + (h)) * 16384 + (n * 2 + k) * 1024))
; #define WAIT_L(n) asm volatile("s_waitcnt lgkmcnt(" #n ")" ::: "memory")
; #define BAR __builtin_amdgcn_s_barrier()
; #define SCHED __builtin_amdgcn_sched_barrier(0)
; template <int MODE> ...
;     ...
;       LDB(B0, 1, 0); LDB(B1, 1, 1); LDA(At, 1, 0); WAIT_L(0); BAR; MMA2(0, 0, 0, 1); BAR; SCHED;
;       LDA(At, 1, 1); WAIT_L(0); BAR; MMA2(1, 0, 1, 1); BAR; SCHED;
;     }
;     ...
;     if (wr == 0) BAR;
	v_mfma_f32_16x16x32_bf16 v[124:127], v[60:63], v[138:141], v[124:127]
	v_mfma_f32_16x16x32_bf16 v[120:123], v[60:63], v[170:173], v[120:123]
	v_mfma_f32_16x16x32_bf16 v[92:95], v[60:63], v[178:181], v[92:95]
	v_mfma_f32_16x16x32_bf16 v[60:63], v[60:63], v[186:189], v[88:91]
	v_mfma_f32_16x16x32_bf16 v[88:91], v[194:197], v[190:193], v[60:63]
	v_mfma_f32_16x16x32_bf16 v[60:63], v[198:201], v[178:181], v[84:87]
	v_mfma_f32_16x16x32_bf16 v[84:87], v[202:205], v[182:185], v[60:63]
	v_mfma_f32_16x16x32_bf16 v[60:63], v[198:201], v[186:189], v[80:83]
	v_mfma_f32_16x16x32_bf16 v[80:83], v[202:205], v[190:193], v[60:63]
	v_mfma_f32_16x16x32_bf16 v[60:63], v[206:209], v[178:181], v[76:79]
	v_mfma_f32_16x16x32_bf16 v[76:79], v[210:213], v[182:185], v[60:63]
	v_mfma_f32_16x16x32_bf16 v[60:63], v[206:209], v[186:189], v[72:75]
	v_mfma_f32_16x16x32_bf16 v[72:75], v[210:213], v[190:193], v[60:63]
	v_mfma_f32_16x16x32_bf16 v[60:63], v[214:217], v[178:181], v[68:71]
	v_mfma_f32_16x16x32_bf16 v[116:119], v[198:201], v[138:141], v[116:119]
	v_mfma_f32_16x16x32_bf16 v[112:115], v[198:201], v[170:173], v[112:115]
	v_mfma_f32_16x16x32_bf16 v[108:111], v[206:209], v[138:141], v[108:111]
	v_mfma_f32_16x16x32_bf16 v[104:107], v[206:209], v[170:173], v[104:107]
	v_mfma_f32_16x16x32_bf16 v[100:103], v[214:217], v[138:141], v[100:103]
	v_mfma_f32_16x16x32_bf16 v[96:99], v[214:217], v[170:173], v[96:99]
	v_mfma_f32_16x16x32_bf16 v[68:71], v[218:221], v[182:185], v[60:63]
	v_mfma_f32_16x16x32_bf16 v[60:63], v[214:217], v[186:189], v[64:67]
	v_mfma_f32_16x16x32_bf16 v[124:127], v[194:197], v[142:145], v[124:127]
	v_mfma_f32_16x16x32_bf16 v[120:123], v[194:197], v[174:177], v[120:123]
	v_mfma_f32_16x16x32_bf16 v[116:119], v[202:205], v[142:145], v[116:119]
	v_mfma_f32_16x16x32_bf16 v[112:115], v[202:205], v[174:177], v[112:115]
	v_mfma_f32_16x16x32_bf16 v[108:111], v[210:213], v[142:145], v[108:111]
	v_mfma_f32_16x16x32_bf16 v[104:107], v[210:213], v[174:177], v[104:107]
	v_mfma_f32_16x16x32_bf16 v[100:103], v[218:221], v[142:145], v[100:103]
	v_mfma_f32_16x16x32_bf16 v[96:99], v[218:221], v[174:177], v[96:99]
	v_mfma_f32_16x16x32_bf16 v[92:95], v[194:197], v[182:185], v[92:95]
	v_mfma_f32_16x16x32_bf16 v[60:63], v[218:221], v[190:193], v[60:63]
	s_barrier
	s_setprio 0
	ds_read_b128 v[194:197], v151 offset:49152
	ds_read_b128 v[198:201], v151 offset:50176
	ds_read_b128 v[202:205], v151 offset:51200
	ds_read_b128 v[206:209], v151 offset:52224
	ds_read_b128 v[210:213], v151 offset:53248
	ds_read_b128 v[214:217], v151 offset:54272
	ds_read_b128 v[218:221], v151 offset:55296
	ds_read_b128 v[222:225], v151 offset:56320
	s_waitcnt lgkmcnt(0)
	s_setprio 1
	s_barrier
	v_mfma_f32_16x16x32_bf16 v[64:67], v[194:197], v[138:141], v[226:229]
	v_mfma_f32_16x16x32_bf16 v[56:59], v[194:197], v[170:173], v[56:59]
	v_mfma_f32_16x16x32_bf16 v[52:55], v[202:205], v[138:141], v[52:55]
	v_mfma_f32_16x16x32_bf16 v[48:51], v[202:205], v[170:173], v[48:51]
	v_mfma_f32_16x16x32_bf16 v[44:47], v[210:213], v[138:141], v[44:47]
	v_mfma_f32_16x16x32_bf16 v[40:43], v[210:213], v[170:173], v[40:43]
	v_mfma_f32_16x16x32_bf16 v[36:39], v[218:221], v[138:141], v[36:39]
	v_mfma_f32_16x16x32_bf16 v[32:35], v[218:221], v[170:173], v[32:35]
	v_mfma_f32_16x16x32_bf16 v[28:31], v[194:197], v[178:181], v[28:31]
	v_mfma_f32_16x16x32_bf16 v[24:27], v[194:197], v[186:189], v[24:27]
	v_mfma_f32_16x16x32_bf16 v[20:23], v[202:205], v[178:181], v[20:23]
	v_mfma_f32_16x16x32_bf16 v[16:19], v[202:205], v[186:189], v[16:19]
	v_mfma_f32_16x16x32_bf16 v[12:15], v[210:213], v[178:181], v[12:15]
	v_mfma_f32_16x16x32_bf16 v[8:11], v[210:213], v[186:189], v[8:11]
	v_mfma_f32_16x16x32_bf16 v[4:7], v[218:221], v[178:181], v[4:7]
	v_mfma_f32_16x16x32_bf16 v[0:3], v[218:221], v[186:189], v[0:3]
	v_mfma_f32_16x16x32_bf16 v[64:67], v[198:201], v[142:145], v[64:67]
	v_mfma_f32_16x16x32_bf16 v[56:59], v[198:201], v[174:177], v[56:59]
	v_mfma_f32_16x16x32_bf16 v[52:55], v[206:209], v[142:145], v[52:55]
	v_mfma_f32_16x16x32_bf16 v[48:51], v[206:209], v[174:177], v[48:51]
	v_mfma_f32_16x16x32_bf16 v[44:47], v[214:217], v[142:145], v[44:47]
	v_mfma_f32_16x16x32_bf16 v[40:43], v[214:217], v[174:177], v[40:43]
	v_mfma_f32_16x16x32_bf16 v[36:39], v[222:225], v[142:145], v[36:39]
	v_mfma_f32_16x16x32_bf16 v[32:35], v[222:225], v[174:177], v[32:35]
	v_mfma_f32_16x16x32_bf16 v[28:31], v[198:201], v[182:185], v[28:31]
	v_mfma_f32_16x16x32_bf16 v[24:27], v[198:201], v[190:193], v[24:27]
	v_mfma_f32_16x16x32_bf16 v[20:23], v[206:209], v[182:185], v[20:23]
	v_mfma_f32_16x16x32_bf16 v[16:19], v[206:209], v[190:193], v[16:19]
	v_mfma_f32_16x16x32_bf16 v[12:15], v[214:217], v[182:185], v[12:15]
	v_mfma_f32_16x16x32_bf16 v[8:11], v[214:217], v[190:193], v[8:11]
	v_mfma_f32_16x16x32_bf16 v[4:7], v[222:225], v[182:185], v[4:7]
	v_mfma_f32_16x16x32_bf16 v[0:3], v[222:225], v[190:193], v[0:3]
	s_barrier
	s_setprio 0
	s_and_saveexec_b64 s[72:73], s[6:7]
	s_cbranch_execz .LBB0_157
	s_barrier

; #define STAGE(Pp, BASE, br, kt) do { const u16* _g = (BASE) + ((long)(br) * K + (long)(kt) * BK); \
;     __builtin_amdgcn_global_load_lds((const unsigned*)(_g + voff0), (unsigned*)((char*)(Pp) + tb16), 16, 0, 0); \
;     __builtin_amdgcn_global_load_lds((const unsigned*)(_g + voff1), (unsigned*)((char*)(Pp) + tb16 + 8192), 16, 0, 0); } while (0)
; #define LDA(dst, b, h) _Pragma("unroll") for (int m = 0; m < 4; ++m) _Pragma("unroll") for (int k = 0; k < 2; ++k) \
;     dst[m][k] = *reinterpret_cast<const bf16x8*>((const char*)shm + aB + (((b) * 2 + (h)) * 16384 + (m * 2 + k) * 1024))
; #define LDB(dst, b, h) _Pragma("unroll") for (int n = 0; n < 2; ++n) _Pragma("unroll") for (int k = 0; k < 2; ++k) \
;     dst[n][k] = *reinterpret_cast<const bf16x8*>((const char*)shm + bB + (((b) * 2 + (h)) * 16384 + (n * 2 + k) * 1024))
; #define WAIT_V(n) asm volatile("s_waitcnt vmcnt(" #n ")" ::: "memory")
; #define WAIT_L(n) asm volatile("s_waitcnt lgkmcnt(" #n ")" ::: "memory")
; #define BAR __builtin_amdgcn_s_barrier()
; #define SCHED __builtin_amdgcn_sched_barrier(0)
; template <int MODE> ...
;     ...
;       LDB(B0, 0, 0); LDB(B1, 0, 1); LDA(At, 0, 0); STAGE(SA(1, 1), A, brow + HALF, t + 1);
;       WAIT_L(0); BAR; MMA2(0, 0, 0, 1); BAR; SCHED;
;       LDA(At, 0, 1); STAGE(SB(0, 0), Bt, bcol, t + 2); STAGE(SB(0, 1), Bt, bcol + HALF, t + 2); STAGE(SA(0, 0), A, brow, t + 2);
;       WAIT_V(6); WAIT_L(0); BAR; MMA2(1, 0, 1, 1); BAR; SCHED;
.LBB0_177:
	s_add_u32 s71, s32, 0xc000
	s_mov_b32 m0, s71
	ds_read_b128 v[168:171], v148
	ds_read_b128 v[172:175], v148 offset:1024
	ds_read_b128 v[176:179], v148 offset:2048
	ds_read_b128 v[180:183], v148 offset:3072
	ds_read_b128 v[184:187], v148 offset:16384
	ds_read_b128 v[188:191], v148 offset:17408
	ds_read_b128 v[192:195], v148 offset:18432
	ds_read_b128 v[196:199], v148 offset:19456
	ds_read_b128 v[200:203], v147
	ds_read_b128 v[204:207], v147 offset:1024
	ds_read_b128 v[208:211], v147 offset:2048
	ds_read_b128 v[212:215], v147 offset:3072
	ds_read_b128 v[216:219], v147 offset:4096
	ds_read_b128 v[220:223], v147 offset:5120
	ds_read_b128 v[224:227], v147 offset:6144
	ds_read_b128 v[228:231], v147 offset:7168
	s_add_u32 s88, s68, s12
	s_addc_u32 s89, s69, s13
	global_load_lds_dwordx4 v142, s[88:89]
	s_add_u32 s71, s32, 0xe000
	s_mov_b32 m0, s71
	s_nop 0
	s_add_u32 s90, s68, s12
	s_addc_u32 s91, s69, s13
	global_load_lds_dwordx4 v144, s[90:91]
	s_waitcnt vmcnt(8)
	s_waitcnt lgkmcnt(0)
	s_setprio 1
	s_barrier
	v_mfma_f32_16x16x32_bf16 v[124:127], v[200:203], v[168:171], v[124:127]
	v_mfma_f32_16x16x32_bf16 v[120:123], v[200:203], v[176:179], v[120:123]
	v_mfma_f32_16x16x32_bf16 v[116:119], v[208:211], v[168:171], v[116:119]
	v_mfma_f32_16x16x32_bf16 v[112:115], v[208:211], v[176:179], v[112:115]
	v_mfma_f32_16x16x32_bf16 v[108:111], v[216:219], v[168:171], v[108:111]
	v_mfma_f32_16x16x32_bf16 v[104:107], v[216:219], v[176:179], v[104:107]
	v_mfma_f32_16x16x32_bf16 v[100:103], v[224:227], v[168:171], v[100:103]
	v_mfma_f32_16x16x32_bf16 v[96:99], v[224:227], v[176:179], v[96:99]
	v_mfma_f32_16x16x32_bf16 v[92:95], v[200:203], v[184:187], v[92:95]
	v_mfma_f32_16x16x32_bf16 v[88:91], v[200:203], v[192:195], v[88:91]
	v_mfma_f32_16x16x32_bf16 v[84:87], v[208:211], v[184:187], v[84:87]
	v_mfma_f32_16x16x32_bf16 v[80:83], v[208:211], v[192:195], v[80:83]
	v_mfma_f32_16x16x32_bf16 v[76:79], v[216:219], v[184:187], v[76:79]
	v_mfma_f32_16x16x32_bf16 v[72:75], v[216:219], v[192:195], v[72:75]
	v_mfma_f32_16x16x32_bf16 v[68:71], v[224:227], v[184:187], v[68:71]
	v_mfma_f32_16x16x32_bf16 v[64:67], v[224:227], v[192:195], v[64:67]
	v_mfma_f32_16x16x32_bf16 v[124:127], v[204:207], v[172:175], v[124:127]
	v_mfma_f32_16x16x32_bf16 v[120:123], v[204:207], v[180:183], v[120:123]
	v_mfma_f32_16x16x32_bf16 v[116:119], v[212:215], v[172:175], v[116:119]
	v_mfma_f32_16x16x32_bf16 v[112:115], v[212:215], v[180:183], v[112:115]
	v_mfma_f32_16x16x32_bf16 v[108:111], v[220:223], v[172:175], v[108:111]
	v_mfma_f32_16x16x32_bf16 v[104:107], v[220:223], v[180:183], v[104:107]
	v_mfma_f32_16x16x32_bf16 v[100:103], v[228:231], v[172:175], v[100:103]
	v_mfma_f32_16x16x32_bf16 v[96:99], v[228:231], v[180:183], v[96:99]
	v_mfma_f32_16x16x32_bf16 v[92:95], v[204:207], v[188:191], v[92:95]
	v_mfma_f32_16x16x32_bf16 v[88:91], v[204:207], v[196:199], v[88:91]
	v_mfma_f32_16x16x32_bf16 v[84:87], v[212:215], v[188:191], v[84:87]
	v_mfma_f32_16x16x32_bf16 v[80:83], v[212:215], v[196:199], v[80:83]
	v_mfma_f32_16x16x32_bf16 v[76:79], v[220:223], v[188:191], v[76:79]
	v_mfma_f32_16x16x32_bf16 v[72:75], v[220:223], v[196:199], v[72:75]
	v_mfma_f32_16x16x32_bf16 v[68:71], v[228:231], v[188:191], v[68:71]
	v_mfma_f32_16x16x32_bf16 v[64:67], v[228:231], v[196:199], v[64:67]
	s_barrier
	s_setprio 0
	s_add_u32 s71, s32, 0x10000
	s_mov_b32 m0, s71
	ds_read_b128 v[200:203], v147 offset:16384
	ds_read_b128 v[204:207], v147 offset:17408
	ds_read_b128 v[208:211], v147 offset:18432
	ds_read_b128 v[212:215], v147 offset:19456
	ds_read_b128 v[216:219], v147 offset:20480
	ds_read_b128 v[220:223], v147 offset:21504
	ds_read_b128 v[224:227], v147 offset:22528
	ds_read_b128 v[228:231], v147 offset:23552
	s_add_u32 s92, s68, s38
	s_addc_u32 s93, s69, s39
	global_load_lds_dwordx4 v138, s[92:93]
	s_add_u32 s71, s32, 0x12000
	s_mov_b32 m0, s71
	s_add_u32 s71, s32, 0x14000
	s_add_u32 s96, s68, s38
	s_addc_u32 s97, s69, s39
	global_load_lds_dwordx4 v140, s[96:97]
	s_mov_b32 m0, s71
	s_add_u32 s71, s32, 0x16000
	s_add_u32 s88, s68, s40
	s_addc_u32 s89, s69, s41
	global_load_lds_dwordx4 v138, s[88:89]
	s_mov_b32 m0, s71
	s_mov_b32 s71, s32
	s_add_u32 s90, s68, s40
	s_addc_u32 s91, s69, s41
	global_load_lds_dwordx4 v140, s[90:91]
	s_mov_b32 m0, s71
	s_add_u32 s71, s32, 0x2000
	s_add_u32 s92, s68, s42
	s_addc_u32 s93, s69, s43
	global_load_lds_dwordx4 v142, s[92:93]
	s_mov_b32 m0, s71
	s_nop 0
	s_add_u32 s96, s68, s42
	s_addc_u32 s97, s69, s43
	global_load_lds_dwordx4 v144, s[96:97]
	s_waitcnt vmcnt(8)
	s_waitcnt lgkmcnt(0)
	s_setprio 1
	s_barrier
; #define STAGE(Pp, BASE, br, kt) do { const u16* _g = (BASE) + ((long)(br) * K + (long)(kt) * BK); \
;     __builtin_amdgcn_global_load_lds((const unsigned*)(_g + voff0), (unsigned*)((char*)(Pp) + tb16), 16, 0, 0); \
;     __builtin_amdgcn_global_load_lds((const unsigned*)(_g + voff1), (unsigned*)((char*)(Pp) + tb16 + 8192), 16, 0, 0); } while (0)
; #define LDA(dst, b, h) _Pragma("unroll") for (int m = 0; m < 4; ++m) _Pragma("unroll") for (int k = 0; k < 2; ++k) \
;     dst[m][k] = *reinterpret_cast<const bf16x8*>((const char*)shm + aB + (((b) * 2 + (h)) * 16384 + (m * 2 + k) * 1024))
; #define LDB(dst, b, h) _Pragma("unroll") for (int n = 0; n < 2; ++n) _Pragma("unroll") for (int k = 0; k < 2; ++k) \
;     dst[n][k] = *reinterpret_cast<const bf16x8*>((const char*)shm + bB + (((b) * 2 + (h)) * 16384 + (n * 2 + k) * 1024))
; #define WAIT_V(n) asm volatile("s_waitcnt vmcnt(" #n ")" ::: "memory")
; #define WAIT_L(n) asm volatile("s_waitcnt lgkmcnt(" #n ")" ::: "memory")
; #define BAR __builtin_amdgcn_s_barrier()
; #define SCHED __builtin_amdgcn_sched_barrier(0)
; template <int MODE> ...
;     ...
;       WAIT_V(6); WAIT_L(0); BAR; MMA2(1, 0, 1, 1); BAR; SCHED;
;       LDB(B0, 1, 0); LDB(B1, 1, 1); LDA(At, 1, 0); STAGE(SA(0, 1), A, brow + HALF, t + 2);
;       WAIT_L(0); BAR; MMA2(0, 0, 0, 1); BAR; SCHED;
	v_mfma_f32_16x16x32_bf16 v[60:63], v[200:203], v[168:171], v[60:63]
	v_mfma_f32_16x16x32_bf16 v[56:59], v[200:203], v[176:179], v[56:59]
	v_mfma_f32_16x16x32_bf16 v[52:55], v[208:211], v[168:171], v[52:55]
	v_mfma_f32_16x16x32_bf16 v[48:51], v[208:211], v[176:179], v[48:51]
	v_mfma_f32_16x16x32_bf16 v[44:47], v[216:219], v[168:171], v[44:47]
	v_mfma_f32_16x16x32_bf16 v[40:43], v[216:219], v[176:179], v[40:43]
	v_mfma_f32_16x16x32_bf16 v[36:39], v[224:227], v[168:171], v[36:39]
	v_mfma_f32_16x16x32_bf16 v[32:35], v[224:227], v[176:179], v[32:35]
	v_mfma_f32_16x16x32_bf16 v[28:31], v[200:203], v[184:187], v[28:31]
	v_mfma_f32_16x16x32_bf16 v[24:27], v[200:203], v[192:195], v[24:27]
	v_mfma_f32_16x16x32_bf16 v[20:23], v[208:211], v[184:187], v[20:23]
	v_mfma_f32_16x16x32_bf16 v[16:19], v[208:211], v[192:195], v[16:19]
	v_mfma_f32_16x16x32_bf16 v[12:15], v[216:219], v[184:187], v[12:15]
	v_mfma_f32_16x16x32_bf16 v[8:11], v[216:219], v[192:195], v[8:11]
	v_mfma_f32_16x16x32_bf16 v[4:7], v[224:227], v[184:187], v[4:7]
	v_mfma_f32_16x16x32_bf16 v[0:3], v[224:227], v[192:195], v[0:3]
	v_mfma_f32_16x16x32_bf16 v[60:63], v[204:207], v[172:175], v[60:63]
	v_mfma_f32_16x16x32_bf16 v[56:59], v[204:207], v[180:183], v[56:59]
	v_mfma_f32_16x16x32_bf16 v[52:55], v[212:215], v[172:175], v[52:55]
	v_mfma_f32_16x16x32_bf16 v[48:51], v[212:215], v[180:183], v[48:51]
	v_mfma_f32_16x16x32_bf16 v[44:47], v[220:223], v[172:175], v[44:47]
	v_mfma_f32_16x16x32_bf16 v[40:43], v[220:223], v[180:183], v[40:43]
	v_mfma_f32_16x16x32_bf16 v[36:39], v[228:231], v[172:175], v[36:39]
	v_mfma_f32_16x16x32_bf16 v[32:35], v[228:231], v[180:183], v[32:35]
	v_mfma_f32_16x16x32_bf16 v[28:31], v[204:207], v[188:191], v[28:31]
	v_mfma_f32_16x16x32_bf16 v[24:27], v[204:207], v[196:199], v[24:27]
	v_mfma_f32_16x16x32_bf16 v[20:23], v[212:215], v[188:191], v[20:23]
	v_mfma_f32_16x16x32_bf16 v[16:19], v[212:215], v[196:199], v[16:19]
	v_mfma_f32_16x16x32_bf16 v[12:15], v[220:223], v[188:191], v[12:15]
	v_mfma_f32_16x16x32_bf16 v[8:11], v[220:223], v[196:199], v[8:11]
	v_mfma_f32_16x16x32_bf16 v[4:7], v[228:231], v[188:191], v[4:7]
	v_mfma_f32_16x16x32_bf16 v[0:3], v[228:231], v[196:199], v[0:3]
	s_barrier
	s_setprio 0
	s_add_u32 s71, s32, 0x4000
	s_mov_b32 m0, s71
	s_add_u32 s71, s32, 0x6000
	ds_read_b128 v[168:171], v148 offset:32768
	ds_read_b128 v[172:175], v148 offset:33792
	ds_read_b128 v[176:179], v148 offset:34816
	ds_read_b128 v[180:183], v148 offset:35840
	ds_read_b128 v[184:187], v148 offset:49152
	ds_read_b128 v[188:191], v148 offset:50176
	ds_read_b128 v[192:195], v148 offset:51200
	ds_read_b128 v[196:199], v148 offset:52224
	ds_read_b128 v[200:203], v147 offset:32768
	ds_read_b128 v[204:207], v147 offset:33792
	ds_read_b128 v[208:211], v147 offset:34816
	ds_read_b128 v[212:215], v147 offset:35840
	ds_read_b128 v[216:219], v147 offset:36864
	ds_read_b128 v[220:223], v147 offset:37888
	ds_read_b128 v[224:227], v147 offset:38912
	ds_read_b128 v[228:231], v147 offset:39936
	s_add_u32 s88, s68, s44
	s_addc_u32 s89, s69, s45
	global_load_lds_dwordx4 v142, s[88:89]
	s_mov_b32 m0, s71
	s_nop 0
	s_add_u32 s90, s68, s44
	s_addc_u32 s91, s69, s45
	global_load_lds_dwordx4 v144, s[90:91]
	s_waitcnt vmcnt(8)
	s_waitcnt lgkmcnt(0)
	s_setprio 1
	s_barrier
	v_mfma_f32_16x16x32_bf16 v[124:127], v[200:203], v[168:171], v[124:127]
	v_mfma_f32_16x16x32_bf16 v[120:123], v[200:203], v[176:179], v[120:123]
	v_mfma_f32_16x16x32_bf16 v[116:119], v[208:211], v[168:171], v[116:119]
	v_mfma_f32_16x16x32_bf16 v[112:115], v[208:211], v[176:179], v[112:115]
	v_mfma_f32_16x16x32_bf16 v[108:111], v[216:219], v[168:171], v[108:111]
	v_mfma_f32_16x16x32_bf16 v[104:107], v[216:219], v[176:179], v[104:107]
	v_mfma_f32_16x16x32_bf16 v[100:103], v[224:227], v[168:171], v[100:103]
	v_mfma_f32_16x16x32_bf16 v[96:99], v[224:227], v[176:179], v[96:99]
	v_mfma_f32_16x16x32_bf16 v[92:95], v[200:203], v[184:187], v[92:95]
	v_mfma_f32_16x16x32_bf16 v[88:91], v[200:203], v[192:195], v[88:91]
	v_mfma_f32_16x16x32_bf16 v[84:87], v[208:211], v[184:187], v[84:87]
	v_mfma_f32_16x16x32_bf16 v[80:83], v[208:211], v[192:195], v[80:83]
	v_mfma_f32_16x16x32_bf16 v[76:79], v[216:219], v[184:187], v[76:79]
	v_mfma_f32_16x16x32_bf16 v[72:75], v[216:219], v[192:195], v[72:75]
	v_mfma_f32_16x16x32_bf16 v[68:71], v[224:227], v[184:187], v[68:71]
	v_mfma_f32_16x16x32_bf16 v[64:67], v[224:227], v[192:195], v[64:67]
	v_mfma_f32_16x16x32_bf16 v[124:127], v[204:207], v[172:175], v[124:127]
	v_mfma_f32_16x16x32_bf16 v[120:123], v[204:207], v[180:183], v[120:123]
	v_mfma_f32_16x16x32_bf16 v[116:119], v[212:215], v[172:175], v[116:119]
	v_mfma_f32_16x16x32_bf16 v[112:115], v[212:215], v[180:183], v[112:115]
	v_mfma_f32_16x16x32_bf16 v[108:111], v[220:223], v[172:175], v[108:111]
	v_mfma_f32_16x16x32_bf16 v[104:107], v[220:223], v[180:183], v[104:107]
	v_mfma_f32_16x16x32_bf16 v[100:103], v[228:231], v[172:175], v[100:103]
	v_mfma_f32_16x16x32_bf16 v[96:99], v[228:231], v[180:183], v[96:99]
	v_mfma_f32_16x16x32_bf16 v[92:95], v[204:207], v[188:191], v[92:95]
	v_mfma_f32_16x16x32_bf16 v[88:91], v[204:207], v[196:199], v[88:91]
	v_mfma_f32_16x16x32_bf16 v[84:87], v[212:215], v[188:191], v[84:87]
	v_mfma_f32_16x16x32_bf16 v[80:83], v[212:215], v[196:199], v[80:83]
	v_mfma_f32_16x16x32_bf16 v[76:79], v[220:223], v[188:191], v[76:79]
	v_mfma_f32_16x16x32_bf16 v[72:75], v[220:223], v[196:199], v[72:75]
	v_mfma_f32_16x16x32_bf16 v[68:71], v[228:231], v[188:191], v[68:71]
	v_mfma_f32_16x16x32_bf16 v[64:67], v[228:231], v[196:199], v[64:67]
	s_barrier
; #define STAGE(Pp, BASE, br, kt) do { const u16* _g = (BASE) + ((long)(br) * K + (long)(kt) * BK); \
;     __builtin_amdgcn_global_load_lds((const unsigned*)(_g + voff0), (unsigned*)((char*)(Pp) + tb16), 16, 0, 0); \
;     __builtin_amdgcn_global_load_lds((const unsigned*)(_g + voff1), (unsigned*)((char*)(Pp) + tb16 + 8192), 16, 0, 0); } while (0)
; #define LDA(dst, b, h) _Pragma("unroll") for (int m = 0; m < 4; ++m) _Pragma("unroll") for (int k = 0; k < 2; ++k) \
;     dst[m][k] = *reinterpret_cast<const bf16x8*>((const char*)shm + aB + (((b) * 2 + (h)) * 16384 + (m * 2 + k) * 1024))
; #define LDB(dst, b, h) _Pragma("unroll") for (int n = 0; n < 2; ++n) _Pragma("unroll") for (int k = 0; k < 2; ++k) \
;     dst[n][k] = *reinterpret_cast<const bf16x8*>((const char*)shm + bB + (((b) * 2 + (h)) * 16384 + (n * 2 + k) * 1024))
; #define WAIT_V(n) asm volatile("s_waitcnt vmcnt(" #n ")" ::: "memory")
; #define WAIT_L(n) asm volatile("s_waitcnt lgkmcnt(" #n ")" ::: "memory")
; #define BAR __builtin_amdgcn_s_barrier()
; #define SCHED __builtin_amdgcn_sched_barrier(0)
; template <int MODE> ...
;     ...
;       LDA(At, 1, 1); STAGE(SB(1, 0), Bt, bcol, t + 3); STAGE(SB(1, 1), Bt, bcol + HALF, t + 3); STAGE(SA(1, 0), A, brow, t + 3);
;       WAIT_V(6); WAIT_L(0); BAR; MMA2(1, 0, 1, 1); BAR; SCHED;
;     }
;     {
;       LDB(B0, 0, 0); LDB(B1, 0, 1); LDA(At, 0, 0); STAGE(SA(1, 1), A, brow + HALF, nt - 1);
;       WAIT_L(0); BAR; MMA2(0, 0, 0, 1); BAR; SCHED;
	s_setprio 0
	s_add_u32 s71, s32, 0x18000
	s_mov_b32 m0, s71
	s_add_u32 s71, s32, 0x1a000
	ds_read_b128 v[200:203], v147 offset:49152
	ds_read_b128 v[204:207], v147 offset:50176
	ds_read_b128 v[208:211], v147 offset:51200
	ds_read_b128 v[212:215], v147 offset:52224
	ds_read_b128 v[216:219], v147 offset:53248
	ds_read_b128 v[220:223], v147 offset:54272
	ds_read_b128 v[224:227], v147 offset:55296
	ds_read_b128 v[228:231], v147 offset:56320
	s_add_u32 s92, s68, s48
	s_addc_u32 s93, s69, s49
	global_load_lds_dwordx4 v138, s[92:93]
	s_mov_b32 m0, s71
	s_add_u32 s71, s32, 0x1c000
	s_add_u32 s96, s68, s48
	s_addc_u32 s97, s69, s49
	global_load_lds_dwordx4 v140, s[96:97]
	s_mov_b32 m0, s71
	s_add_u32 s71, s32, 0x1e000
	s_add_u32 s88, s68, s50
	s_addc_u32 s89, s69, s51
	global_load_lds_dwordx4 v138, s[88:89]
	s_mov_b32 m0, s71
	s_add_u32 s71, s32, 0x8000
	s_add_u32 s90, s68, s50
	s_addc_u32 s91, s69, s51
	global_load_lds_dwordx4 v140, s[90:91]
	s_mov_b32 m0, s71
	s_add_u32 s71, s32, 0xa000
	s_add_u32 s92, s68, s60
	s_addc_u32 s93, s69, s61
	global_load_lds_dwordx4 v142, s[92:93]
	s_mov_b32 m0, s71
	s_nop 0
	s_add_u32 s96, s68, s60
	s_addc_u32 s97, s69, s61
	global_load_lds_dwordx4 v144, s[96:97]
	s_waitcnt vmcnt(8)
	s_waitcnt lgkmcnt(0)
	s_setprio 1
	s_barrier
	v_mfma_f32_16x16x32_bf16 v[60:63], v[200:203], v[168:171], v[60:63]
	v_mfma_f32_16x16x32_bf16 v[56:59], v[200:203], v[176:179], v[56:59]
	v_mfma_f32_16x16x32_bf16 v[52:55], v[208:211], v[168:171], v[52:55]
	v_mfma_f32_16x16x32_bf16 v[48:51], v[208:211], v[176:179], v[48:51]
	v_mfma_f32_16x16x32_bf16 v[44:47], v[216:219], v[168:171], v[44:47]
	v_mfma_f32_16x16x32_bf16 v[40:43], v[216:219], v[176:179], v[40:43]
	v_mfma_f32_16x16x32_bf16 v[36:39], v[224:227], v[168:171], v[36:39]
	v_mfma_f32_16x16x32_bf16 v[32:35], v[224:227], v[176:179], v[32:35]
	v_mfma_f32_16x16x32_bf16 v[28:31], v[200:203], v[184:187], v[28:31]
	v_mfma_f32_16x16x32_bf16 v[24:27], v[200:203], v[192:195], v[24:27]
	v_mfma_f32_16x16x32_bf16 v[20:23], v[208:211], v[184:187], v[20:23]
	v_mfma_f32_16x16x32_bf16 v[16:19], v[208:211], v[192:195], v[16:19]
	v_mfma_f32_16x16x32_bf16 v[12:15], v[216:219], v[184:187], v[12:15]
	v_mfma_f32_16x16x32_bf16 v[8:11], v[216:219], v[192:195], v[8:11]
	v_mfma_f32_16x16x32_bf16 v[4:7], v[224:227], v[184:187], v[4:7]
	v_mfma_f32_16x16x32_bf16 v[0:3], v[224:227], v[192:195], v[0:3]
	v_mfma_f32_16x16x32_bf16 v[60:63], v[204:207], v[172:175], v[60:63]
	v_mfma_f32_16x16x32_bf16 v[56:59], v[204:207], v[180:183], v[56:59]
	v_mfma_f32_16x16x32_bf16 v[52:55], v[212:215], v[172:175], v[52:55]
	v_mfma_f32_16x16x32_bf16 v[48:51], v[212:215], v[180:183], v[48:51]
	v_mfma_f32_16x16x32_bf16 v[44:47], v[220:223], v[172:175], v[44:47]
	v_mfma_f32_16x16x32_bf16 v[40:43], v[220:223], v[180:183], v[40:43]
	v_mfma_f32_16x16x32_bf16 v[36:39], v[228:231], v[172:175], v[36:39]
	v_mfma_f32_16x16x32_bf16 v[32:35], v[228:231], v[180:183], v[32:35]
	v_mfma_f32_16x16x32_bf16 v[28:31], v[204:207], v[188:191], v[28:31]
	v_mfma_f32_16x16x32_bf16 v[24:27], v[204:207], v[196:199], v[24:27]
	v_mfma_f32_16x16x32_bf16 v[20:23], v[212:215], v[188:191], v[20:23]
	v_mfma_f32_16x16x32_bf16 v[16:19], v[212:215], v[196:199], v[16:19]
	v_mfma_f32_16x16x32_bf16 v[12:15], v[220:223], v[188:191], v[12:15]
	v_mfma_f32_16x16x32_bf16 v[8:11], v[220:223], v[196:199], v[8:11]
	v_mfma_f32_16x16x32_bf16 v[4:7], v[228:231], v[188:191], v[4:7]
	v_mfma_f32_16x16x32_bf16 v[0:3], v[228:231], v[196:199], v[0:3]
	s_barrier
	s_setprio 0
	s_add_i32 s70, s70, 2
	s_add_u32 s68, s68, 0x100
	s_addc_u32 s69, s69, 0
	s_cmp_lt_u32 s70, 60
	s_cbranch_scc1 .LBB0_177
	s_add_u32 s66, s66, 0x1f80
	v_readfirstlane_b32 s68, v165
	s_addc_u32 s67, s67, 0
	s_mov_b32 m0, s68
	v_readfirstlane_b32 s68, v166
	ds_read_b128 v[138:141], v148
	ds_read_b128 v[142:145], v148 offset:1024
	ds_read_b128 v[168:171], v148 offset:2048
	ds_read_b128 v[172:175], v148 offset:3072
	ds_read_b128 v[176:179], v148 offset:16384
	ds_read_b128 v[180:183], v148 offset:17408
	ds_read_b128 v[184:187], v148 offset:18432
	ds_read_b128 v[188:191], v148 offset:19456
	ds_read_b128 v[192:195], v147
	ds_read_b128 v[196:199], v147 offset:1024
	ds_read_b128 v[200:203], v147 offset:2048
	ds_read_b128 v[204:207], v147 offset:3072
	ds_read_b128 v[208:211], v147 offset:4096
	ds_read_b128 v[212:215], v147 offset:5120
	ds_read_b128 v[216:219], v147 offset:6144
	ds_read_b128 v[220:223], v147 offset:7168
	global_load_lds_dwordx4 v134, s[66:67]
	s_mov_b32 m0, s68
	s_nop 0
	global_load_lds_dwordx4 v136, s[66:67]
	s_waitcnt vmcnt(8)
	s_waitcnt lgkmcnt(0)
	s_setprio 1
	s_barrier
; #define STAGE(Pp, BASE, br, kt) do { const u16* _g = (BASE) + ((long)(br) * K + (long)(kt) * BK); \
;     __builtin_amdgcn_global_load_lds((const unsigned*)(_g + voff0), (unsigned*)((char*)(Pp) + tb16), 16, 0, 0); \
;     __builtin_amdgcn_global_load_lds((const unsigned*)(_g + voff1), (unsigned*)((char*)(Pp) + tb16 + 8192), 16, 0, 0); } while (0)
; #define LDA(dst, b, h) _Pragma("unroll") for (int m = 0; m < 4; ++m) _Pragma("unroll") for (int k = 0; k < 2; ++k) \
;     dst[m][k] = *reinterpret_cast<const bf16x8*>((const char*)shm + aB + (((b) * 2 + (h)) * 16384 + (m * 2 + k) * 1024))
; #define LDB(dst, b, h) _Pragma("unroll") for (int n = 0; n < 2; ++n) _Pragma("unroll") for (int k = 0; k < 2; ++k) \
;     dst[n][k] = *reinterpret_cast<const bf16x8*>((const char*)shm + bB + (((b) * 2 + (h)) * 16384 + (n * 2 + k) * 1024))
; #define WAIT_V(n) asm volatile("s_waitcnt vmcnt(" #n ")" ::: "memory")
; #define WAIT_L(n) asm volatile("s_waitcnt lgkmcnt(" #n ")" ::: "memory")
; #define BAR __builtin_amdgcn_s_barrier()
; #define SCHED __builtin_amdgcn_sched_barrier(0)
; template <int MODE> ...
;     ...
;       LDB(B0, 0, 0); LDB(B1, 0, 1); LDA(At, 0, 0); STAGE(SA(1, 1), A, brow + HALF, nt - 1);
;       WAIT_L(0); BAR; MMA2(0, 0, 0, 1); BAR; SCHED;
;       LDA(At, 0, 1); WAIT_V(0); WAIT_L(0); BAR; MMA2(1, 0, 1, 1); BAR; SCHED;
;       LDB(B0, 1, 0); LDB(B1, 1, 1); LDA(At, 1, 0); WAIT_L(0); BAR; MMA2(0, 0, 0, 1); BAR; SCHED;
	v_mfma_f32_16x16x32_bf16 v[124:127], v[192:195], v[138:141], v[124:127]
	v_mfma_f32_16x16x32_bf16 v[120:123], v[192:195], v[168:171], v[120:123]
	v_mfma_f32_16x16x32_bf16 v[116:119], v[200:203], v[138:141], v[116:119]
	v_mfma_f32_16x16x32_bf16 v[112:115], v[200:203], v[168:171], v[112:115]
	v_mfma_f32_16x16x32_bf16 v[108:111], v[208:211], v[138:141], v[108:111]
	v_mfma_f32_16x16x32_bf16 v[104:107], v[208:211], v[168:171], v[104:107]
	v_mfma_f32_16x16x32_bf16 v[100:103], v[216:219], v[138:141], v[100:103]
	v_mfma_f32_16x16x32_bf16 v[96:99], v[216:219], v[168:171], v[96:99]
	v_mfma_f32_16x16x32_bf16 v[92:95], v[192:195], v[176:179], v[92:95]
	v_mfma_f32_16x16x32_bf16 v[88:91], v[192:195], v[184:187], v[88:91]
	v_mfma_f32_16x16x32_bf16 v[84:87], v[200:203], v[176:179], v[84:87]
	v_mfma_f32_16x16x32_bf16 v[80:83], v[200:203], v[184:187], v[80:83]
	v_mfma_f32_16x16x32_bf16 v[76:79], v[208:211], v[176:179], v[76:79]
	v_mfma_f32_16x16x32_bf16 v[72:75], v[208:211], v[184:187], v[72:75]
	v_mfma_f32_16x16x32_bf16 v[68:71], v[216:219], v[176:179], v[68:71]
	v_mfma_f32_16x16x32_bf16 v[64:67], v[216:219], v[184:187], v[64:67]
	v_mfma_f32_16x16x32_bf16 v[124:127], v[196:199], v[142:145], v[124:127]
	v_mfma_f32_16x16x32_bf16 v[120:123], v[196:199], v[172:175], v[120:123]
	v_mfma_f32_16x16x32_bf16 v[116:119], v[204:207], v[142:145], v[116:119]
	v_mfma_f32_16x16x32_bf16 v[112:115], v[204:207], v[172:175], v[112:115]
	v_mfma_f32_16x16x32_bf16 v[108:111], v[212:215], v[142:145], v[108:111]
	v_mfma_f32_16x16x32_bf16 v[104:107], v[212:215], v[172:175], v[104:107]
	v_mfma_f32_16x16x32_bf16 v[100:103], v[220:223], v[142:145], v[100:103]
	v_mfma_f32_16x16x32_bf16 v[96:99], v[220:223], v[172:175], v[96:99]
	v_mfma_f32_16x16x32_bf16 v[92:95], v[196:199], v[180:183], v[92:95]
	v_mfma_f32_16x16x32_bf16 v[88:91], v[196:199], v[188:191], v[88:91]
	v_mfma_f32_16x16x32_bf16 v[84:87], v[204:207], v[180:183], v[84:87]
	v_mfma_f32_16x16x32_bf16 v[80:83], v[204:207], v[188:191], v[80:83]
	v_mfma_f32_16x16x32_bf16 v[76:79], v[212:215], v[180:183], v[76:79]
	v_mfma_f32_16x16x32_bf16 v[72:75], v[212:215], v[188:191], v[72:75]
	v_mfma_f32_16x16x32_bf16 v[68:71], v[220:223], v[180:183], v[68:71]
	v_mfma_f32_16x16x32_bf16 v[64:67], v[220:223], v[188:191], v[64:67]
	s_barrier
	s_setprio 0
	ds_read_b128 v[192:195], v147 offset:16384
	ds_read_b128 v[196:199], v147 offset:17408
	ds_read_b128 v[200:203], v147 offset:18432
	ds_read_b128 v[204:207], v147 offset:19456
	ds_read_b128 v[208:211], v147 offset:20480
	ds_read_b128 v[212:215], v147 offset:21504
	ds_read_b128 v[216:219], v147 offset:22528
	ds_read_b128 v[220:223], v147 offset:23552
	s_waitcnt vmcnt(0)
	s_waitcnt lgkmcnt(0)
	s_setprio 1
	s_barrier
	v_mfma_f32_16x16x32_bf16 v[56:59], v[192:195], v[168:171], v[56:59]
	v_mfma_f32_16x16x32_bf16 v[52:55], v[200:203], v[138:141], v[52:55]
	v_mfma_f32_16x16x32_bf16 v[48:51], v[200:203], v[168:171], v[48:51]
	v_mfma_f32_16x16x32_bf16 v[44:47], v[208:211], v[138:141], v[44:47]
	v_mfma_f32_16x16x32_bf16 v[40:43], v[208:211], v[168:171], v[40:43]
	v_mfma_f32_16x16x32_bf16 v[36:39], v[216:219], v[138:141], v[36:39]
	v_mfma_f32_16x16x32_bf16 v[32:35], v[216:219], v[168:171], v[32:35]
	v_mfma_f32_16x16x32_bf16 v[28:31], v[192:195], v[176:179], v[28:31]
	v_mfma_f32_16x16x32_bf16 v[24:27], v[192:195], v[184:187], v[24:27]
	v_mfma_f32_16x16x32_bf16 v[20:23], v[200:203], v[176:179], v[20:23]
	v_mfma_f32_16x16x32_bf16 v[16:19], v[200:203], v[184:187], v[16:19]
	v_mfma_f32_16x16x32_bf16 v[12:15], v[208:211], v[176:179], v[12:15]
	v_mfma_f32_16x16x32_bf16 v[8:11], v[208:211], v[184:187], v[8:11]
	v_mfma_f32_16x16x32_bf16 v[4:7], v[216:219], v[176:179], v[4:7]
	v_mfma_f32_16x16x32_bf16 v[0:3], v[216:219], v[184:187], v[0:3]
	v_mfma_f32_16x16x32_bf16 v[60:63], v[192:195], v[138:141], v[60:63]
	v_mfma_f32_16x16x32_bf16 v[56:59], v[196:199], v[172:175], v[56:59]
	v_mfma_f32_16x16x32_bf16 v[52:55], v[204:207], v[142:145], v[52:55]
	v_mfma_f32_16x16x32_bf16 v[48:51], v[204:207], v[172:175], v[48:51]
	v_mfma_f32_16x16x32_bf16 v[44:47], v[212:215], v[142:145], v[44:47]
	v_mfma_f32_16x16x32_bf16 v[40:43], v[212:215], v[172:175], v[40:43]
	v_mfma_f32_16x16x32_bf16 v[36:39], v[220:223], v[142:145], v[36:39]
	v_mfma_f32_16x16x32_bf16 v[32:35], v[220:223], v[172:175], v[32:35]
	v_mfma_f32_16x16x32_bf16 v[28:31], v[196:199], v[180:183], v[28:31]
	v_mfma_f32_16x16x32_bf16 v[24:27], v[196:199], v[188:191], v[24:27]
	v_mfma_f32_16x16x32_bf16 v[20:23], v[204:207], v[180:183], v[20:23]
	v_mfma_f32_16x16x32_bf16 v[16:19], v[204:207], v[188:191], v[16:19]
	v_mfma_f32_16x16x32_bf16 v[12:15], v[212:215], v[180:183], v[12:15]
	v_mfma_f32_16x16x32_bf16 v[8:11], v[212:215], v[188:191], v[8:11]
	v_mfma_f32_16x16x32_bf16 v[4:7], v[220:223], v[180:183], v[4:7]
	v_mfma_f32_16x16x32_bf16 v[0:3], v[220:223], v[188:191], v[0:3]
	v_mfma_f32_16x16x32_bf16 v[224:227], v[196:199], v[142:145], v[60:63]
	s_barrier
	s_setprio 0
	ds_read_b128 v[138:141], v148 offset:32768
	ds_read_b128 v[142:145], v148 offset:33792
	ds_read_b128 v[168:171], v148 offset:34816
	ds_read_b128 v[172:175], v148 offset:35840
	ds_read_b128 v[176:179], v148 offset:49152
	ds_read_b128 v[180:183], v148 offset:50176
	ds_read_b128 v[184:187], v148 offset:51200
	ds_read_b128 v[188:191], v148 offset:52224
	ds_read_b128 v[60:63], v147 offset:32768
	ds_read_b128 v[192:195], v147 offset:33792
	ds_read_b128 v[196:199], v147 offset:34816
	ds_read_b128 v[200:203], v147 offset:35840
	ds_read_b128 v[204:207], v147 offset:36864
	ds_read_b128 v[208:211], v147 offset:37888
	ds_read_b128 v[212:215], v147 offset:38912
	ds_read_b128 v[216:219], v147 offset:39936
	s_waitcnt lgkmcnt(0)
	s_setprio 1
	s_barrier
; #define LDA(dst, b, h) _Pragma("unroll") for (int m = 0; m < 4; ++m) _Pragma("unroll") for (int k = 0; k < 2; ++k) \
;     dst[m][k] = *reinterpret_cast<const bf16x8*>((const char*)shm + aB + (((b) * 2 + (h)) * 16384 + (m * 2 + k) * 1024))
; #define LDB(dst, b, h) _Pragma("unroll") for (int n = 0; n < 2; ++n) _Pragma("unroll") for (int k = 0; k < 2; ++k) \
;     dst[n][k] = *reinterpret_cast<const bf16x8*>((const char*)shm + bB + (((b) * 2 + (h)) * 16384 + (n * 2 + k) * 1024))
; #define WAIT_L(n) asm volatile("s_waitcnt lgkmcnt(" #n ")" ::: "memory")
; #define BAR __builtin_amdgcn_s_barrier()
; #define SCHED __builtin_amdgcn_sched_barrier(0)
; template <int MODE> ...
;     ...
;       LDB(B0, 1, 0); LDB(B1, 1, 1); LDA(At, 1, 0); WAIT_L(0); BAR; MMA2(0, 0, 0, 1); BAR; SCHED;
;       LDA(At, 1, 1); WAIT_L(0); BAR; MMA2(1, 0, 1, 1); BAR; SCHED;
;     }
;     ...
;     if (wr == 0) BAR;
	v_mfma_f32_16x16x32_bf16 v[124:127], v[60:63], v[138:141], v[124:127]
	v_mfma_f32_16x16x32_bf16 v[120:123], v[60:63], v[168:171], v[120:123]
	v_mfma_f32_16x16x32_bf16 v[92:95], v[60:63], v[176:179], v[92:95]
	v_mfma_f32_16x16x32_bf16 v[60:63], v[60:63], v[184:187], v[88:91]
	v_mfma_f32_16x16x32_bf16 v[88:91], v[192:195], v[188:191], v[60:63]
	v_mfma_f32_16x16x32_bf16 v[60:63], v[196:199], v[176:179], v[84:87]
	v_mfma_f32_16x16x32_bf16 v[84:87], v[200:203], v[180:183], v[60:63]
	v_mfma_f32_16x16x32_bf16 v[60:63], v[196:199], v[184:187], v[80:83]
	v_mfma_f32_16x16x32_bf16 v[80:83], v[200:203], v[188:191], v[60:63]
	v_mfma_f32_16x16x32_bf16 v[60:63], v[204:207], v[176:179], v[76:79]
	v_mfma_f32_16x16x32_bf16 v[76:79], v[208:211], v[180:183], v[60:63]
	v_mfma_f32_16x16x32_bf16 v[60:63], v[204:207], v[184:187], v[72:75]
	v_mfma_f32_16x16x32_bf16 v[72:75], v[208:211], v[188:191], v[60:63]
	v_mfma_f32_16x16x32_bf16 v[60:63], v[212:215], v[176:179], v[68:71]
	v_mfma_f32_16x16x32_bf16 v[116:119], v[196:199], v[138:141], v[116:119]
	v_mfma_f32_16x16x32_bf16 v[112:115], v[196:199], v[168:171], v[112:115]
	v_mfma_f32_16x16x32_bf16 v[108:111], v[204:207], v[138:141], v[108:111]
	v_mfma_f32_16x16x32_bf16 v[104:107], v[204:207], v[168:171], v[104:107]
	v_mfma_f32_16x16x32_bf16 v[100:103], v[212:215], v[138:141], v[100:103]
	v_mfma_f32_16x16x32_bf16 v[96:99], v[212:215], v[168:171], v[96:99]
	v_mfma_f32_16x16x32_bf16 v[68:71], v[216:219], v[180:183], v[60:63]
	v_mfma_f32_16x16x32_bf16 v[60:63], v[212:215], v[184:187], v[64:67]
	v_mfma_f32_16x16x32_bf16 v[124:127], v[192:195], v[142:145], v[124:127]
	v_mfma_f32_16x16x32_bf16 v[120:123], v[192:195], v[172:175], v[120:123]
	v_mfma_f32_16x16x32_bf16 v[116:119], v[200:203], v[142:145], v[116:119]
	v_mfma_f32_16x16x32_bf16 v[112:115], v[200:203], v[172:175], v[112:115]
	v_mfma_f32_16x16x32_bf16 v[108:111], v[208:211], v[142:145], v[108:111]
	v_mfma_f32_16x16x32_bf16 v[104:107], v[208:211], v[172:175], v[104:107]
	v_mfma_f32_16x16x32_bf16 v[100:103], v[216:219], v[142:145], v[100:103]
	v_mfma_f32_16x16x32_bf16 v[96:99], v[216:219], v[172:175], v[96:99]
	v_mfma_f32_16x16x32_bf16 v[92:95], v[192:195], v[180:183], v[92:95]
	v_mfma_f32_16x16x32_bf16 v[60:63], v[216:219], v[188:191], v[60:63]
	s_barrier
	s_setprio 0
	ds_read_b128 v[192:195], v147 offset:49152
	ds_read_b128 v[196:199], v147 offset:50176
	ds_read_b128 v[200:203], v147 offset:51200
	ds_read_b128 v[204:207], v147 offset:52224
	ds_read_b128 v[208:211], v147 offset:53248
	ds_read_b128 v[212:215], v147 offset:54272
	ds_read_b128 v[216:219], v147 offset:55296
	ds_read_b128 v[220:223], v147 offset:56320
	s_waitcnt lgkmcnt(0)
	s_setprio 1
	s_barrier
	v_mfma_f32_16x16x32_bf16 v[64:67], v[192:195], v[138:141], v[224:227]
	v_mfma_f32_16x16x32_bf16 v[56:59], v[192:195], v[168:171], v[56:59]
	v_mfma_f32_16x16x32_bf16 v[52:55], v[200:203], v[138:141], v[52:55]
	v_mfma_f32_16x16x32_bf16 v[48:51], v[200:203], v[168:171], v[48:51]
	v_mfma_f32_16x16x32_bf16 v[44:47], v[208:211], v[138:141], v[44:47]
	v_mfma_f32_16x16x32_bf16 v[40:43], v[208:211], v[168:171], v[40:43]
	v_mfma_f32_16x16x32_bf16 v[36:39], v[216:219], v[138:141], v[36:39]
	v_mfma_f32_16x16x32_bf16 v[32:35], v[216:219], v[168:171], v[32:35]
	v_mfma_f32_16x16x32_bf16 v[28:31], v[192:195], v[176:179], v[28:31]
	v_mfma_f32_16x16x32_bf16 v[24:27], v[192:195], v[184:187], v[24:27]
	v_mfma_f32_16x16x32_bf16 v[20:23], v[200:203], v[176:179], v[20:23]
	v_mfma_f32_16x16x32_bf16 v[16:19], v[200:203], v[184:187], v[16:19]
	v_mfma_f32_16x16x32_bf16 v[12:15], v[208:211], v[176:179], v[12:15]
	v_mfma_f32_16x16x32_bf16 v[8:11], v[208:211], v[184:187], v[8:11]
	v_mfma_f32_16x16x32_bf16 v[4:7], v[216:219], v[176:179], v[4:7]
	v_mfma_f32_16x16x32_bf16 v[0:3], v[216:219], v[184:187], v[0:3]
	v_mfma_f32_16x16x32_bf16 v[64:67], v[196:199], v[142:145], v[64:67]
	v_mfma_f32_16x16x32_bf16 v[56:59], v[196:199], v[172:175], v[56:59]
	v_mfma_f32_16x16x32_bf16 v[52:55], v[204:207], v[142:145], v[52:55]
	v_mfma_f32_16x16x32_bf16 v[48:51], v[204:207], v[172:175], v[48:51]
	v_mfma_f32_16x16x32_bf16 v[44:47], v[212:215], v[142:145], v[44:47]
	v_mfma_f32_16x16x32_bf16 v[40:43], v[212:215], v[172:175], v[40:43]
	v_mfma_f32_16x16x32_bf16 v[36:39], v[220:223], v[142:145], v[36:39]
	v_mfma_f32_16x16x32_bf16 v[32:35], v[220:223], v[172:175], v[32:35]
	v_mfma_f32_16x16x32_bf16 v[28:31], v[196:199], v[180:183], v[28:31]
	v_mfma_f32_16x16x32_bf16 v[24:27], v[196:199], v[188:191], v[24:27]
	v_mfma_f32_16x16x32_bf16 v[20:23], v[204:207], v[180:183], v[20:23]
	v_mfma_f32_16x16x32_bf16 v[16:19], v[204:207], v[188:191], v[16:19]
	v_mfma_f32_16x16x32_bf16 v[12:15], v[212:215], v[180:183], v[12:15]
	v_mfma_f32_16x16x32_bf16 v[8:11], v[212:215], v[188:191], v[8:11]
	v_mfma_f32_16x16x32_bf16 v[4:7], v[220:223], v[180:183], v[4:7]
	v_mfma_f32_16x16x32_bf16 v[0:3], v[220:223], v[188:191], v[0:3]
	s_barrier
	s_setprio 0
	s_and_saveexec_b64 s[66:67], s[6:7]
	s_cbranch_execz .LBB0_180
	s_barrier

; #define STAGE(Pp, BASE, br, kt) do { const u16* _g = (BASE) + ((long)(br) * K + (long)(kt) * BK); \
;     __builtin_amdgcn_global_load_lds((const unsigned*)(_g + voff0), (unsigned*)((char*)(Pp) + tb16), 16, 0, 0); \
;     __builtin_amdgcn_global_load_lds((const unsigned*)(_g + voff1), (unsigned*)((char*)(Pp) + tb16 + 8192), 16, 0, 0); } while (0)
; #define LDA(dst, b, h) _Pragma("unroll") for (int m = 0; m < 4; ++m) _Pragma("unroll") for (int k = 0; k < 2; ++k) \
;     dst[m][k] = *reinterpret_cast<const bf16x8*>((const char*)shm + aB + (((b) * 2 + (h)) * 16384 + (m * 2 + k) * 1024))
; #define LDB(dst, b, h) _Pragma("unroll") for (int n = 0; n < 2; ++n) _Pragma("unroll") for (int k = 0; k < 2; ++k) \
;     dst[n][k] = *reinterpret_cast<const bf16x8*>((const char*)shm + bB + (((b) * 2 + (h)) * 16384 + (n * 2 + k) * 1024))
; #define WAIT_V(n) asm volatile("s_waitcnt vmcnt(" #n ")" ::: "memory")
; #define WAIT_L(n) asm volatile("s_waitcnt lgkmcnt(" #n ")" ::: "memory")
; #define BAR __builtin_amdgcn_s_barrier()
; #define SCHED __builtin_amdgcn_sched_barrier(0)
; template <int MODE> ...
;     ...
;       LDB(B0, 0, 0); LDB(B1, 0, 1); LDA(At, 0, 0); STAGE(SA(1, 1), A, brow + HALF, t + 1);
;       WAIT_L(0); BAR; MMA2(0, 0, 0, 1); BAR; SCHED;
;       LDA(At, 0, 1); STAGE(SB(0, 0), Bt, bcol, t + 2); STAGE(SB(0, 1), Bt, bcol + HALF, t + 2); STAGE(SA(0, 0), A, brow, t + 2);
;       WAIT_V(6); WAIT_L(0); BAR; MMA2(1, 0, 1, 1); BAR; SCHED;
.LBB0_486:
	s_add_u32 s74, s32, 0xc000
	s_mov_b32 m0, s74
	ds_read_b128 v[166:169], v145
	ds_read_b128 v[170:173], v145 offset:1024
	ds_read_b128 v[174:177], v145 offset:2048
	ds_read_b128 v[178:181], v145 offset:3072
	ds_read_b128 v[182:185], v145 offset:16384
	ds_read_b128 v[186:189], v145 offset:17408
	ds_read_b128 v[190:193], v145 offset:18432
	ds_read_b128 v[194:197], v145 offset:19456
	ds_read_b128 v[198:201], v144
	ds_read_b128 v[202:205], v144 offset:1024
	ds_read_b128 v[206:209], v144 offset:2048
	ds_read_b128 v[210:213], v144 offset:3072
	ds_read_b128 v[214:217], v144 offset:4096
	ds_read_b128 v[218:221], v144 offset:5120
	ds_read_b128 v[222:225], v144 offset:6144
	ds_read_b128 v[226:229], v144 offset:7168
	s_add_u32 s88, s72, s16
	s_addc_u32 s89, s73, s17
	global_load_lds_dwordx4 v140, s[88:89]
	s_add_u32 s74, s32, 0xe000
	s_mov_b32 m0, s74
	s_nop 0
	s_add_u32 s90, s72, s16
	s_addc_u32 s91, s73, s17
	global_load_lds_dwordx4 v142, s[90:91]
	s_waitcnt vmcnt(8)
	s_waitcnt lgkmcnt(0)
	s_setprio 1
	s_barrier
	v_mfma_f32_16x16x32_bf16 v[124:127], v[198:201], v[166:169], v[124:127]
	v_mfma_f32_16x16x32_bf16 v[120:123], v[198:201], v[174:177], v[120:123]
	v_mfma_f32_16x16x32_bf16 v[116:119], v[206:209], v[166:169], v[116:119]
	v_mfma_f32_16x16x32_bf16 v[112:115], v[206:209], v[174:177], v[112:115]
	v_mfma_f32_16x16x32_bf16 v[108:111], v[214:217], v[166:169], v[108:111]
	v_mfma_f32_16x16x32_bf16 v[104:107], v[214:217], v[174:177], v[104:107]
	v_mfma_f32_16x16x32_bf16 v[100:103], v[222:225], v[166:169], v[100:103]
	v_mfma_f32_16x16x32_bf16 v[96:99], v[222:225], v[174:177], v[96:99]
	v_mfma_f32_16x16x32_bf16 v[92:95], v[198:201], v[182:185], v[92:95]
	v_mfma_f32_16x16x32_bf16 v[88:91], v[198:201], v[190:193], v[88:91]
	v_mfma_f32_16x16x32_bf16 v[84:87], v[206:209], v[182:185], v[84:87]
	v_mfma_f32_16x16x32_bf16 v[80:83], v[206:209], v[190:193], v[80:83]
	v_mfma_f32_16x16x32_bf16 v[76:79], v[214:217], v[182:185], v[76:79]
	v_mfma_f32_16x16x32_bf16 v[72:75], v[214:217], v[190:193], v[72:75]
	v_mfma_f32_16x16x32_bf16 v[68:71], v[222:225], v[182:185], v[68:71]
	v_mfma_f32_16x16x32_bf16 v[64:67], v[222:225], v[190:193], v[64:67]
	v_mfma_f32_16x16x32_bf16 v[124:127], v[202:205], v[170:173], v[124:127]
	v_mfma_f32_16x16x32_bf16 v[120:123], v[202:205], v[178:181], v[120:123]
	v_mfma_f32_16x16x32_bf16 v[116:119], v[210:213], v[170:173], v[116:119]
	v_mfma_f32_16x16x32_bf16 v[112:115], v[210:213], v[178:181], v[112:115]
	v_mfma_f32_16x16x32_bf16 v[108:111], v[218:221], v[170:173], v[108:111]
	v_mfma_f32_16x16x32_bf16 v[104:107], v[218:221], v[178:181], v[104:107]
	v_mfma_f32_16x16x32_bf16 v[100:103], v[226:229], v[170:173], v[100:103]
	v_mfma_f32_16x16x32_bf16 v[96:99], v[226:229], v[178:181], v[96:99]
	v_mfma_f32_16x16x32_bf16 v[92:95], v[202:205], v[186:189], v[92:95]
	v_mfma_f32_16x16x32_bf16 v[88:91], v[202:205], v[194:197], v[88:91]
	v_mfma_f32_16x16x32_bf16 v[84:87], v[210:213], v[186:189], v[84:87]
	v_mfma_f32_16x16x32_bf16 v[80:83], v[210:213], v[194:197], v[80:83]
	v_mfma_f32_16x16x32_bf16 v[76:79], v[218:221], v[186:189], v[76:79]
	v_mfma_f32_16x16x32_bf16 v[72:75], v[218:221], v[194:197], v[72:75]
	v_mfma_f32_16x16x32_bf16 v[68:71], v[226:229], v[186:189], v[68:71]
	v_mfma_f32_16x16x32_bf16 v[64:67], v[226:229], v[194:197], v[64:67]
	s_barrier
	s_setprio 0
	s_add_u32 s74, s32, 0x10000
	s_mov_b32 m0, s74
	ds_read_b128 v[198:201], v144 offset:16384
	ds_read_b128 v[202:205], v144 offset:17408
	ds_read_b128 v[206:209], v144 offset:18432
	ds_read_b128 v[210:213], v144 offset:19456
	ds_read_b128 v[214:217], v144 offset:20480
	ds_read_b128 v[218:221], v144 offset:21504
	ds_read_b128 v[222:225], v144 offset:22528
	ds_read_b128 v[226:229], v144 offset:23552
	s_add_u32 s92, s72, s38
	s_addc_u32 s93, s73, s39
	global_load_lds_dwordx4 v136, s[92:93]
	s_add_u32 s74, s32, 0x12000
	s_mov_b32 m0, s74
	s_add_u32 s74, s32, 0x14000
	s_add_u32 s96, s72, s38
	s_addc_u32 s97, s73, s39
	global_load_lds_dwordx4 v138, s[96:97]
	s_mov_b32 m0, s74
	s_add_u32 s74, s32, 0x16000
	s_add_u32 s88, s72, s40
	s_addc_u32 s89, s73, s41
	global_load_lds_dwordx4 v136, s[88:89]
	s_mov_b32 m0, s74
	s_mov_b32 s74, s32
	s_add_u32 s90, s72, s40
	s_addc_u32 s91, s73, s41
	global_load_lds_dwordx4 v138, s[90:91]
	s_mov_b32 m0, s74
	s_add_u32 s74, s32, 0x2000
	s_add_u32 s92, s72, s42
	s_addc_u32 s93, s73, s43
	global_load_lds_dwordx4 v140, s[92:93]
	s_mov_b32 m0, s74
	s_nop 0
	s_add_u32 s96, s72, s42
	s_addc_u32 s97, s73, s43
	global_load_lds_dwordx4 v142, s[96:97]
	s_waitcnt vmcnt(8)
	s_waitcnt lgkmcnt(0)
	s_setprio 1
	s_barrier
; #define STAGE(Pp, BASE, br, kt) do { const u16* _g = (BASE) + ((long)(br) * K + (long)(kt) * BK); \
;     __builtin_amdgcn_global_load_lds((const unsigned*)(_g + voff0), (unsigned*)((char*)(Pp) + tb16), 16, 0, 0); \
;     __builtin_amdgcn_global_load_lds((const unsigned*)(_g + voff1), (unsigned*)((char*)(Pp) + tb16 + 8192), 16, 0, 0); } while (0)
; #define LDA(dst, b, h) _Pragma("unroll") for (int m = 0; m < 4; ++m) _Pragma("unroll") for (int k = 0; k < 2; ++k) \
;     dst[m][k] = *reinterpret_cast<const bf16x8*>((const char*)shm + aB + (((b) * 2 + (h)) * 16384 + (m * 2 + k) * 1024))
; #define LDB(dst, b, h) _Pragma("unroll") for (int n = 0; n < 2; ++n) _Pragma("unroll") for (int k = 0; k < 2; ++k) \
;     dst[n][k] = *reinterpret_cast<const bf16x8*>((const char*)shm + bB + (((b) * 2 + (h)) * 16384 + (n * 2 + k) * 1024))
; #define WAIT_V(n) asm volatile("s_waitcnt vmcnt(" #n ")" ::: "memory")
; #define WAIT_L(n) asm volatile("s_waitcnt lgkmcnt(" #n ")" ::: "memory")
; #define BAR __builtin_amdgcn_s_barrier()
; #define SCHED __builtin_amdgcn_sched_barrier(0)
; template <int MODE> ...
;     ...
;       WAIT_V(6); WAIT_L(0); BAR; MMA2(1, 0, 1, 1); BAR; SCHED;
;       LDB(B0, 1, 0); LDB(B1, 1, 1); LDA(At, 1, 0); STAGE(SA(0, 1), A, brow + HALF, t + 2);
;       WAIT_L(0); BAR; MMA2(0, 0, 0, 1); BAR; SCHED;
	v_mfma_f32_16x16x32_bf16 v[60:63], v[198:201], v[166:169], v[60:63]
	v_mfma_f32_16x16x32_bf16 v[56:59], v[198:201], v[174:177], v[56:59]
	v_mfma_f32_16x16x32_bf16 v[52:55], v[206:209], v[166:169], v[52:55]
	v_mfma_f32_16x16x32_bf16 v[48:51], v[206:209], v[174:177], v[48:51]
	v_mfma_f32_16x16x32_bf16 v[44:47], v[214:217], v[166:169], v[44:47]
	v_mfma_f32_16x16x32_bf16 v[40:43], v[214:217], v[174:177], v[40:43]
	v_mfma_f32_16x16x32_bf16 v[36:39], v[222:225], v[166:169], v[36:39]
	v_mfma_f32_16x16x32_bf16 v[32:35], v[222:225], v[174:177], v[32:35]
	v_mfma_f32_16x16x32_bf16 v[28:31], v[198:201], v[182:185], v[28:31]
	v_mfma_f32_16x16x32_bf16 v[24:27], v[198:201], v[190:193], v[24:27]
	v_mfma_f32_16x16x32_bf16 v[20:23], v[206:209], v[182:185], v[20:23]
	v_mfma_f32_16x16x32_bf16 v[16:19], v[206:209], v[190:193], v[16:19]
	v_mfma_f32_16x16x32_bf16 v[12:15], v[214:217], v[182:185], v[12:15]
	v_mfma_f32_16x16x32_bf16 v[8:11], v[214:217], v[190:193], v[8:11]
	v_mfma_f32_16x16x32_bf16 v[4:7], v[222:225], v[182:185], v[4:7]
	v_mfma_f32_16x16x32_bf16 v[0:3], v[222:225], v[190:193], v[0:3]
	v_mfma_f32_16x16x32_bf16 v[60:63], v[202:205], v[170:173], v[60:63]
	v_mfma_f32_16x16x32_bf16 v[56:59], v[202:205], v[178:181], v[56:59]
	v_mfma_f32_16x16x32_bf16 v[52:55], v[210:213], v[170:173], v[52:55]
	v_mfma_f32_16x16x32_bf16 v[48:51], v[210:213], v[178:181], v[48:51]
	v_mfma_f32_16x16x32_bf16 v[44:47], v[218:221], v[170:173], v[44:47]
	v_mfma_f32_16x16x32_bf16 v[40:43], v[218:221], v[178:181], v[40:43]
	v_mfma_f32_16x16x32_bf16 v[36:39], v[226:229], v[170:173], v[36:39]
	v_mfma_f32_16x16x32_bf16 v[32:35], v[226:229], v[178:181], v[32:35]
	v_mfma_f32_16x16x32_bf16 v[28:31], v[202:205], v[186:189], v[28:31]
	v_mfma_f32_16x16x32_bf16 v[24:27], v[202:205], v[194:197], v[24:27]
	v_mfma_f32_16x16x32_bf16 v[20:23], v[210:213], v[186:189], v[20:23]
	v_mfma_f32_16x16x32_bf16 v[16:19], v[210:213], v[194:197], v[16:19]
	v_mfma_f32_16x16x32_bf16 v[12:15], v[218:221], v[186:189], v[12:15]
	v_mfma_f32_16x16x32_bf16 v[8:11], v[218:221], v[194:197], v[8:11]
	v_mfma_f32_16x16x32_bf16 v[4:7], v[226:229], v[186:189], v[4:7]
	v_mfma_f32_16x16x32_bf16 v[0:3], v[226:229], v[194:197], v[0:3]
	s_barrier
	s_setprio 0
	s_add_u32 s74, s32, 0x4000
	s_mov_b32 m0, s74
	s_add_u32 s74, s32, 0x6000
	ds_read_b128 v[166:169], v145 offset:32768
	ds_read_b128 v[170:173], v145 offset:33792
	ds_read_b128 v[174:177], v145 offset:34816
	ds_read_b128 v[178:181], v145 offset:35840
	ds_read_b128 v[182:185], v145 offset:49152
	ds_read_b128 v[186:189], v145 offset:50176
	ds_read_b128 v[190:193], v145 offset:51200
	ds_read_b128 v[194:197], v145 offset:52224
	ds_read_b128 v[198:201], v144 offset:32768
	ds_read_b128 v[202:205], v144 offset:33792
	ds_read_b128 v[206:209], v144 offset:34816
	ds_read_b128 v[210:213], v144 offset:35840
	ds_read_b128 v[214:217], v144 offset:36864
	ds_read_b128 v[218:221], v144 offset:37888
	ds_read_b128 v[222:225], v144 offset:38912
	ds_read_b128 v[226:229], v144 offset:39936
	s_add_u32 s88, s72, s44
	s_addc_u32 s89, s73, s45
	global_load_lds_dwordx4 v140, s[88:89]
	s_mov_b32 m0, s74
	s_nop 0
	s_add_u32 s90, s72, s44
	s_addc_u32 s91, s73, s45
	global_load_lds_dwordx4 v142, s[90:91]
	s_waitcnt vmcnt(8)
	s_waitcnt lgkmcnt(0)
	s_setprio 1
	s_barrier
	v_mfma_f32_16x16x32_bf16 v[124:127], v[198:201], v[166:169], v[124:127]
	v_mfma_f32_16x16x32_bf16 v[120:123], v[198:201], v[174:177], v[120:123]
	v_mfma_f32_16x16x32_bf16 v[116:119], v[206:209], v[166:169], v[116:119]
	v_mfma_f32_16x16x32_bf16 v[112:115], v[206:209], v[174:177], v[112:115]
	v_mfma_f32_16x16x32_bf16 v[108:111], v[214:217], v[166:169], v[108:111]
	v_mfma_f32_16x16x32_bf16 v[104:107], v[214:217], v[174:177], v[104:107]
	v_mfma_f32_16x16x32_bf16 v[100:103], v[222:225], v[166:169], v[100:103]
	v_mfma_f32_16x16x32_bf16 v[96:99], v[222:225], v[174:177], v[96:99]
	v_mfma_f32_16x16x32_bf16 v[92:95], v[198:201], v[182:185], v[92:95]
	v_mfma_f32_16x16x32_bf16 v[88:91], v[198:201], v[190:193], v[88:91]
	v_mfma_f32_16x16x32_bf16 v[84:87], v[206:209], v[182:185], v[84:87]
	v_mfma_f32_16x16x32_bf16 v[80:83], v[206:209], v[190:193], v[80:83]
	v_mfma_f32_16x16x32_bf16 v[76:79], v[214:217], v[182:185], v[76:79]
	v_mfma_f32_16x16x32_bf16 v[72:75], v[214:217], v[190:193], v[72:75]
	v_mfma_f32_16x16x32_bf16 v[68:71], v[222:225], v[182:185], v[68:71]
	v_mfma_f32_16x16x32_bf16 v[64:67], v[222:225], v[190:193], v[64:67]
	v_mfma_f32_16x16x32_bf16 v[124:127], v[202:205], v[170:173], v[124:127]
	v_mfma_f32_16x16x32_bf16 v[120:123], v[202:205], v[178:181], v[120:123]
	v_mfma_f32_16x16x32_bf16 v[116:119], v[210:213], v[170:173], v[116:119]
	v_mfma_f32_16x16x32_bf16 v[112:115], v[210:213], v[178:181], v[112:115]
	v_mfma_f32_16x16x32_bf16 v[108:111], v[218:221], v[170:173], v[108:111]
	v_mfma_f32_16x16x32_bf16 v[104:107], v[218:221], v[178:181], v[104:107]
	v_mfma_f32_16x16x32_bf16 v[100:103], v[226:229], v[170:173], v[100:103]
	v_mfma_f32_16x16x32_bf16 v[96:99], v[226:229], v[178:181], v[96:99]
	v_mfma_f32_16x16x32_bf16 v[92:95], v[202:205], v[186:189], v[92:95]
	v_mfma_f32_16x16x32_bf16 v[88:91], v[202:205], v[194:197], v[88:91]
	v_mfma_f32_16x16x32_bf16 v[84:87], v[210:213], v[186:189], v[84:87]
	v_mfma_f32_16x16x32_bf16 v[80:83], v[210:213], v[194:197], v[80:83]
	v_mfma_f32_16x16x32_bf16 v[76:79], v[218:221], v[186:189], v[76:79]
	v_mfma_f32_16x16x32_bf16 v[72:75], v[218:221], v[194:197], v[72:75]
	v_mfma_f32_16x16x32_bf16 v[68:71], v[226:229], v[186:189], v[68:71]
	v_mfma_f32_16x16x32_bf16 v[64:67], v[226:229], v[194:197], v[64:67]
	s_barrier
; #define STAGE(Pp, BASE, br, kt) do { const u16* _g = (BASE) + ((long)(br) * K + (long)(kt) * BK); \
;     __builtin_amdgcn_global_load_lds((const unsigned*)(_g + voff0), (unsigned*)((char*)(Pp) + tb16), 16, 0, 0); \
;     __builtin_amdgcn_global_load_lds((const unsigned*)(_g + voff1), (unsigned*)((char*)(Pp) + tb16 + 8192), 16, 0, 0); } while (0)
; #define LDA(dst, b, h) _Pragma("unroll") for (int m = 0; m < 4; ++m) _Pragma("unroll") for (int k = 0; k < 2; ++k) \
;     dst[m][k] = *reinterpret_cast<const bf16x8*>((const char*)shm + aB + (((b) * 2 + (h)) * 16384 + (m * 2 + k) * 1024))
; #define LDB(dst, b, h) _Pragma("unroll") for (int n = 0; n < 2; ++n) _Pragma("unroll") for (int k = 0; k < 2; ++k) \
;     dst[n][k] = *reinterpret_cast<const bf16x8*>((const char*)shm + bB + (((b) * 2 + (h)) * 16384 + (n * 2 + k) * 1024))
; #define WAIT_V(n) asm volatile("s_waitcnt vmcnt(" #n ")" ::: "memory")
; #define WAIT_L(n) asm volatile("s_waitcnt lgkmcnt(" #n ")" ::: "memory")
; #define BAR __builtin_amdgcn_s_barrier()
; #define SCHED __builtin_amdgcn_sched_barrier(0)
; template <int MODE> ...
;     ...
;       LDA(At, 1, 1); STAGE(SB(1, 0), Bt, bcol, t + 3); STAGE(SB(1, 1), Bt, bcol + HALF, t + 3); STAGE(SA(1, 0), A, brow, t + 3);
;       WAIT_V(6); WAIT_L(0); BAR; MMA2(1, 0, 1, 1); BAR; SCHED;
;     }
;     {
;       LDB(B0, 0, 0); LDB(B1, 0, 1); LDA(At, 0, 0); STAGE(SA(1, 1), A, brow + HALF, nt - 1);
;       WAIT_L(0); BAR; MMA2(0, 0, 0, 1); BAR; SCHED;
	s_setprio 0
	s_add_u32 s74, s32, 0x18000
	s_mov_b32 m0, s74
	s_add_u32 s74, s32, 0x1a000
	ds_read_b128 v[198:201], v144 offset:49152
	ds_read_b128 v[202:205], v144 offset:50176
	ds_read_b128 v[206:209], v144 offset:51200
	ds_read_b128 v[210:213], v144 offset:52224
	ds_read_b128 v[214:217], v144 offset:53248
	ds_read_b128 v[218:221], v144 offset:54272
	ds_read_b128 v[222:225], v144 offset:55296
	ds_read_b128 v[226:229], v144 offset:56320
	s_add_u32 s92, s72, s48
	s_addc_u32 s93, s73, s49
	global_load_lds_dwordx4 v136, s[92:93]
	s_mov_b32 m0, s74
	s_add_u32 s74, s32, 0x1c000
	s_add_u32 s96, s72, s48
	s_addc_u32 s97, s73, s49
	global_load_lds_dwordx4 v138, s[96:97]
	s_mov_b32 m0, s74
	s_add_u32 s74, s32, 0x1e000
	s_add_u32 s88, s72, s50
	s_addc_u32 s89, s73, s51
	global_load_lds_dwordx4 v136, s[88:89]
	s_mov_b32 m0, s74
	s_add_u32 s74, s32, 0x8000
	s_add_u32 s90, s72, s50
	s_addc_u32 s91, s73, s51
	global_load_lds_dwordx4 v138, s[90:91]
	s_mov_b32 m0, s74
	s_add_u32 s74, s32, 0xa000
	s_add_u32 s92, s72, s60
	s_addc_u32 s93, s73, s61
	global_load_lds_dwordx4 v140, s[92:93]
	s_mov_b32 m0, s74
	s_nop 0
	s_add_u32 s96, s72, s60
	s_addc_u32 s97, s73, s61
	global_load_lds_dwordx4 v142, s[96:97]
	s_waitcnt vmcnt(8)
	s_waitcnt lgkmcnt(0)
	s_setprio 1
	s_barrier
	v_mfma_f32_16x16x32_bf16 v[60:63], v[198:201], v[166:169], v[60:63]
	v_mfma_f32_16x16x32_bf16 v[56:59], v[198:201], v[174:177], v[56:59]
	v_mfma_f32_16x16x32_bf16 v[52:55], v[206:209], v[166:169], v[52:55]
	v_mfma_f32_16x16x32_bf16 v[48:51], v[206:209], v[174:177], v[48:51]
	v_mfma_f32_16x16x32_bf16 v[44:47], v[214:217], v[166:169], v[44:47]
	v_mfma_f32_16x16x32_bf16 v[40:43], v[214:217], v[174:177], v[40:43]
	v_mfma_f32_16x16x32_bf16 v[36:39], v[222:225], v[166:169], v[36:39]
	v_mfma_f32_16x16x32_bf16 v[32:35], v[222:225], v[174:177], v[32:35]
	v_mfma_f32_16x16x32_bf16 v[28:31], v[198:201], v[182:185], v[28:31]
	v_mfma_f32_16x16x32_bf16 v[24:27], v[198:201], v[190:193], v[24:27]
	v_mfma_f32_16x16x32_bf16 v[20:23], v[206:209], v[182:185], v[20:23]
	v_mfma_f32_16x16x32_bf16 v[16:19], v[206:209], v[190:193], v[16:19]
	v_mfma_f32_16x16x32_bf16 v[12:15], v[214:217], v[182:185], v[12:15]
	v_mfma_f32_16x16x32_bf16 v[8:11], v[214:217], v[190:193], v[8:11]
	v_mfma_f32_16x16x32_bf16 v[4:7], v[222:225], v[182:185], v[4:7]
	v_mfma_f32_16x16x32_bf16 v[0:3], v[222:225], v[190:193], v[0:3]
	v_mfma_f32_16x16x32_bf16 v[60:63], v[202:205], v[170:173], v[60:63]
	v_mfma_f32_16x16x32_bf16 v[56:59], v[202:205], v[178:181], v[56:59]
	v_mfma_f32_16x16x32_bf16 v[52:55], v[210:213], v[170:173], v[52:55]
	v_mfma_f32_16x16x32_bf16 v[48:51], v[210:213], v[178:181], v[48:51]
	v_mfma_f32_16x16x32_bf16 v[44:47], v[218:221], v[170:173], v[44:47]
	v_mfma_f32_16x16x32_bf16 v[40:43], v[218:221], v[178:181], v[40:43]
	v_mfma_f32_16x16x32_bf16 v[36:39], v[226:229], v[170:173], v[36:39]
	v_mfma_f32_16x16x32_bf16 v[32:35], v[226:229], v[178:181], v[32:35]
	v_mfma_f32_16x16x32_bf16 v[28:31], v[202:205], v[186:189], v[28:31]
	v_mfma_f32_16x16x32_bf16 v[24:27], v[202:205], v[194:197], v[24:27]
	v_mfma_f32_16x16x32_bf16 v[20:23], v[210:213], v[186:189], v[20:23]
	v_mfma_f32_16x16x32_bf16 v[16:19], v[210:213], v[194:197], v[16:19]
	v_mfma_f32_16x16x32_bf16 v[12:15], v[218:221], v[186:189], v[12:15]
	v_mfma_f32_16x16x32_bf16 v[8:11], v[218:221], v[194:197], v[8:11]
	v_mfma_f32_16x16x32_bf16 v[4:7], v[226:229], v[186:189], v[4:7]
	v_mfma_f32_16x16x32_bf16 v[0:3], v[226:229], v[194:197], v[0:3]
	s_barrier
	s_setprio 0
	s_add_i32 s63, s63, 2
	s_add_u32 s72, s72, 0x100
	s_addc_u32 s73, s73, 0
	s_cmp_lt_u32 s63, 60
	s_cbranch_scc1 .LBB0_486
	s_add_u32 s70, s70, 0x1f80
	v_readfirstlane_b32 s63, v160
	s_addc_u32 s71, s71, 0
	s_mov_b32 m0, s63
	v_readfirstlane_b32 s63, v161
	ds_read_b128 v[136:139], v145
	ds_read_b128 v[140:143], v145 offset:1024
	ds_read_b128 v[166:169], v145 offset:2048
	ds_read_b128 v[170:173], v145 offset:3072
	ds_read_b128 v[174:177], v145 offset:16384
	ds_read_b128 v[178:181], v145 offset:17408
	ds_read_b128 v[182:185], v145 offset:18432
	ds_read_b128 v[186:189], v145 offset:19456
	ds_read_b128 v[190:193], v144
	ds_read_b128 v[194:197], v144 offset:1024
	ds_read_b128 v[198:201], v144 offset:2048
	ds_read_b128 v[202:205], v144 offset:3072
	ds_read_b128 v[206:209], v144 offset:4096
	ds_read_b128 v[210:213], v144 offset:5120
	ds_read_b128 v[214:217], v144 offset:6144
	ds_read_b128 v[218:221], v144 offset:7168
	global_load_lds_dwordx4 v132, s[70:71]
	s_mov_b32 m0, s63
	s_nop 0
	global_load_lds_dwordx4 v134, s[70:71]
	s_waitcnt vmcnt(8)
	s_waitcnt lgkmcnt(0)
	s_setprio 1
	s_barrier
; #define STAGE(Pp, BASE, br, kt) do { const u16* _g = (BASE) + ((long)(br) * K + (long)(kt) * BK); \
;     __builtin_amdgcn_global_load_lds((const unsigned*)(_g + voff0), (unsigned*)((char*)(Pp) + tb16), 16, 0, 0); \
;     __builtin_amdgcn_global_load_lds((const unsigned*)(_g + voff1), (unsigned*)((char*)(Pp) + tb16 + 8192), 16, 0, 0); } while (0)
; #define LDA(dst, b, h) _Pragma("unroll") for (int m = 0; m < 4; ++m) _Pragma("unroll") for (int k = 0; k < 2; ++k) \
;     dst[m][k] = *reinterpret_cast<const bf16x8*>((const char*)shm + aB + (((b) * 2 + (h)) * 16384 + (m * 2 + k) * 1024))
; #define LDB(dst, b, h) _Pragma("unroll") for (int n = 0; n < 2; ++n) _Pragma("unroll") for (int k = 0; k < 2; ++k) \
;     dst[n][k] = *reinterpret_cast<const bf16x8*>((const char*)shm + bB + (((b) * 2 + (h)) * 16384 + (n * 2 + k) * 1024))
; #define WAIT_V(n) asm volatile("s_waitcnt vmcnt(" #n ")" ::: "memory")
; #define WAIT_L(n) asm volatile("s_waitcnt lgkmcnt(" #n ")" ::: "memory")
; #define BAR __builtin_amdgcn_s_barrier()
; #define SCHED __builtin_amdgcn_sched_barrier(0)
; template <int MODE> ...
;     ...
;       LDB(B0, 0, 0); LDB(B1, 0, 1); LDA(At, 0, 0); STAGE(SA(1, 1), A, brow + HALF, nt - 1);
;       WAIT_L(0); BAR; MMA2(0, 0, 0, 1); BAR; SCHED;
;       LDA(At, 0, 1); WAIT_V(0); WAIT_L(0); BAR; MMA2(1, 0, 1, 1); BAR; SCHED;
	v_mfma_f32_16x16x32_bf16 v[124:127], v[190:193], v[136:139], v[124:127]
	v_mfma_f32_16x16x32_bf16 v[116:119], v[198:201], v[136:139], v[116:119]
	v_mfma_f32_16x16x32_bf16 v[108:111], v[206:209], v[136:139], v[108:111]
	v_mfma_f32_16x16x32_bf16 v[100:103], v[214:217], v[136:139], v[100:103]
	v_mfma_f32_16x16x32_bf16 v[96:99], v[214:217], v[166:169], v[96:99]
	v_mfma_f32_16x16x32_bf16 v[92:95], v[190:193], v[174:177], v[92:95]
	v_mfma_f32_16x16x32_bf16 v[88:91], v[190:193], v[182:185], v[88:91]
	v_mfma_f32_16x16x32_bf16 v[80:83], v[198:201], v[182:185], v[80:83]
	v_mfma_f32_16x16x32_bf16 v[76:79], v[206:209], v[174:177], v[76:79]
	v_mfma_f32_16x16x32_bf16 v[124:127], v[194:197], v[140:143], v[124:127]
	v_mfma_f32_16x16x32_bf16 v[120:123], v[190:193], v[166:169], v[120:123]
	v_mfma_f32_16x16x32_bf16 v[116:119], v[202:205], v[140:143], v[116:119]
	v_mfma_f32_16x16x32_bf16 v[112:115], v[198:201], v[166:169], v[112:115]
	v_mfma_f32_16x16x32_bf16 v[108:111], v[210:213], v[140:143], v[108:111]
	v_mfma_f32_16x16x32_bf16 v[104:107], v[206:209], v[166:169], v[104:107]
	v_mfma_f32_16x16x32_bf16 v[100:103], v[218:221], v[140:143], v[100:103]
	v_mfma_f32_16x16x32_bf16 v[96:99], v[218:221], v[170:173], v[96:99]
	v_mfma_f32_16x16x32_bf16 v[92:95], v[194:197], v[178:181], v[92:95]
	v_mfma_f32_16x16x32_bf16 v[88:91], v[194:197], v[186:189], v[88:91]
	v_mfma_f32_16x16x32_bf16 v[84:87], v[198:201], v[174:177], v[84:87]
	v_mfma_f32_16x16x32_bf16 v[80:83], v[202:205], v[186:189], v[80:83]
	v_mfma_f32_16x16x32_bf16 v[76:79], v[210:213], v[178:181], v[76:79]
	v_mfma_f32_16x16x32_bf16 v[72:75], v[206:209], v[182:185], v[72:75]
	v_mfma_f32_16x16x32_bf16 v[68:71], v[214:217], v[174:177], v[68:71]
	v_mfma_f32_16x16x32_bf16 v[64:67], v[214:217], v[182:185], v[64:67]
	v_mfma_f32_16x16x32_bf16 v[222:225], v[194:197], v[170:173], v[120:123]
	v_mfma_f32_16x16x32_bf16 v[226:229], v[202:205], v[170:173], v[112:115]
	v_mfma_f32_16x16x32_bf16 v[230:233], v[210:213], v[170:173], v[104:107]
	v_mfma_f32_16x16x32_bf16 v[190:193], v[202:205], v[178:181], v[84:87]
	v_mfma_f32_16x16x32_bf16 v[194:197], v[210:213], v[186:189], v[72:75]
	v_mfma_f32_16x16x32_bf16 v[198:201], v[218:221], v[178:181], v[68:71]
	v_mfma_f32_16x16x32_bf16 v[202:205], v[218:221], v[186:189], v[64:67]
	s_barrier
	s_setprio 0
	s_nop 0
	ds_read_b128 v[64:67], v144 offset:16384
	ds_read_b128 v[68:71], v144 offset:17408
	ds_read_b128 v[72:75], v144 offset:18432
	ds_read_b128 v[84:87], v144 offset:19456
	ds_read_b128 v[104:107], v144 offset:20480
	ds_read_b128 v[112:115], v144 offset:21504
	ds_read_b128 v[120:123], v144 offset:22528
	ds_read_b128 v[206:209], v144 offset:23552
	s_waitcnt vmcnt(0)
	s_waitcnt lgkmcnt(0)
	s_setprio 1
	s_barrier
	v_mfma_f32_16x16x32_bf16 v[60:63], v[64:67], v[136:139], v[60:63]
	v_mfma_f32_16x16x32_bf16 v[56:59], v[64:67], v[166:169], v[56:59]
	v_mfma_f32_16x16x32_bf16 v[52:55], v[72:75], v[136:139], v[52:55]
	v_mfma_f32_16x16x32_bf16 v[48:51], v[72:75], v[166:169], v[48:51]
	v_mfma_f32_16x16x32_bf16 v[44:47], v[104:107], v[136:139], v[44:47]
	v_mfma_f32_16x16x32_bf16 v[40:43], v[104:107], v[166:169], v[40:43]
	v_mfma_f32_16x16x32_bf16 v[28:31], v[64:67], v[174:177], v[28:31]
	v_mfma_f32_16x16x32_bf16 v[24:27], v[64:67], v[182:185], v[24:27]
	v_mfma_f32_16x16x32_bf16 v[20:23], v[72:75], v[174:177], v[20:23]
	v_mfma_f32_16x16x32_bf16 v[60:63], v[68:71], v[140:143], v[60:63]
	v_mfma_f32_16x16x32_bf16 v[56:59], v[68:71], v[170:173], v[56:59]
	v_mfma_f32_16x16x32_bf16 v[52:55], v[84:87], v[140:143], v[52:55]
	v_mfma_f32_16x16x32_bf16 v[48:51], v[84:87], v[170:173], v[48:51]
	v_mfma_f32_16x16x32_bf16 v[44:47], v[112:115], v[140:143], v[44:47]
	v_mfma_f32_16x16x32_bf16 v[40:43], v[112:115], v[170:173], v[40:43]
	v_mfma_f32_16x16x32_bf16 v[36:39], v[120:123], v[136:139], v[36:39]
	v_mfma_f32_16x16x32_bf16 v[32:35], v[120:123], v[166:169], v[32:35]
	v_mfma_f32_16x16x32_bf16 v[28:31], v[68:71], v[178:181], v[28:31]
	v_mfma_f32_16x16x32_bf16 v[24:27], v[68:71], v[186:189], v[24:27]
	v_mfma_f32_16x16x32_bf16 v[20:23], v[84:87], v[178:181], v[20:23]
	v_mfma_f32_16x16x32_bf16 v[16:19], v[72:75], v[182:185], v[16:19]
	v_mfma_f32_16x16x32_bf16 v[12:15], v[104:107], v[174:177], v[12:15]
	v_mfma_f32_16x16x32_bf16 v[8:11], v[104:107], v[182:185], v[8:11]
	v_mfma_f32_16x16x32_bf16 v[4:7], v[120:123], v[174:177], v[4:7]
	v_mfma_f32_16x16x32_bf16 v[0:3], v[120:123], v[182:185], v[0:3]
	v_mfma_f32_16x16x32_bf16 v[136:139], v[206:209], v[140:143], v[36:39]
	v_mfma_f32_16x16x32_bf16 v[140:143], v[206:209], v[170:173], v[32:35]
	v_mfma_f32_16x16x32_bf16 v[166:169], v[84:87], v[186:189], v[16:19]
	v_mfma_f32_16x16x32_bf16 v[170:173], v[112:115], v[178:181], v[12:15]
	v_mfma_f32_16x16x32_bf16 v[210:213], v[112:115], v[186:189], v[8:11]
	v_mfma_f32_16x16x32_bf16 v[174:177], v[206:209], v[178:181], v[4:7]
	v_mfma_f32_16x16x32_bf16 v[178:181], v[206:209], v[186:189], v[0:3]
	s_barrier
; #define LDA(dst, b, h) _Pragma("unroll") for (int m = 0; m < 4; ++m) _Pragma("unroll") for (int k = 0; k < 2; ++k) \
;     dst[m][k] = *reinterpret_cast<const bf16x8*>((const char*)shm + aB + (((b) * 2 + (h)) * 16384 + (m * 2 + k) * 1024))
; #define LDB(dst, b, h) _Pragma("unroll") for (int n = 0; n < 2; ++n) _Pragma("unroll") for (int k = 0; k < 2; ++k) \
;     dst[n][k] = *reinterpret_cast<const bf16x8*>((const char*)shm + bB + (((b) * 2 + (h)) * 16384 + (n * 2 + k) * 1024))
; #define WAIT_L(n) asm volatile("s_waitcnt lgkmcnt(" #n ")" ::: "memory")
; #define BAR __builtin_amdgcn_s_barrier()
; #define SCHED __builtin_amdgcn_sched_barrier(0)
; template <int MODE> ...
;     ...
;       LDB(B0, 1, 0); LDB(B1, 1, 1); LDA(At, 1, 0); WAIT_L(0); BAR; MMA2(0, 0, 0, 1); BAR; SCHED;
;       LDA(At, 1, 1); WAIT_L(0); BAR; MMA2(1, 0, 1, 1); BAR; SCHED;
;     }
;     ...
;     if (wr == 0) BAR;
	s_setprio 0
	ds_read_b128 v[12:15], v145 offset:32768
	ds_read_b128 v[16:19], v145 offset:33792
	ds_read_b128 v[182:185], v145 offset:34816
	ds_read_b128 v[186:189], v145 offset:35840
	ds_read_b128 v[206:209], v145 offset:49152
	ds_read_b128 v[214:217], v145 offset:50176
	ds_read_b128 v[218:221], v145 offset:51200
	ds_read_b128 v[234:237], v145 offset:52224
	ds_read_b128 v[0:3], v144 offset:32768
	ds_read_b128 v[4:7], v144 offset:33792
	ds_read_b128 v[8:11], v144 offset:34816
	ds_read_b128 v[32:35], v144 offset:35840
	ds_read_b128 v[36:39], v144 offset:36864
	ds_read_b128 v[238:241], v144 offset:37888
	ds_read_b128 v[242:245], v144 offset:38912
	ds_read_b128 v[246:249], v144 offset:39936
	s_waitcnt lgkmcnt(0)
	s_setprio 1
	s_barrier
	v_mfma_f32_16x16x32_bf16 v[64:67], v[0:3], v[12:15], v[124:127]
	v_mfma_f32_16x16x32_bf16 v[68:71], v[242:245], v[182:185], v[96:99]
	v_mfma_f32_16x16x32_bf16 v[120:123], v[4:7], v[16:19], v[64:67]
	v_mfma_f32_16x16x32_bf16 v[64:67], v[0:3], v[182:185], v[222:225]
	v_mfma_f32_16x16x32_bf16 v[84:87], v[246:249], v[186:189], v[68:71]
	v_mfma_f32_16x16x32_bf16 v[68:71], v[0:3], v[206:209], v[92:95]
	v_mfma_f32_16x16x32_bf16 v[0:3], v[0:3], v[218:221], v[88:91]
	v_mfma_f32_16x16x32_bf16 v[88:91], v[4:7], v[234:237], v[0:3]
	v_mfma_f32_16x16x32_bf16 v[0:3], v[8:11], v[206:209], v[190:193]
	v_mfma_f32_16x16x32_bf16 v[124:127], v[4:7], v[186:189], v[64:67]
	v_mfma_f32_16x16x32_bf16 v[64:67], v[8:11], v[12:15], v[116:119]
	v_mfma_f32_16x16x32_bf16 v[72:75], v[32:35], v[214:217], v[0:3]
	v_mfma_f32_16x16x32_bf16 v[0:3], v[8:11], v[218:221], v[80:83]
	v_mfma_f32_16x16x32_bf16 v[112:115], v[32:35], v[16:19], v[64:67]
	v_mfma_f32_16x16x32_bf16 v[64:67], v[8:11], v[182:185], v[226:229]
	v_mfma_f32_16x16x32_bf16 v[92:95], v[32:35], v[234:237], v[0:3]
	v_mfma_f32_16x16x32_bf16 v[0:3], v[36:39], v[206:209], v[76:79]
	v_mfma_f32_16x16x32_bf16 v[116:119], v[32:35], v[186:189], v[64:67]
	v_mfma_f32_16x16x32_bf16 v[64:67], v[36:39], v[12:15], v[108:111]
	v_mfma_f32_16x16x32_bf16 v[76:79], v[238:241], v[214:217], v[0:3]
	v_mfma_f32_16x16x32_bf16 v[0:3], v[36:39], v[218:221], v[194:197]
	v_mfma_f32_16x16x32_bf16 v[104:107], v[238:241], v[16:19], v[64:67]
	v_mfma_f32_16x16x32_bf16 v[64:67], v[36:39], v[182:185], v[230:233]
	v_mfma_f32_16x16x32_bf16 v[96:99], v[238:241], v[234:237], v[0:3]
	v_mfma_f32_16x16x32_bf16 v[0:3], v[242:245], v[206:209], v[198:201]
	v_mfma_f32_16x16x32_bf16 v[108:111], v[238:241], v[186:189], v[64:67]
	v_mfma_f32_16x16x32_bf16 v[64:67], v[242:245], v[12:15], v[100:103]
	v_mfma_f32_16x16x32_bf16 v[80:83], v[246:249], v[214:217], v[0:3]
	v_mfma_f32_16x16x32_bf16 v[0:3], v[242:245], v[218:221], v[202:205]
	v_mfma_f32_16x16x32_bf16 v[64:67], v[246:249], v[16:19], v[64:67]
	v_mfma_f32_16x16x32_bf16 v[68:71], v[4:7], v[214:217], v[68:71]
	v_mfma_f32_16x16x32_bf16 v[100:103], v[246:249], v[234:237], v[0:3]
	s_barrier
	s_setprio 0
	ds_read_b128 v[190:193], v144 offset:49152
	ds_read_b128 v[194:197], v144 offset:50176
	ds_read_b128 v[198:201], v144 offset:51200
	ds_read_b128 v[202:205], v144 offset:52224
	ds_read_b128 v[222:225], v144 offset:53248
	ds_read_b128 v[226:229], v144 offset:54272
	ds_read_b128 v[230:233], v144 offset:55296
	ds_read_b128 v[238:241], v144 offset:56320
	s_waitcnt lgkmcnt(0)
	s_setprio 1
	s_barrier
	v_mfma_f32_16x16x32_bf16 v[4:7], v[190:193], v[182:185], v[56:59]
	v_mfma_f32_16x16x32_bf16 v[8:11], v[198:201], v[182:185], v[48:51]
	v_mfma_f32_16x16x32_bf16 v[0:3], v[190:193], v[12:15], v[60:63]
	v_mfma_f32_16x16x32_bf16 v[32:35], v[194:197], v[186:189], v[4:7]
	v_mfma_f32_16x16x32_bf16 v[4:7], v[198:201], v[12:15], v[52:55]
	v_mfma_f32_16x16x32_bf16 v[36:39], v[202:205], v[186:189], v[8:11]
	v_mfma_f32_16x16x32_bf16 v[8:11], v[222:225], v[12:15], v[44:47]
	v_mfma_f32_16x16x32_bf16 v[12:15], v[230:233], v[12:15], v[136:139]
	v_mfma_f32_16x16x32_bf16 v[0:3], v[194:197], v[16:19], v[0:3]
	v_mfma_f32_16x16x32_bf16 v[4:7], v[202:205], v[16:19], v[4:7]
	v_mfma_f32_16x16x32_bf16 v[8:11], v[226:229], v[16:19], v[8:11]
	v_mfma_f32_16x16x32_bf16 v[12:15], v[238:241], v[16:19], v[12:15]
	v_mfma_f32_16x16x32_bf16 v[16:19], v[230:233], v[182:185], v[140:143]
	v_mfma_f32_16x16x32_bf16 v[24:27], v[190:193], v[218:221], v[24:27]
	v_mfma_f32_16x16x32_bf16 v[44:47], v[238:241], v[186:189], v[16:19]
	v_mfma_f32_16x16x32_bf16 v[16:19], v[190:193], v[206:209], v[28:31]
	v_mfma_f32_16x16x32_bf16 v[48:51], v[194:197], v[234:237], v[24:27]
	v_mfma_f32_16x16x32_bf16 v[24:27], v[198:201], v[218:221], v[166:169]
	v_mfma_f32_16x16x32_bf16 v[28:31], v[222:225], v[218:221], v[210:213]
	v_mfma_f32_16x16x32_bf16 v[40:43], v[222:225], v[182:185], v[40:43]
	v_mfma_f32_16x16x32_bf16 v[20:23], v[198:201], v[206:209], v[20:23]
	v_mfma_f32_16x16x32_bf16 v[52:55], v[202:205], v[234:237], v[24:27]
	v_mfma_f32_16x16x32_bf16 v[24:27], v[222:225], v[206:209], v[170:173]
	v_mfma_f32_16x16x32_bf16 v[56:59], v[226:229], v[234:237], v[28:31]
	v_mfma_f32_16x16x32_bf16 v[28:31], v[230:233], v[206:209], v[174:177]
	v_mfma_f32_16x16x32_bf16 v[60:63], v[230:233], v[218:221], v[178:181]
	v_mfma_f32_16x16x32_bf16 v[40:43], v[226:229], v[186:189], v[40:43]
	v_mfma_f32_16x16x32_bf16 v[16:19], v[194:197], v[214:217], v[16:19]
	v_mfma_f32_16x16x32_bf16 v[20:23], v[202:205], v[214:217], v[20:23]
	v_mfma_f32_16x16x32_bf16 v[24:27], v[226:229], v[214:217], v[24:27]
	v_mfma_f32_16x16x32_bf16 v[28:31], v[238:241], v[214:217], v[28:31]
	v_mfma_f32_16x16x32_bf16 v[60:63], v[238:241], v[234:237], v[60:63]
	s_barrier
	s_setprio 0
	s_and_saveexec_b64 s[70:71], s[6:7]
	s_cbranch_execz .LBB0_489
	s_barrier

; #define STAGE(Pp, BASE, br, kt) do { const u16* _g = (BASE) + ((long)(br) * K + (long)(kt) * BK); \
;     __builtin_amdgcn_global_load_lds((const unsigned*)(_g + voff0), (unsigned*)((char*)(Pp) + tb16), 16, 0, 0); \
;     __builtin_amdgcn_global_load_lds((const unsigned*)(_g + voff1), (unsigned*)((char*)(Pp) + tb16 + 8192), 16, 0, 0); } while (0)
; #define LDA(dst, b, h) _Pragma("unroll") for (int m = 0; m < 4; ++m) _Pragma("unroll") for (int k = 0; k < 2; ++k) \
;     dst[m][k] = *reinterpret_cast<const bf16x8*>((const char*)shm + aB + (((b) * 2 + (h)) * 16384 + (m * 2 + k) * 1024))
; #define LDB(dst, b, h) _Pragma("unroll") for (int n = 0; n < 2; ++n) _Pragma("unroll") for (int k = 0; k < 2; ++k) \
;     dst[n][k] = *reinterpret_cast<const bf16x8*>((const char*)shm + bB + (((b) * 2 + (h)) * 16384 + (n * 2 + k) * 1024))
; #define WAIT_V(n) asm volatile("s_waitcnt vmcnt(" #n ")" ::: "memory")
; #define WAIT_L(n) asm volatile("s_waitcnt lgkmcnt(" #n ")" ::: "memory")
; #define BAR __builtin_amdgcn_s_barrier()
; #define SCHED __builtin_amdgcn_sched_barrier(0)
; template <int MODE> ...
;     ...
;       LDB(B0, 0, 0); LDB(B1, 0, 1); LDA(At, 0, 0); STAGE(SA(1, 1), A, brow + HALF, t + 1);
;       WAIT_L(0); BAR; MMA2(0, 0, 0, 1); BAR; SCHED;
;       LDA(At, 0, 1); STAGE(SB(0, 0), Bt, bcol, t + 2); STAGE(SB(0, 1), Bt, bcol + HALF, t + 2); STAGE(SA(0, 0), A, brow, t + 2);
;       WAIT_V(6); WAIT_L(0); BAR; MMA2(1, 0, 1, 1); BAR; SCHED;
.LBB0_591:
	s_add_u32 s65, s32, 0xc000
	s_mov_b32 m0, s65
	ds_read_b128 v[168:171], v149
	ds_read_b128 v[172:175], v149 offset:1024
	ds_read_b128 v[176:179], v149 offset:2048
	ds_read_b128 v[180:183], v149 offset:3072
	ds_read_b128 v[184:187], v149 offset:16384
	ds_read_b128 v[188:191], v149 offset:17408
	ds_read_b128 v[192:195], v149 offset:18432
	ds_read_b128 v[196:199], v149 offset:19456
	ds_read_b128 v[200:203], v148
	ds_read_b128 v[204:207], v148 offset:1024
	ds_read_b128 v[208:211], v148 offset:2048
	ds_read_b128 v[212:215], v148 offset:3072
	ds_read_b128 v[216:219], v148 offset:4096
	ds_read_b128 v[220:223], v148 offset:5120
	ds_read_b128 v[224:227], v148 offset:6144
	ds_read_b128 v[228:231], v148 offset:7168
	s_add_u32 s88, s10, s38
	s_addc_u32 s89, s11, s39
	global_load_lds_dwordx4 v142, s[88:89]
	s_add_u32 s65, s32, 0xe000
	s_mov_b32 m0, s65
	s_nop 0
	s_add_u32 s90, s10, s38
	s_addc_u32 s91, s11, s39
	global_load_lds_dwordx4 v144, s[90:91]
	s_waitcnt vmcnt(8)
	s_waitcnt lgkmcnt(0)
	s_setprio 1
	s_barrier
	v_mfma_f32_16x16x32_bf16 v[124:127], v[200:203], v[168:171], v[124:127]
	v_mfma_f32_16x16x32_bf16 v[120:123], v[200:203], v[176:179], v[120:123]
	v_mfma_f32_16x16x32_bf16 v[116:119], v[208:211], v[168:171], v[116:119]
	v_mfma_f32_16x16x32_bf16 v[112:115], v[208:211], v[176:179], v[112:115]
	v_mfma_f32_16x16x32_bf16 v[108:111], v[216:219], v[168:171], v[108:111]
	v_mfma_f32_16x16x32_bf16 v[104:107], v[216:219], v[176:179], v[104:107]
	v_mfma_f32_16x16x32_bf16 v[100:103], v[224:227], v[168:171], v[100:103]
	v_mfma_f32_16x16x32_bf16 v[96:99], v[224:227], v[176:179], v[96:99]
	v_mfma_f32_16x16x32_bf16 v[88:91], v[200:203], v[184:187], v[88:91]
	v_mfma_f32_16x16x32_bf16 v[72:75], v[200:203], v[192:195], v[72:75]
	v_mfma_f32_16x16x32_bf16 v[56:59], v[208:211], v[184:187], v[56:59]
	v_mfma_f32_16x16x32_bf16 v[48:51], v[208:211], v[192:195], v[48:51]
	v_mfma_f32_16x16x32_bf16 v[44:47], v[216:219], v[184:187], v[44:47]
	v_mfma_f32_16x16x32_bf16 v[40:43], v[216:219], v[192:195], v[40:43]
	v_mfma_f32_16x16x32_bf16 v[36:39], v[224:227], v[184:187], v[36:39]
	v_mfma_f32_16x16x32_bf16 v[32:35], v[224:227], v[192:195], v[32:35]
	v_mfma_f32_16x16x32_bf16 v[124:127], v[204:207], v[172:175], v[124:127]
	v_mfma_f32_16x16x32_bf16 v[120:123], v[204:207], v[180:183], v[120:123]
	v_mfma_f32_16x16x32_bf16 v[116:119], v[212:215], v[172:175], v[116:119]
	v_mfma_f32_16x16x32_bf16 v[112:115], v[212:215], v[180:183], v[112:115]
	v_mfma_f32_16x16x32_bf16 v[108:111], v[220:223], v[172:175], v[108:111]
	v_mfma_f32_16x16x32_bf16 v[104:107], v[220:223], v[180:183], v[104:107]
	v_mfma_f32_16x16x32_bf16 v[100:103], v[228:231], v[172:175], v[100:103]
	v_mfma_f32_16x16x32_bf16 v[96:99], v[228:231], v[180:183], v[96:99]
	v_mfma_f32_16x16x32_bf16 v[88:91], v[204:207], v[188:191], v[88:91]
	v_mfma_f32_16x16x32_bf16 v[72:75], v[204:207], v[196:199], v[72:75]
	v_mfma_f32_16x16x32_bf16 v[56:59], v[212:215], v[188:191], v[56:59]
	v_mfma_f32_16x16x32_bf16 v[48:51], v[212:215], v[196:199], v[48:51]
	v_mfma_f32_16x16x32_bf16 v[44:47], v[220:223], v[188:191], v[44:47]
	v_mfma_f32_16x16x32_bf16 v[40:43], v[220:223], v[196:199], v[40:43]
	v_mfma_f32_16x16x32_bf16 v[36:39], v[228:231], v[188:191], v[36:39]
	v_mfma_f32_16x16x32_bf16 v[32:35], v[228:231], v[196:199], v[32:35]
	s_barrier
	s_setprio 0
	s_add_u32 s65, s32, 0x10000
	s_mov_b32 m0, s65
	ds_read_b128 v[200:203], v148 offset:16384
	ds_read_b128 v[204:207], v148 offset:17408
	ds_read_b128 v[208:211], v148 offset:18432
	ds_read_b128 v[212:215], v148 offset:19456
	ds_read_b128 v[216:219], v148 offset:20480
	ds_read_b128 v[220:223], v148 offset:21504
	ds_read_b128 v[224:227], v148 offset:22528
	ds_read_b128 v[228:231], v148 offset:23552
	s_add_u32 s92, s10, s40
	s_addc_u32 s93, s11, s41
	global_load_lds_dwordx4 v138, s[92:93]
	s_add_u32 s65, s32, 0x12000
	s_mov_b32 m0, s65
	s_add_u32 s65, s32, 0x14000
	s_add_u32 s96, s10, s40
	s_addc_u32 s97, s11, s41
	global_load_lds_dwordx4 v140, s[96:97]
	s_mov_b32 m0, s65
	s_add_u32 s65, s32, 0x16000
	s_add_u32 s88, s10, s42
	s_addc_u32 s89, s11, s43
	global_load_lds_dwordx4 v138, s[88:89]
	s_mov_b32 m0, s65
	s_mov_b32 s65, s32
	s_add_u32 s90, s10, s42
	s_addc_u32 s91, s11, s43
	global_load_lds_dwordx4 v140, s[90:91]
	s_mov_b32 m0, s65
	s_add_u32 s65, s32, 0x2000
	s_add_u32 s92, s10, s44
	s_addc_u32 s93, s11, s45
	global_load_lds_dwordx4 v142, s[92:93]
	s_mov_b32 m0, s65
	s_nop 0
	s_add_u32 s96, s10, s44
	s_addc_u32 s97, s11, s45
	global_load_lds_dwordx4 v144, s[96:97]
	s_waitcnt vmcnt(8)
	s_waitcnt lgkmcnt(0)
	s_setprio 1
	s_barrier
; #define STAGE(Pp, BASE, br, kt) do { const u16* _g = (BASE) + ((long)(br) * K + (long)(kt) * BK); \
;     __builtin_amdgcn_global_load_lds((const unsigned*)(_g + voff0), (unsigned*)((char*)(Pp) + tb16), 16, 0, 0); \
;     __builtin_amdgcn_global_load_lds((const unsigned*)(_g + voff1), (unsigned*)((char*)(Pp) + tb16 + 8192), 16, 0, 0); } while (0)
; #define LDA(dst, b, h) _Pragma("unroll") for (int m = 0; m < 4; ++m) _Pragma("unroll") for (int k = 0; k < 2; ++k) \
;     dst[m][k] = *reinterpret_cast<const bf16x8*>((const char*)shm + aB + (((b) * 2 + (h)) * 16384 + (m * 2 + k) * 1024))
; #define LDB(dst, b, h) _Pragma("unroll") for (int n = 0; n < 2; ++n) _Pragma("unroll") for (int k = 0; k < 2; ++k) \
;     dst[n][k] = *reinterpret_cast<const bf16x8*>((const char*)shm + bB + (((b) * 2 + (h)) * 16384 + (n * 2 + k) * 1024))
; #define WAIT_V(n) asm volatile("s_waitcnt vmcnt(" #n ")" ::: "memory")
; #define WAIT_L(n) asm volatile("s_waitcnt lgkmcnt(" #n ")" ::: "memory")
; #define BAR __builtin_amdgcn_s_barrier()
; #define SCHED __builtin_amdgcn_sched_barrier(0)
; template <int MODE> ...
;     ...
;       WAIT_V(6); WAIT_L(0); BAR; MMA2(1, 0, 1, 1); BAR; SCHED;
;       LDB(B0, 1, 0); LDB(B1, 1, 1); LDA(At, 1, 0); STAGE(SA(0, 1), A, brow + HALF, t + 2);
;       WAIT_L(0); BAR; MMA2(0, 0, 0, 1); BAR; SCHED;
	v_mfma_f32_16x16x32_bf16 v[28:31], v[200:203], v[168:171], v[28:31]
	v_mfma_f32_16x16x32_bf16 v[24:27], v[200:203], v[176:179], v[24:27]
	v_mfma_f32_16x16x32_bf16 v[20:23], v[208:211], v[168:171], v[20:23]
	v_mfma_f32_16x16x32_bf16 v[16:19], v[208:211], v[176:179], v[16:19]
	v_mfma_f32_16x16x32_bf16 v[12:15], v[216:219], v[168:171], v[12:15]
	v_mfma_f32_16x16x32_bf16 v[8:11], v[216:219], v[176:179], v[8:11]
	v_mfma_f32_16x16x32_bf16 v[4:7], v[224:227], v[168:171], v[4:7]
	v_mfma_f32_16x16x32_bf16 v[0:3], v[224:227], v[176:179], v[0:3]
	v_mfma_f32_16x16x32_bf16 v[52:55], v[200:203], v[184:187], v[52:55]
	v_mfma_f32_16x16x32_bf16 v[60:63], v[200:203], v[192:195], v[60:63]
	v_mfma_f32_16x16x32_bf16 v[64:67], v[208:211], v[184:187], v[64:67]
	v_mfma_f32_16x16x32_bf16 v[68:71], v[208:211], v[192:195], v[68:71]
	v_mfma_f32_16x16x32_bf16 v[76:79], v[216:219], v[184:187], v[76:79]
	v_mfma_f32_16x16x32_bf16 v[80:83], v[216:219], v[192:195], v[80:83]
	v_mfma_f32_16x16x32_bf16 v[84:87], v[224:227], v[184:187], v[84:87]
	v_mfma_f32_16x16x32_bf16 v[92:95], v[224:227], v[192:195], v[92:95]
	v_mfma_f32_16x16x32_bf16 v[28:31], v[204:207], v[172:175], v[28:31]
	v_mfma_f32_16x16x32_bf16 v[24:27], v[204:207], v[180:183], v[24:27]
	v_mfma_f32_16x16x32_bf16 v[20:23], v[212:215], v[172:175], v[20:23]
	v_mfma_f32_16x16x32_bf16 v[16:19], v[212:215], v[180:183], v[16:19]
	v_mfma_f32_16x16x32_bf16 v[12:15], v[220:223], v[172:175], v[12:15]
	v_mfma_f32_16x16x32_bf16 v[8:11], v[220:223], v[180:183], v[8:11]
	v_mfma_f32_16x16x32_bf16 v[4:7], v[228:231], v[172:175], v[4:7]
	v_mfma_f32_16x16x32_bf16 v[0:3], v[228:231], v[180:183], v[0:3]
	v_mfma_f32_16x16x32_bf16 v[52:55], v[204:207], v[188:191], v[52:55]
	v_mfma_f32_16x16x32_bf16 v[60:63], v[204:207], v[196:199], v[60:63]
	v_mfma_f32_16x16x32_bf16 v[64:67], v[212:215], v[188:191], v[64:67]
	v_mfma_f32_16x16x32_bf16 v[68:71], v[212:215], v[196:199], v[68:71]
	v_mfma_f32_16x16x32_bf16 v[76:79], v[220:223], v[188:191], v[76:79]
	v_mfma_f32_16x16x32_bf16 v[80:83], v[220:223], v[196:199], v[80:83]
	v_mfma_f32_16x16x32_bf16 v[84:87], v[228:231], v[188:191], v[84:87]
	v_mfma_f32_16x16x32_bf16 v[92:95], v[228:231], v[196:199], v[92:95]
	s_barrier
	s_setprio 0
	s_add_u32 s65, s32, 0x4000
	s_mov_b32 m0, s65
	s_add_u32 s65, s32, 0x6000
	ds_read_b128 v[168:171], v149 offset:32768
	ds_read_b128 v[172:175], v149 offset:33792
	ds_read_b128 v[176:179], v149 offset:34816
	ds_read_b128 v[180:183], v149 offset:35840
	ds_read_b128 v[184:187], v149 offset:49152
	ds_read_b128 v[188:191], v149 offset:50176
	ds_read_b128 v[192:195], v149 offset:51200
	ds_read_b128 v[196:199], v149 offset:52224
	ds_read_b128 v[200:203], v148 offset:32768
	ds_read_b128 v[204:207], v148 offset:33792
	ds_read_b128 v[208:211], v148 offset:34816
	ds_read_b128 v[212:215], v148 offset:35840
	ds_read_b128 v[216:219], v148 offset:36864
	ds_read_b128 v[220:223], v148 offset:37888
	ds_read_b128 v[224:227], v148 offset:38912
	ds_read_b128 v[228:231], v148 offset:39936
	s_add_u32 s88, s10, s48
	s_addc_u32 s89, s11, s49
	global_load_lds_dwordx4 v142, s[88:89]
	s_mov_b32 m0, s65
	s_nop 0
	s_add_u32 s90, s10, s48
	s_addc_u32 s91, s11, s49
	global_load_lds_dwordx4 v144, s[90:91]
	s_waitcnt vmcnt(8)
	s_waitcnt lgkmcnt(0)
	s_setprio 1
	s_barrier
	v_mfma_f32_16x16x32_bf16 v[124:127], v[200:203], v[168:171], v[124:127]
	v_mfma_f32_16x16x32_bf16 v[120:123], v[200:203], v[176:179], v[120:123]
	v_mfma_f32_16x16x32_bf16 v[116:119], v[208:211], v[168:171], v[116:119]
	v_mfma_f32_16x16x32_bf16 v[112:115], v[208:211], v[176:179], v[112:115]
	v_mfma_f32_16x16x32_bf16 v[108:111], v[216:219], v[168:171], v[108:111]
	v_mfma_f32_16x16x32_bf16 v[104:107], v[216:219], v[176:179], v[104:107]
	v_mfma_f32_16x16x32_bf16 v[100:103], v[224:227], v[168:171], v[100:103]
	v_mfma_f32_16x16x32_bf16 v[96:99], v[224:227], v[176:179], v[96:99]
	v_mfma_f32_16x16x32_bf16 v[88:91], v[200:203], v[184:187], v[88:91]
	v_mfma_f32_16x16x32_bf16 v[72:75], v[200:203], v[192:195], v[72:75]
	v_mfma_f32_16x16x32_bf16 v[56:59], v[208:211], v[184:187], v[56:59]
	v_mfma_f32_16x16x32_bf16 v[48:51], v[208:211], v[192:195], v[48:51]
	v_mfma_f32_16x16x32_bf16 v[44:47], v[216:219], v[184:187], v[44:47]
	v_mfma_f32_16x16x32_bf16 v[40:43], v[216:219], v[192:195], v[40:43]
	v_mfma_f32_16x16x32_bf16 v[36:39], v[224:227], v[184:187], v[36:39]
	v_mfma_f32_16x16x32_bf16 v[32:35], v[224:227], v[192:195], v[32:35]
	v_mfma_f32_16x16x32_bf16 v[124:127], v[204:207], v[172:175], v[124:127]
	v_mfma_f32_16x16x32_bf16 v[120:123], v[204:207], v[180:183], v[120:123]
	v_mfma_f32_16x16x32_bf16 v[116:119], v[212:215], v[172:175], v[116:119]
	v_mfma_f32_16x16x32_bf16 v[112:115], v[212:215], v[180:183], v[112:115]
	v_mfma_f32_16x16x32_bf16 v[108:111], v[220:223], v[172:175], v[108:111]
	v_mfma_f32_16x16x32_bf16 v[104:107], v[220:223], v[180:183], v[104:107]
	v_mfma_f32_16x16x32_bf16 v[100:103], v[228:231], v[172:175], v[100:103]
	v_mfma_f32_16x16x32_bf16 v[96:99], v[228:231], v[180:183], v[96:99]
	v_mfma_f32_16x16x32_bf16 v[88:91], v[204:207], v[188:191], v[88:91]
	v_mfma_f32_16x16x32_bf16 v[72:75], v[204:207], v[196:199], v[72:75]
	v_mfma_f32_16x16x32_bf16 v[56:59], v[212:215], v[188:191], v[56:59]
	v_mfma_f32_16x16x32_bf16 v[48:51], v[212:215], v[196:199], v[48:51]
	v_mfma_f32_16x16x32_bf16 v[44:47], v[220:223], v[188:191], v[44:47]
	v_mfma_f32_16x16x32_bf16 v[40:43], v[220:223], v[196:199], v[40:43]
	v_mfma_f32_16x16x32_bf16 v[36:39], v[228:231], v[188:191], v[36:39]
	v_mfma_f32_16x16x32_bf16 v[32:35], v[228:231], v[196:199], v[32:35]
	s_barrier
; #define STAGE(Pp, BASE, br, kt) do { const u16* _g = (BASE) + ((long)(br) * K + (long)(kt) * BK); \
;     __builtin_amdgcn_global_load_lds((const unsigned*)(_g + voff0), (unsigned*)((char*)(Pp) + tb16), 16, 0, 0); \
;     __builtin_amdgcn_global_load_lds((const unsigned*)(_g + voff1), (unsigned*)((char*)(Pp) + tb16 + 8192), 16, 0, 0); } while (0)
; #define LDA(dst, b, h) _Pragma("unroll") for (int m = 0; m < 4; ++m) _Pragma("unroll") for (int k = 0; k < 2; ++k) \
;     dst[m][k] = *reinterpret_cast<const bf16x8*>((const char*)shm + aB + (((b) * 2 + (h)) * 16384 + (m * 2 + k) * 1024))
; #define LDB(dst, b, h) _Pragma("unroll") for (int n = 0; n < 2; ++n) _Pragma("unroll") for (int k = 0; k < 2; ++k) \
;     dst[n][k] = *reinterpret_cast<const bf16x8*>((const char*)shm + bB + (((b) * 2 + (h)) * 16384 + (n * 2 + k) * 1024))
; #define WAIT_V(n) asm volatile("s_waitcnt vmcnt(" #n ")" ::: "memory")
; #define WAIT_L(n) asm volatile("s_waitcnt lgkmcnt(" #n ")" ::: "memory")
; #define BAR __builtin_amdgcn_s_barrier()
; #define SCHED __builtin_amdgcn_sched_barrier(0)
; template <int MODE> ...
;     ...
;       LDA(At, 1, 1); STAGE(SB(1, 0), Bt, bcol, t + 3); STAGE(SB(1, 1), Bt, bcol + HALF, t + 3); STAGE(SA(1, 0), A, brow, t + 3);
;       WAIT_V(6); WAIT_L(0); BAR; MMA2(1, 0, 1, 1); BAR; SCHED;
;     }
;     {
;       LDB(B0, 0, 0); LDB(B1, 0, 1); LDA(At, 0, 0); STAGE(SA(1, 1), A, brow + HALF, nt - 1);
;       WAIT_L(0); BAR; MMA2(0, 0, 0, 1); BAR; SCHED;
	s_setprio 0
	s_add_u32 s65, s32, 0x18000
	s_mov_b32 m0, s65
	s_add_u32 s65, s32, 0x1a000
	ds_read_b128 v[200:203], v148 offset:49152
	ds_read_b128 v[204:207], v148 offset:50176
	ds_read_b128 v[208:211], v148 offset:51200
	ds_read_b128 v[212:215], v148 offset:52224
	ds_read_b128 v[216:219], v148 offset:53248
	ds_read_b128 v[220:223], v148 offset:54272
	ds_read_b128 v[224:227], v148 offset:55296
	ds_read_b128 v[228:231], v148 offset:56320
	s_add_u32 s92, s10, s50
	s_addc_u32 s93, s11, s51
	global_load_lds_dwordx4 v138, s[92:93]
	s_mov_b32 m0, s65
	s_add_u32 s65, s32, 0x1c000
	s_add_u32 s96, s10, s50
	s_addc_u32 s97, s11, s51
	global_load_lds_dwordx4 v140, s[96:97]
	s_mov_b32 m0, s65
	s_add_u32 s65, s32, 0x1e000
	s_add_u32 s88, s10, s60
	s_addc_u32 s89, s11, s61
	global_load_lds_dwordx4 v138, s[88:89]
	s_mov_b32 m0, s65
	s_add_u32 s65, s32, 0x8000
	s_add_u32 s90, s10, s60
	s_addc_u32 s91, s11, s61
	global_load_lds_dwordx4 v140, s[90:91]
	s_mov_b32 m0, s65
	s_add_u32 s65, s32, 0xa000
	s_add_u32 s92, s10, s62
	s_addc_u32 s93, s11, s63
	global_load_lds_dwordx4 v142, s[92:93]
	s_mov_b32 m0, s65
	s_nop 0
	s_add_u32 s96, s10, s62
	s_addc_u32 s97, s11, s63
	global_load_lds_dwordx4 v144, s[96:97]
	s_waitcnt vmcnt(8)
	s_waitcnt lgkmcnt(0)
	s_setprio 1
	s_barrier
	v_mfma_f32_16x16x32_bf16 v[28:31], v[200:203], v[168:171], v[28:31]
	v_mfma_f32_16x16x32_bf16 v[24:27], v[200:203], v[176:179], v[24:27]
	v_mfma_f32_16x16x32_bf16 v[20:23], v[208:211], v[168:171], v[20:23]
	v_mfma_f32_16x16x32_bf16 v[16:19], v[208:211], v[176:179], v[16:19]
	v_mfma_f32_16x16x32_bf16 v[12:15], v[216:219], v[168:171], v[12:15]
	v_mfma_f32_16x16x32_bf16 v[8:11], v[216:219], v[176:179], v[8:11]
	v_mfma_f32_16x16x32_bf16 v[4:7], v[224:227], v[168:171], v[4:7]
	v_mfma_f32_16x16x32_bf16 v[0:3], v[224:227], v[176:179], v[0:3]
	v_mfma_f32_16x16x32_bf16 v[52:55], v[200:203], v[184:187], v[52:55]
	v_mfma_f32_16x16x32_bf16 v[60:63], v[200:203], v[192:195], v[60:63]
	v_mfma_f32_16x16x32_bf16 v[64:67], v[208:211], v[184:187], v[64:67]
	v_mfma_f32_16x16x32_bf16 v[68:71], v[208:211], v[192:195], v[68:71]
	v_mfma_f32_16x16x32_bf16 v[76:79], v[216:219], v[184:187], v[76:79]
	v_mfma_f32_16x16x32_bf16 v[80:83], v[216:219], v[192:195], v[80:83]
	v_mfma_f32_16x16x32_bf16 v[84:87], v[224:227], v[184:187], v[84:87]
	v_mfma_f32_16x16x32_bf16 v[92:95], v[224:227], v[192:195], v[92:95]
	v_mfma_f32_16x16x32_bf16 v[28:31], v[204:207], v[172:175], v[28:31]
	v_mfma_f32_16x16x32_bf16 v[24:27], v[204:207], v[180:183], v[24:27]
	v_mfma_f32_16x16x32_bf16 v[20:23], v[212:215], v[172:175], v[20:23]
	v_mfma_f32_16x16x32_bf16 v[16:19], v[212:215], v[180:183], v[16:19]
	v_mfma_f32_16x16x32_bf16 v[12:15], v[220:223], v[172:175], v[12:15]
	v_mfma_f32_16x16x32_bf16 v[8:11], v[220:223], v[180:183], v[8:11]
	v_mfma_f32_16x16x32_bf16 v[4:7], v[228:231], v[172:175], v[4:7]
	v_mfma_f32_16x16x32_bf16 v[0:3], v[228:231], v[180:183], v[0:3]
	v_mfma_f32_16x16x32_bf16 v[52:55], v[204:207], v[188:191], v[52:55]
	v_mfma_f32_16x16x32_bf16 v[60:63], v[204:207], v[196:199], v[60:63]
	v_mfma_f32_16x16x32_bf16 v[64:67], v[212:215], v[188:191], v[64:67]
	v_mfma_f32_16x16x32_bf16 v[68:71], v[212:215], v[196:199], v[68:71]
	v_mfma_f32_16x16x32_bf16 v[76:79], v[220:223], v[188:191], v[76:79]
	v_mfma_f32_16x16x32_bf16 v[80:83], v[220:223], v[196:199], v[80:83]
	v_mfma_f32_16x16x32_bf16 v[84:87], v[228:231], v[188:191], v[84:87]
	v_mfma_f32_16x16x32_bf16 v[92:95], v[228:231], v[196:199], v[92:95]
	s_barrier
	s_setprio 0
	s_add_i32 s35, s35, 2
	s_add_u32 s10, s10, 0x100
	s_addc_u32 s11, s11, 0
	s_cmp_lt_u32 s35, 60
	s_cbranch_scc1 .LBB0_591
	s_add_u32 s8, s8, 0x1f80
	v_readfirstlane_b32 s10, v165
	s_addc_u32 s9, s9, 0
	s_mov_b32 m0, s10
	v_readfirstlane_b32 s10, v166
	ds_read_b128 v[138:141], v149
	ds_read_b128 v[142:145], v149 offset:1024
	ds_read_b128 v[168:171], v149 offset:2048
	ds_read_b128 v[172:175], v149 offset:3072
	ds_read_b128 v[176:179], v149 offset:16384
	ds_read_b128 v[180:183], v149 offset:17408
	ds_read_b128 v[184:187], v149 offset:18432
	ds_read_b128 v[188:191], v149 offset:19456
	ds_read_b128 v[192:195], v148
	ds_read_b128 v[196:199], v148 offset:1024
	ds_read_b128 v[200:203], v148 offset:2048
	ds_read_b128 v[204:207], v148 offset:3072
	ds_read_b128 v[208:211], v148 offset:4096
	ds_read_b128 v[212:215], v148 offset:5120
	ds_read_b128 v[216:219], v148 offset:6144
	ds_read_b128 v[220:223], v148 offset:7168
	global_load_lds_dwordx4 v134, s[8:9]
	s_mov_b32 m0, s10
	s_nop 0
	global_load_lds_dwordx4 v136, s[8:9]
	s_waitcnt vmcnt(8)
	s_waitcnt lgkmcnt(0)
	s_setprio 1
	s_barrier
; #define STAGE(Pp, BASE, br, kt) do { const u16* _g = (BASE) + ((long)(br) * K + (long)(kt) * BK); \
;     __builtin_amdgcn_global_load_lds((const unsigned*)(_g + voff0), (unsigned*)((char*)(Pp) + tb16), 16, 0, 0); \
;     __builtin_amdgcn_global_load_lds((const unsigned*)(_g + voff1), (unsigned*)((char*)(Pp) + tb16 + 8192), 16, 0, 0); } while (0)
; #define LDA(dst, b, h) _Pragma("unroll") for (int m = 0; m < 4; ++m) _Pragma("unroll") for (int k = 0; k < 2; ++k) \
;     dst[m][k] = *reinterpret_cast<const bf16x8*>((const char*)shm + aB + (((b) * 2 + (h)) * 16384 + (m * 2 + k) * 1024))
; #define LDB(dst, b, h) _Pragma("unroll") for (int n = 0; n < 2; ++n) _Pragma("unroll") for (int k = 0; k < 2; ++k) \
;     dst[n][k] = *reinterpret_cast<const bf16x8*>((const char*)shm + bB + (((b) * 2 + (h)) * 16384 + (n * 2 + k) * 1024))
; #define WAIT_V(n) asm volatile("s_waitcnt vmcnt(" #n ")" ::: "memory")
; #define WAIT_L(n) asm volatile("s_waitcnt lgkmcnt(" #n ")" ::: "memory")
; #define BAR __builtin_amdgcn_s_barrier()
; #define SCHED __builtin_amdgcn_sched_barrier(0)
; template <int MODE> ...
;     ...
;       LDB(B0, 0, 0); LDB(B1, 0, 1); LDA(At, 0, 0); STAGE(SA(1, 1), A, brow + HALF, nt - 1);
;       WAIT_L(0); BAR; MMA2(0, 0, 0, 1); BAR; SCHED;
;       LDA(At, 0, 1); WAIT_V(0); WAIT_L(0); BAR; MMA2(1, 0, 1, 1); BAR; SCHED;
	v_mfma_f32_16x16x32_bf16 v[124:127], v[192:195], v[138:141], v[124:127]
	v_mfma_f32_16x16x32_bf16 v[120:123], v[192:195], v[168:171], v[120:123]
	v_mfma_f32_16x16x32_bf16 v[116:119], v[200:203], v[138:141], v[116:119]
	v_mfma_f32_16x16x32_bf16 v[112:115], v[200:203], v[168:171], v[112:115]
	v_mfma_f32_16x16x32_bf16 v[108:111], v[208:211], v[138:141], v[108:111]
	v_mfma_f32_16x16x32_bf16 v[104:107], v[208:211], v[168:171], v[104:107]
	v_mfma_f32_16x16x32_bf16 v[96:99], v[216:219], v[168:171], v[96:99]
	v_mfma_f32_16x16x32_bf16 v[88:91], v[192:195], v[176:179], v[88:91]
	v_mfma_f32_16x16x32_bf16 v[72:75], v[192:195], v[184:187], v[72:75]
	v_mfma_f32_16x16x32_bf16 v[56:59], v[200:203], v[176:179], v[56:59]
	v_mfma_f32_16x16x32_bf16 v[48:51], v[200:203], v[184:187], v[48:51]
	v_mfma_f32_16x16x32_bf16 v[44:47], v[208:211], v[176:179], v[44:47]
	v_mfma_f32_16x16x32_bf16 v[40:43], v[208:211], v[184:187], v[40:43]
	v_mfma_f32_16x16x32_bf16 v[36:39], v[216:219], v[176:179], v[36:39]
	v_mfma_f32_16x16x32_bf16 v[32:35], v[216:219], v[184:187], v[32:35]
	v_mfma_f32_16x16x32_bf16 v[124:127], v[196:199], v[142:145], v[124:127]
	v_mfma_f32_16x16x32_bf16 v[120:123], v[196:199], v[172:175], v[120:123]
	v_mfma_f32_16x16x32_bf16 v[116:119], v[204:207], v[142:145], v[116:119]
	v_mfma_f32_16x16x32_bf16 v[112:115], v[204:207], v[172:175], v[112:115]
	v_mfma_f32_16x16x32_bf16 v[108:111], v[212:215], v[142:145], v[108:111]
	v_mfma_f32_16x16x32_bf16 v[104:107], v[212:215], v[172:175], v[104:107]
	v_mfma_f32_16x16x32_bf16 v[100:103], v[216:219], v[138:141], v[100:103]
	v_mfma_f32_16x16x32_bf16 v[96:99], v[220:223], v[172:175], v[96:99]
	v_mfma_f32_16x16x32_bf16 v[88:91], v[196:199], v[180:183], v[88:91]
	v_mfma_f32_16x16x32_bf16 v[72:75], v[196:199], v[188:191], v[72:75]
	v_mfma_f32_16x16x32_bf16 v[56:59], v[204:207], v[180:183], v[56:59]
	v_mfma_f32_16x16x32_bf16 v[48:51], v[204:207], v[188:191], v[48:51]
	v_mfma_f32_16x16x32_bf16 v[44:47], v[212:215], v[180:183], v[44:47]
	v_mfma_f32_16x16x32_bf16 v[40:43], v[212:215], v[188:191], v[40:43]
	v_mfma_f32_16x16x32_bf16 v[36:39], v[220:223], v[180:183], v[36:39]
	v_mfma_f32_16x16x32_bf16 v[32:35], v[220:223], v[188:191], v[32:35]
	v_mfma_f32_16x16x32_bf16 v[224:227], v[220:223], v[142:145], v[100:103]
	s_barrier
	s_setprio 0
	s_nop 0
	ds_read_b128 v[100:103], v148 offset:16384
	ds_read_b128 v[192:195], v148 offset:17408
	ds_read_b128 v[196:199], v148 offset:18432
	ds_read_b128 v[200:203], v148 offset:19456
	ds_read_b128 v[204:207], v148 offset:20480
	ds_read_b128 v[208:211], v148 offset:21504
	ds_read_b128 v[212:215], v148 offset:22528
	ds_read_b128 v[216:219], v148 offset:23552
	s_waitcnt vmcnt(0)
	s_waitcnt lgkmcnt(0)
	s_setprio 1
	s_barrier
	v_mfma_f32_16x16x32_bf16 v[28:31], v[100:103], v[138:141], v[28:31]
	v_mfma_f32_16x16x32_bf16 v[20:23], v[196:199], v[138:141], v[20:23]
	v_mfma_f32_16x16x32_bf16 v[12:15], v[204:207], v[138:141], v[12:15]
	v_mfma_f32_16x16x32_bf16 v[4:7], v[212:215], v[138:141], v[4:7]
	v_mfma_f32_16x16x32_bf16 v[0:3], v[212:215], v[168:171], v[0:3]
	v_mfma_f32_16x16x32_bf16 v[28:31], v[192:195], v[142:145], v[28:31]
	v_mfma_f32_16x16x32_bf16 v[20:23], v[200:203], v[142:145], v[20:23]
	v_mfma_f32_16x16x32_bf16 v[220:223], v[208:211], v[142:145], v[12:15]
	v_mfma_f32_16x16x32_bf16 v[138:141], v[216:219], v[142:145], v[4:7]
	v_mfma_f32_16x16x32_bf16 v[142:145], v[216:219], v[172:175], v[0:3]
	v_mfma_f32_16x16x32_bf16 v[0:3], v[100:103], v[176:179], v[52:55]
	v_mfma_f32_16x16x32_bf16 v[24:27], v[100:103], v[168:171], v[24:27]
	v_mfma_f32_16x16x32_bf16 v[16:19], v[196:199], v[168:171], v[16:19]
	v_mfma_f32_16x16x32_bf16 v[8:11], v[204:207], v[168:171], v[8:11]
	v_mfma_f32_16x16x32_bf16 v[168:171], v[192:195], v[180:183], v[0:3]
	v_mfma_f32_16x16x32_bf16 v[0:3], v[100:103], v[184:187], v[60:63]
	v_mfma_f32_16x16x32_bf16 v[24:27], v[192:195], v[172:175], v[24:27]
	v_mfma_f32_16x16x32_bf16 v[16:19], v[200:203], v[172:175], v[16:19]
	v_mfma_f32_16x16x32_bf16 v[228:231], v[208:211], v[172:175], v[8:11]
	v_mfma_f32_16x16x32_bf16 v[172:175], v[192:195], v[188:191], v[0:3]
	v_mfma_f32_16x16x32_bf16 v[0:3], v[196:199], v[176:179], v[64:67]
	v_mfma_f32_16x16x32_bf16 v[192:195], v[200:203], v[180:183], v[0:3]
	v_mfma_f32_16x16x32_bf16 v[0:3], v[196:199], v[184:187], v[68:71]
	v_mfma_f32_16x16x32_bf16 v[196:199], v[200:203], v[188:191], v[0:3]
	v_mfma_f32_16x16x32_bf16 v[0:3], v[204:207], v[176:179], v[76:79]
	v_mfma_f32_16x16x32_bf16 v[200:203], v[208:211], v[180:183], v[0:3]
	v_mfma_f32_16x16x32_bf16 v[0:3], v[204:207], v[184:187], v[80:83]
	v_mfma_f32_16x16x32_bf16 v[204:207], v[208:211], v[188:191], v[0:3]
	v_mfma_f32_16x16x32_bf16 v[0:3], v[212:215], v[176:179], v[84:87]
	v_mfma_f32_16x16x32_bf16 v[176:179], v[216:219], v[180:183], v[0:3]
	v_mfma_f32_16x16x32_bf16 v[0:3], v[212:215], v[184:187], v[92:95]
	v_mfma_f32_16x16x32_bf16 v[180:183], v[216:219], v[188:191], v[0:3]
	s_barrier
; #define LDA(dst, b, h) _Pragma("unroll") for (int m = 0; m < 4; ++m) _Pragma("unroll") for (int k = 0; k < 2; ++k) \
;     dst[m][k] = *reinterpret_cast<const bf16x8*>((const char*)shm + aB + (((b) * 2 + (h)) * 16384 + (m * 2 + k) * 1024))
; #define LDB(dst, b, h) _Pragma("unroll") for (int n = 0; n < 2; ++n) _Pragma("unroll") for (int k = 0; k < 2; ++k) \
;     dst[n][k] = *reinterpret_cast<const bf16x8*>((const char*)shm + bB + (((b) * 2 + (h)) * 16384 + (n * 2 + k) * 1024))
; #define WAIT_L(n) asm volatile("s_waitcnt lgkmcnt(" #n ")" ::: "memory")
; #define BAR __builtin_amdgcn_s_barrier()
; #define SCHED __builtin_amdgcn_sched_barrier(0)
; template <int MODE> ...
;     ...
;       LDB(B0, 1, 0); LDB(B1, 1, 1); LDA(At, 1, 0); WAIT_L(0); BAR; MMA2(0, 0, 0, 1); BAR; SCHED;
;       LDA(At, 1, 1); WAIT_L(0); BAR; MMA2(1, 0, 1, 1); BAR; SCHED;
;     }
;     ...
;     if (wr == 0) BAR;
	s_setprio 0
	ds_read_b128 v[64:67], v149 offset:32768
	ds_read_b128 v[184:187], v149 offset:33792
	ds_read_b128 v[188:191], v149 offset:34816
	ds_read_b128 v[208:211], v149 offset:35840
	ds_read_b128 v[212:215], v149 offset:49152
	ds_read_b128 v[216:219], v149 offset:50176
	ds_read_b128 v[232:235], v149 offset:51200
	ds_read_b128 v[236:239], v149 offset:52224
	ds_read_b128 v[8:11], v148 offset:32768
	ds_read_b128 v[52:55], v148 offset:33792
	ds_read_b128 v[60:63], v148 offset:34816
	ds_read_b128 v[68:71], v148 offset:35840
	ds_read_b128 v[76:79], v148 offset:36864
	ds_read_b128 v[80:83], v148 offset:37888
	ds_read_b128 v[240:243], v148 offset:38912
	ds_read_b128 v[244:247], v148 offset:39936
	s_waitcnt lgkmcnt(0)
	s_setprio 1
	s_barrier
	v_mfma_f32_16x16x32_bf16 v[12:15], v[60:63], v[64:67], v[116:119]
	v_mfma_f32_16x16x32_bf16 v[0:3], v[8:11], v[64:67], v[124:127]
	v_mfma_f32_16x16x32_bf16 v[124:127], v[68:71], v[184:187], v[12:15]
	v_mfma_f32_16x16x32_bf16 v[12:15], v[60:63], v[188:191], v[112:115]
	v_mfma_f32_16x16x32_bf16 v[116:119], v[68:71], v[208:211], v[12:15]
	v_mfma_f32_16x16x32_bf16 v[12:15], v[76:79], v[64:67], v[108:111]
	v_mfma_f32_16x16x32_bf16 v[108:111], v[80:83], v[184:187], v[12:15]
	v_mfma_f32_16x16x32_bf16 v[12:15], v[76:79], v[188:191], v[104:107]
	v_mfma_f32_16x16x32_bf16 v[100:103], v[80:83], v[208:211], v[12:15]
	v_mfma_f32_16x16x32_bf16 v[12:15], v[240:243], v[64:67], v[224:227]
	v_mfma_f32_16x16x32_bf16 v[92:95], v[244:247], v[184:187], v[12:15]
	v_mfma_f32_16x16x32_bf16 v[12:15], v[240:243], v[188:191], v[96:99]
	v_mfma_f32_16x16x32_bf16 v[4:7], v[52:55], v[184:187], v[0:3]
	v_mfma_f32_16x16x32_bf16 v[0:3], v[8:11], v[188:191], v[120:123]
	v_mfma_f32_16x16x32_bf16 v[84:87], v[244:247], v[208:211], v[12:15]
	v_mfma_f32_16x16x32_bf16 v[12:15], v[8:11], v[212:215], v[88:91]
	v_mfma_f32_16x16x32_bf16 v[8:11], v[8:11], v[232:235], v[72:75]
	v_mfma_f32_16x16x32_bf16 v[0:3], v[52:55], v[208:211], v[0:3]
	v_mfma_f32_16x16x32_bf16 v[12:15], v[52:55], v[216:219], v[12:15]
	v_mfma_f32_16x16x32_bf16 v[8:11], v[52:55], v[236:239], v[8:11]
	v_mfma_f32_16x16x32_bf16 v[52:55], v[60:63], v[212:215], v[56:59]
	v_mfma_f32_16x16x32_bf16 v[48:51], v[60:63], v[232:235], v[48:51]
	v_mfma_f32_16x16x32_bf16 v[44:47], v[76:79], v[212:215], v[44:47]
	v_mfma_f32_16x16x32_bf16 v[40:43], v[76:79], v[232:235], v[40:43]
	v_mfma_f32_16x16x32_bf16 v[36:39], v[240:243], v[212:215], v[36:39]
	v_mfma_f32_16x16x32_bf16 v[32:35], v[240:243], v[232:235], v[32:35]
	v_mfma_f32_16x16x32_bf16 v[120:123], v[68:71], v[216:219], v[52:55]
	v_mfma_f32_16x16x32_bf16 v[112:115], v[68:71], v[236:239], v[48:51]
	v_mfma_f32_16x16x32_bf16 v[104:107], v[80:83], v[216:219], v[44:47]
	v_mfma_f32_16x16x32_bf16 v[96:99], v[80:83], v[236:239], v[40:43]
	v_mfma_f32_16x16x32_bf16 v[88:91], v[244:247], v[216:219], v[36:39]
	v_mfma_f32_16x16x32_bf16 v[80:83], v[244:247], v[236:239], v[32:35]
	s_barrier
	s_setprio 0
	s_nop 0
	ds_read_b128 v[32:35], v148 offset:49152
	ds_read_b128 v[40:43], v148 offset:50176
	ds_read_b128 v[48:51], v148 offset:51200
	ds_read_b128 v[224:227], v148 offset:52224
	ds_read_b128 v[240:243], v148 offset:53248
	ds_read_b128 v[244:247], v148 offset:54272
	ds_read_b128 v[248:251], v148 offset:55296
	ds_read_b128 v[130:133], v148 offset:56320
	s_waitcnt lgkmcnt(0)
	s_setprio 1
	s_barrier
	v_mfma_f32_16x16x32_bf16 v[24:27], v[32:35], v[188:191], v[24:27]
	v_mfma_f32_16x16x32_bf16 v[16:19], v[48:51], v[188:191], v[16:19]
	v_mfma_f32_16x16x32_bf16 v[68:71], v[40:43], v[208:211], v[24:27]
	v_mfma_f32_16x16x32_bf16 v[52:55], v[224:227], v[208:211], v[16:19]
	v_mfma_f32_16x16x32_bf16 v[16:19], v[240:243], v[64:67], v[220:223]
	v_mfma_f32_16x16x32_bf16 v[24:27], v[32:35], v[212:215], v[168:171]
	v_mfma_f32_16x16x32_bf16 v[44:47], v[244:247], v[184:187], v[16:19]
	v_mfma_f32_16x16x32_bf16 v[16:19], v[240:243], v[188:191], v[228:231]
	v_mfma_f32_16x16x32_bf16 v[72:75], v[40:43], v[216:219], v[24:27]
	v_mfma_f32_16x16x32_bf16 v[24:27], v[32:35], v[232:235], v[172:175]
	v_mfma_f32_16x16x32_bf16 v[28:31], v[32:35], v[64:67], v[28:31]
	v_mfma_f32_16x16x32_bf16 v[20:23], v[48:51], v[64:67], v[20:23]
	v_mfma_f32_16x16x32_bf16 v[36:39], v[244:247], v[208:211], v[16:19]
	v_mfma_f32_16x16x32_bf16 v[16:19], v[248:251], v[64:67], v[138:141]
	v_mfma_f32_16x16x32_bf16 v[64:67], v[40:43], v[236:239], v[24:27]
	v_mfma_f32_16x16x32_bf16 v[24:27], v[48:51], v[212:215], v[192:195]
	v_mfma_f32_16x16x32_bf16 v[56:59], v[224:227], v[216:219], v[24:27]
	v_mfma_f32_16x16x32_bf16 v[24:27], v[48:51], v[232:235], v[196:199]
	v_mfma_f32_16x16x32_bf16 v[48:51], v[224:227], v[236:239], v[24:27]
	v_mfma_f32_16x16x32_bf16 v[24:27], v[240:243], v[212:215], v[200:203]
	v_mfma_f32_16x16x32_bf16 v[76:79], v[40:43], v[184:187], v[28:31]
	v_mfma_f32_16x16x32_bf16 v[40:43], v[244:247], v[216:219], v[24:27]
	v_mfma_f32_16x16x32_bf16 v[24:27], v[240:243], v[232:235], v[204:207]
	v_mfma_f32_16x16x32_bf16 v[32:35], v[244:247], v[236:239], v[24:27]
	v_mfma_f32_16x16x32_bf16 v[24:27], v[248:251], v[212:215], v[176:179]
	v_mfma_f32_16x16x32_bf16 v[60:63], v[224:227], v[184:187], v[20:23]
	v_mfma_f32_16x16x32_bf16 v[20:23], v[130:133], v[184:187], v[16:19]
	v_mfma_f32_16x16x32_bf16 v[16:19], v[248:251], v[188:191], v[142:145]
	v_mfma_f32_16x16x32_bf16 v[28:31], v[130:133], v[216:219], v[24:27]
	v_mfma_f32_16x16x32_bf16 v[24:27], v[248:251], v[232:235], v[180:183]
	v_mfma_f32_16x16x32_bf16 v[16:19], v[130:133], v[208:211], v[16:19]
	v_mfma_f32_16x16x32_bf16 v[24:27], v[130:133], v[236:239], v[24:27]
	s_barrier
	s_setprio 0
	s_and_saveexec_b64 s[8:9], s[6:7]
	s_cbranch_execz .LBB0_594
	s_barrier

; #define STAGE(Pp, BASE, br, kt) do { const u16* _g = (BASE) + ((long)(br) * K + (long)(kt) * BK); \
;     __builtin_amdgcn_global_load_lds((const unsigned*)(_g + voff0), (unsigned*)((char*)(Pp) + tb16), 16, 0, 0); \
;     __builtin_amdgcn_global_load_lds((const unsigned*)(_g + voff1), (unsigned*)((char*)(Pp) + tb16 + 8192), 16, 0, 0); } while (0)
; #define LDA(dst, b, h) _Pragma("unroll") for (int m = 0; m < 4; ++m) _Pragma("unroll") for (int k = 0; k < 2; ++k) \
;     dst[m][k] = *reinterpret_cast<const bf16x8*>((const char*)shm + aB + (((b) * 2 + (h)) * 16384 + (m * 2 + k) * 1024))
; #define LDB(dst, b, h) _Pragma("unroll") for (int n = 0; n < 2; ++n) _Pragma("unroll") for (int k = 0; k < 2; ++k) \
;     dst[n][k] = *reinterpret_cast<const bf16x8*>((const char*)shm + bB + (((b) * 2 + (h)) * 16384 + (n * 2 + k) * 1024))
; #define WAIT_V(n) asm volatile("s_waitcnt vmcnt(" #n ")" ::: "memory")
; #define WAIT_L(n) asm volatile("s_waitcnt lgkmcnt(" #n ")" ::: "memory")
; #define BAR __builtin_amdgcn_s_barrier()
; #define SCHED __builtin_amdgcn_sched_barrier(0)
; template <int MODE> ...
;     ...
;       LDB(B0, 0, 0); LDB(B1, 0, 1); LDA(At, 0, 0); STAGE(SA(1, 1), A, brow + HALF, t + 1);
;       WAIT_L(0); BAR; MMA2(0, 0, 0, 1); BAR; SCHED;
;       LDA(At, 0, 1); STAGE(SB(0, 0), Bt, bcol, t + 2); STAGE(SB(0, 1), Bt, bcol + HALF, t + 2); STAGE(SA(0, 0), A, brow, t + 2);
;       WAIT_V(6); WAIT_L(0); BAR; MMA2(1, 0, 1, 1); BAR; SCHED;
.LBB0_848:
	s_add_u32 s64, s32, 0xc000
	s_mov_b32 m0, s64
	ds_read_b128 v[170:173], v151
	ds_read_b128 v[174:177], v151 offset:1024
	ds_read_b128 v[178:181], v151 offset:2048
	ds_read_b128 v[182:185], v151 offset:3072
	ds_read_b128 v[186:189], v151 offset:16384
	ds_read_b128 v[190:193], v151 offset:17408
	ds_read_b128 v[194:197], v151 offset:18432
	ds_read_b128 v[198:201], v151 offset:19456
	ds_read_b128 v[202:205], v150
	ds_read_b128 v[206:209], v150 offset:1024
	ds_read_b128 v[210:213], v150 offset:2048
	ds_read_b128 v[214:217], v150 offset:3072
	ds_read_b128 v[218:221], v150 offset:4096
	ds_read_b128 v[222:225], v150 offset:5120
	ds_read_b128 v[226:229], v150 offset:6144
	ds_read_b128 v[230:233], v150 offset:7168
	s_add_u32 s88, s62, s22
	s_addc_u32 s89, s63, s23
	global_load_lds_dwordx4 v146, s[88:89]
	s_add_u32 s64, s32, 0xe000
	s_mov_b32 m0, s64
	s_nop 0
	s_add_u32 s90, s62, s22
	s_addc_u32 s91, s63, s23
	global_load_lds_dwordx4 v148, s[90:91]
	s_waitcnt vmcnt(8)
	s_waitcnt lgkmcnt(0)
	s_setprio 1
	s_barrier
	v_mfma_f32_16x16x32_bf16 v[124:127], v[202:205], v[170:173], v[124:127]
	v_mfma_f32_16x16x32_bf16 v[120:123], v[202:205], v[178:181], v[120:123]
	v_mfma_f32_16x16x32_bf16 v[116:119], v[210:213], v[170:173], v[116:119]
	v_mfma_f32_16x16x32_bf16 v[112:115], v[210:213], v[178:181], v[112:115]
	v_mfma_f32_16x16x32_bf16 v[108:111], v[218:221], v[170:173], v[108:111]
	v_mfma_f32_16x16x32_bf16 v[104:107], v[218:221], v[178:181], v[104:107]
	v_mfma_f32_16x16x32_bf16 v[100:103], v[226:229], v[170:173], v[100:103]
	v_mfma_f32_16x16x32_bf16 v[96:99], v[226:229], v[178:181], v[96:99]
	v_mfma_f32_16x16x32_bf16 v[92:95], v[202:205], v[186:189], v[92:95]
	v_mfma_f32_16x16x32_bf16 v[88:91], v[202:205], v[194:197], v[88:91]
	v_mfma_f32_16x16x32_bf16 v[84:87], v[210:213], v[186:189], v[84:87]
	v_mfma_f32_16x16x32_bf16 v[80:83], v[210:213], v[194:197], v[80:83]
	v_mfma_f32_16x16x32_bf16 v[76:79], v[218:221], v[186:189], v[76:79]
	v_mfma_f32_16x16x32_bf16 v[72:75], v[218:221], v[194:197], v[72:75]
	v_mfma_f32_16x16x32_bf16 v[68:71], v[226:229], v[186:189], v[68:71]
	v_mfma_f32_16x16x32_bf16 v[64:67], v[226:229], v[194:197], v[64:67]
	v_mfma_f32_16x16x32_bf16 v[124:127], v[206:209], v[174:177], v[124:127]
	v_mfma_f32_16x16x32_bf16 v[120:123], v[206:209], v[182:185], v[120:123]
	v_mfma_f32_16x16x32_bf16 v[116:119], v[214:217], v[174:177], v[116:119]
	v_mfma_f32_16x16x32_bf16 v[112:115], v[214:217], v[182:185], v[112:115]
	v_mfma_f32_16x16x32_bf16 v[108:111], v[222:225], v[174:177], v[108:111]
	v_mfma_f32_16x16x32_bf16 v[104:107], v[222:225], v[182:185], v[104:107]
	v_mfma_f32_16x16x32_bf16 v[100:103], v[230:233], v[174:177], v[100:103]
	v_mfma_f32_16x16x32_bf16 v[96:99], v[230:233], v[182:185], v[96:99]
	v_mfma_f32_16x16x32_bf16 v[92:95], v[206:209], v[190:193], v[92:95]
	v_mfma_f32_16x16x32_bf16 v[88:91], v[206:209], v[198:201], v[88:91]
	v_mfma_f32_16x16x32_bf16 v[84:87], v[214:217], v[190:193], v[84:87]
	v_mfma_f32_16x16x32_bf16 v[80:83], v[214:217], v[198:201], v[80:83]
	v_mfma_f32_16x16x32_bf16 v[76:79], v[222:225], v[190:193], v[76:79]
	v_mfma_f32_16x16x32_bf16 v[72:75], v[222:225], v[198:201], v[72:75]
	v_mfma_f32_16x16x32_bf16 v[68:71], v[230:233], v[190:193], v[68:71]
	v_mfma_f32_16x16x32_bf16 v[64:67], v[230:233], v[198:201], v[64:67]
	s_barrier
	s_setprio 0
	s_add_u32 s64, s32, 0x10000
	s_mov_b32 m0, s64
	ds_read_b128 v[202:205], v150 offset:16384
	ds_read_b128 v[206:209], v150 offset:17408
	ds_read_b128 v[210:213], v150 offset:18432
	ds_read_b128 v[214:217], v150 offset:19456
	ds_read_b128 v[218:221], v150 offset:20480
	ds_read_b128 v[222:225], v150 offset:21504
	ds_read_b128 v[226:229], v150 offset:22528
	ds_read_b128 v[230:233], v150 offset:23552
	s_add_u32 s92, s62, s24
	s_addc_u32 s93, s63, s25
	global_load_lds_dwordx4 v138, s[92:93]
	s_add_u32 s64, s32, 0x12000
	s_mov_b32 m0, s64
	s_add_u32 s64, s32, 0x14000
	s_add_u32 s96, s62, s24
	s_addc_u32 s97, s63, s25
	global_load_lds_dwordx4 v140, s[96:97]
	s_mov_b32 m0, s64
	s_add_u32 s64, s32, 0x16000
	s_add_u32 s88, s62, s26
	s_addc_u32 s89, s63, s27
	global_load_lds_dwordx4 v142, s[88:89]
	s_mov_b32 m0, s64
	s_mov_b32 s64, s32
	s_add_u32 s90, s62, s26
	s_addc_u32 s91, s63, s27
	global_load_lds_dwordx4 v144, s[90:91]
	s_mov_b32 m0, s64
	s_add_u32 s64, s32, 0x2000
	s_add_u32 s92, s62, s28
	s_addc_u32 s93, s63, s29
	global_load_lds_dwordx4 v146, s[92:93]
	s_mov_b32 m0, s64
	s_nop 0
	s_add_u32 s96, s62, s28
	s_addc_u32 s97, s63, s29
	global_load_lds_dwordx4 v148, s[96:97]
	s_waitcnt vmcnt(8)
	s_waitcnt lgkmcnt(0)
	s_setprio 1
	s_barrier
; #define STAGE(Pp, BASE, br, kt) do { const u16* _g = (BASE) + ((long)(br) * K + (long)(kt) * BK); \
;     __builtin_amdgcn_global_load_lds((const unsigned*)(_g + voff0), (unsigned*)((char*)(Pp) + tb16), 16, 0, 0); \
;     __builtin_amdgcn_global_load_lds((const unsigned*)(_g + voff1), (unsigned*)((char*)(Pp) + tb16 + 8192), 16, 0, 0); } while (0)
; #define LDA(dst, b, h) _Pragma("unroll") for (int m = 0; m < 4; ++m) _Pragma("unroll") for (int k = 0; k < 2; ++k) \
;     dst[m][k] = *reinterpret_cast<const bf16x8*>((const char*)shm + aB + (((b) * 2 + (h)) * 16384 + (m * 2 + k) * 1024))
; #define LDB(dst, b, h) _Pragma("unroll") for (int n = 0; n < 2; ++n) _Pragma("unroll") for (int k = 0; k < 2; ++k) \
;     dst[n][k] = *reinterpret_cast<const bf16x8*>((const char*)shm + bB + (((b) * 2 + (h)) * 16384 + (n * 2 + k) * 1024))
; #define WAIT_V(n) asm volatile("s_waitcnt vmcnt(" #n ")" ::: "memory")
; #define WAIT_L(n) asm volatile("s_waitcnt lgkmcnt(" #n ")" ::: "memory")
; #define BAR __builtin_amdgcn_s_barrier()
; #define SCHED __builtin_amdgcn_sched_barrier(0)
; template <int MODE> ...
;     ...
;       WAIT_V(6); WAIT_L(0); BAR; MMA2(1, 0, 1, 1); BAR; SCHED;
;       LDB(B0, 1, 0); LDB(B1, 1, 1); LDA(At, 1, 0); STAGE(SA(0, 1), A, brow + HALF, t + 2);
;       WAIT_L(0); BAR; MMA2(0, 0, 0, 1); BAR; SCHED;
	v_mfma_f32_16x16x32_bf16 v[60:63], v[202:205], v[170:173], v[60:63]
	v_mfma_f32_16x16x32_bf16 v[56:59], v[202:205], v[178:181], v[56:59]
	v_mfma_f32_16x16x32_bf16 v[52:55], v[210:213], v[170:173], v[52:55]
	v_mfma_f32_16x16x32_bf16 v[48:51], v[210:213], v[178:181], v[48:51]
	v_mfma_f32_16x16x32_bf16 v[44:47], v[218:221], v[170:173], v[44:47]
	v_mfma_f32_16x16x32_bf16 v[40:43], v[218:221], v[178:181], v[40:43]
	v_mfma_f32_16x16x32_bf16 v[36:39], v[226:229], v[170:173], v[36:39]
	v_mfma_f32_16x16x32_bf16 v[32:35], v[226:229], v[178:181], v[32:35]
	v_mfma_f32_16x16x32_bf16 v[28:31], v[202:205], v[186:189], v[28:31]
	v_mfma_f32_16x16x32_bf16 v[24:27], v[202:205], v[194:197], v[24:27]
	v_mfma_f32_16x16x32_bf16 v[20:23], v[210:213], v[186:189], v[20:23]
	v_mfma_f32_16x16x32_bf16 v[16:19], v[210:213], v[194:197], v[16:19]
	v_mfma_f32_16x16x32_bf16 v[12:15], v[218:221], v[186:189], v[12:15]
	v_mfma_f32_16x16x32_bf16 v[8:11], v[218:221], v[194:197], v[8:11]
	v_mfma_f32_16x16x32_bf16 v[4:7], v[226:229], v[186:189], v[4:7]
	v_mfma_f32_16x16x32_bf16 v[0:3], v[226:229], v[194:197], v[0:3]
	v_mfma_f32_16x16x32_bf16 v[60:63], v[206:209], v[174:177], v[60:63]
	v_mfma_f32_16x16x32_bf16 v[56:59], v[206:209], v[182:185], v[56:59]
	v_mfma_f32_16x16x32_bf16 v[52:55], v[214:217], v[174:177], v[52:55]
	v_mfma_f32_16x16x32_bf16 v[48:51], v[214:217], v[182:185], v[48:51]
	v_mfma_f32_16x16x32_bf16 v[44:47], v[222:225], v[174:177], v[44:47]
	v_mfma_f32_16x16x32_bf16 v[40:43], v[222:225], v[182:185], v[40:43]
	v_mfma_f32_16x16x32_bf16 v[36:39], v[230:233], v[174:177], v[36:39]
	v_mfma_f32_16x16x32_bf16 v[32:35], v[230:233], v[182:185], v[32:35]
	v_mfma_f32_16x16x32_bf16 v[28:31], v[206:209], v[190:193], v[28:31]
	v_mfma_f32_16x16x32_bf16 v[24:27], v[206:209], v[198:201], v[24:27]
	v_mfma_f32_16x16x32_bf16 v[20:23], v[214:217], v[190:193], v[20:23]
	v_mfma_f32_16x16x32_bf16 v[16:19], v[214:217], v[198:201], v[16:19]
	v_mfma_f32_16x16x32_bf16 v[12:15], v[222:225], v[190:193], v[12:15]
	v_mfma_f32_16x16x32_bf16 v[8:11], v[222:225], v[198:201], v[8:11]
	v_mfma_f32_16x16x32_bf16 v[4:7], v[230:233], v[190:193], v[4:7]
	v_mfma_f32_16x16x32_bf16 v[0:3], v[230:233], v[198:201], v[0:3]
	s_barrier
	s_setprio 0
	s_add_u32 s64, s32, 0x4000
	s_mov_b32 m0, s64
	s_add_u32 s64, s32, 0x6000
	ds_read_b128 v[170:173], v151 offset:32768
	ds_read_b128 v[174:177], v151 offset:33792
	ds_read_b128 v[178:181], v151 offset:34816
	ds_read_b128 v[182:185], v151 offset:35840
	ds_read_b128 v[186:189], v151 offset:49152
	ds_read_b128 v[190:193], v151 offset:50176
	ds_read_b128 v[194:197], v151 offset:51200
	ds_read_b128 v[198:201], v151 offset:52224
	ds_read_b128 v[202:205], v150 offset:32768
	ds_read_b128 v[206:209], v150 offset:33792
	ds_read_b128 v[210:213], v150 offset:34816
	ds_read_b128 v[214:217], v150 offset:35840
	ds_read_b128 v[218:221], v150 offset:36864
	ds_read_b128 v[222:225], v150 offset:37888
	ds_read_b128 v[226:229], v150 offset:38912
	ds_read_b128 v[230:233], v150 offset:39936
	s_add_u32 s88, s62, s36
	s_addc_u32 s89, s63, s37
	global_load_lds_dwordx4 v146, s[88:89]
	s_mov_b32 m0, s64
	s_nop 0
	s_add_u32 s90, s62, s36
	s_addc_u32 s91, s63, s37
	global_load_lds_dwordx4 v148, s[90:91]
	s_waitcnt vmcnt(8)
	s_waitcnt lgkmcnt(0)
	s_setprio 1
	s_barrier
	v_mfma_f32_16x16x32_bf16 v[124:127], v[202:205], v[170:173], v[124:127]
	v_mfma_f32_16x16x32_bf16 v[120:123], v[202:205], v[178:181], v[120:123]
	v_mfma_f32_16x16x32_bf16 v[116:119], v[210:213], v[170:173], v[116:119]
	v_mfma_f32_16x16x32_bf16 v[112:115], v[210:213], v[178:181], v[112:115]
	v_mfma_f32_16x16x32_bf16 v[108:111], v[218:221], v[170:173], v[108:111]
	v_mfma_f32_16x16x32_bf16 v[104:107], v[218:221], v[178:181], v[104:107]
	v_mfma_f32_16x16x32_bf16 v[100:103], v[226:229], v[170:173], v[100:103]
	v_mfma_f32_16x16x32_bf16 v[96:99], v[226:229], v[178:181], v[96:99]
	v_mfma_f32_16x16x32_bf16 v[92:95], v[202:205], v[186:189], v[92:95]
	v_mfma_f32_16x16x32_bf16 v[88:91], v[202:205], v[194:197], v[88:91]
	v_mfma_f32_16x16x32_bf16 v[84:87], v[210:213], v[186:189], v[84:87]
	v_mfma_f32_16x16x32_bf16 v[80:83], v[210:213], v[194:197], v[80:83]
	v_mfma_f32_16x16x32_bf16 v[76:79], v[218:221], v[186:189], v[76:79]
	v_mfma_f32_16x16x32_bf16 v[72:75], v[218:221], v[194:197], v[72:75]
	v_mfma_f32_16x16x32_bf16 v[68:71], v[226:229], v[186:189], v[68:71]
	v_mfma_f32_16x16x32_bf16 v[64:67], v[226:229], v[194:197], v[64:67]
	v_mfma_f32_16x16x32_bf16 v[124:127], v[206:209], v[174:177], v[124:127]
	v_mfma_f32_16x16x32_bf16 v[120:123], v[206:209], v[182:185], v[120:123]
	v_mfma_f32_16x16x32_bf16 v[116:119], v[214:217], v[174:177], v[116:119]
	v_mfma_f32_16x16x32_bf16 v[112:115], v[214:217], v[182:185], v[112:115]
	v_mfma_f32_16x16x32_bf16 v[108:111], v[222:225], v[174:177], v[108:111]
	v_mfma_f32_16x16x32_bf16 v[104:107], v[222:225], v[182:185], v[104:107]
	v_mfma_f32_16x16x32_bf16 v[100:103], v[230:233], v[174:177], v[100:103]
	v_mfma_f32_16x16x32_bf16 v[96:99], v[230:233], v[182:185], v[96:99]
	v_mfma_f32_16x16x32_bf16 v[92:95], v[206:209], v[190:193], v[92:95]
	v_mfma_f32_16x16x32_bf16 v[88:91], v[206:209], v[198:201], v[88:91]
	v_mfma_f32_16x16x32_bf16 v[84:87], v[214:217], v[190:193], v[84:87]
	v_mfma_f32_16x16x32_bf16 v[80:83], v[214:217], v[198:201], v[80:83]
	v_mfma_f32_16x16x32_bf16 v[76:79], v[222:225], v[190:193], v[76:79]
	v_mfma_f32_16x16x32_bf16 v[72:75], v[222:225], v[198:201], v[72:75]
	v_mfma_f32_16x16x32_bf16 v[68:71], v[230:233], v[190:193], v[68:71]
	v_mfma_f32_16x16x32_bf16 v[64:67], v[230:233], v[198:201], v[64:67]
	s_barrier
; #define STAGE(Pp, BASE, br, kt) do { const u16* _g = (BASE) + ((long)(br) * K + (long)(kt) * BK); \
;     __builtin_amdgcn_global_load_lds((const unsigned*)(_g + voff0), (unsigned*)((char*)(Pp) + tb16), 16, 0, 0); \
;     __builtin_amdgcn_global_load_lds((const unsigned*)(_g + voff1), (unsigned*)((char*)(Pp) + tb16 + 8192), 16, 0, 0); } while (0)
; #define LDA(dst, b, h) _Pragma("unroll") for (int m = 0; m < 4; ++m) _Pragma("unroll") for (int k = 0; k < 2; ++k) \
;     dst[m][k] = *reinterpret_cast<const bf16x8*>((const char*)shm + aB + (((b) * 2 + (h)) * 16384 + (m * 2 + k) * 1024))
; #define LDB(dst, b, h) _Pragma("unroll") for (int n = 0; n < 2; ++n) _Pragma("unroll") for (int k = 0; k < 2; ++k) \
;     dst[n][k] = *reinterpret_cast<const bf16x8*>((const char*)shm + bB + (((b) * 2 + (h)) * 16384 + (n * 2 + k) * 1024))
; #define WAIT_V(n) asm volatile("s_waitcnt vmcnt(" #n ")" ::: "memory")
; #define WAIT_L(n) asm volatile("s_waitcnt lgkmcnt(" #n ")" ::: "memory")
; #define BAR __builtin_amdgcn_s_barrier()
; #define SCHED __builtin_amdgcn_sched_barrier(0)
; template <int MODE> ...
;     ...
;       LDA(At, 1, 1); STAGE(SB(1, 0), Bt, bcol, t + 3); STAGE(SB(1, 1), Bt, bcol + HALF, t + 3); STAGE(SA(1, 0), A, brow, t + 3);
;       WAIT_V(6); WAIT_L(0); BAR; MMA2(1, 0, 1, 1); BAR; SCHED;
;     }
;     {
;       LDB(B0, 0, 0); LDB(B1, 0, 1); LDA(At, 0, 0); STAGE(SA(1, 1), A, brow + HALF, nt - 1);
;       WAIT_L(0); BAR; MMA2(0, 0, 0, 1); BAR; SCHED;
	s_setprio 0
	s_add_u32 s64, s32, 0x18000
	s_mov_b32 m0, s64
	s_add_u32 s64, s32, 0x1a000
	ds_read_b128 v[202:205], v150 offset:49152
	ds_read_b128 v[206:209], v150 offset:50176
	ds_read_b128 v[210:213], v150 offset:51200
	ds_read_b128 v[214:217], v150 offset:52224
	ds_read_b128 v[218:221], v150 offset:53248
	ds_read_b128 v[222:225], v150 offset:54272
	ds_read_b128 v[226:229], v150 offset:55296
	ds_read_b128 v[230:233], v150 offset:56320
	s_add_u32 s92, s62, s38
	s_addc_u32 s93, s63, s39
	global_load_lds_dwordx4 v138, s[92:93]
	s_mov_b32 m0, s64
	s_add_u32 s64, s32, 0x1c000
	s_add_u32 s96, s62, s38
	s_addc_u32 s97, s63, s39
	global_load_lds_dwordx4 v140, s[96:97]
	s_mov_b32 m0, s64
	s_add_u32 s64, s32, 0x1e000
	s_add_u32 s88, s62, s40
	s_addc_u32 s89, s63, s41
	global_load_lds_dwordx4 v142, s[88:89]
	s_mov_b32 m0, s64
	s_add_u32 s64, s32, 0x8000
	s_add_u32 s90, s62, s40
	s_addc_u32 s91, s63, s41
	global_load_lds_dwordx4 v144, s[90:91]
	s_mov_b32 m0, s64
	s_add_u32 s64, s32, 0xa000
	s_add_u32 s92, s62, s42
	s_addc_u32 s93, s63, s43
	global_load_lds_dwordx4 v146, s[92:93]
	s_mov_b32 m0, s64
	s_nop 0
	s_add_u32 s96, s62, s42
	s_addc_u32 s97, s63, s43
	global_load_lds_dwordx4 v148, s[96:97]
	s_waitcnt vmcnt(8)
	s_waitcnt lgkmcnt(0)
	s_setprio 1
	s_barrier
	v_mfma_f32_16x16x32_bf16 v[60:63], v[202:205], v[170:173], v[60:63]
	v_mfma_f32_16x16x32_bf16 v[56:59], v[202:205], v[178:181], v[56:59]
	v_mfma_f32_16x16x32_bf16 v[52:55], v[210:213], v[170:173], v[52:55]
	v_mfma_f32_16x16x32_bf16 v[48:51], v[210:213], v[178:181], v[48:51]
	v_mfma_f32_16x16x32_bf16 v[44:47], v[218:221], v[170:173], v[44:47]
	v_mfma_f32_16x16x32_bf16 v[40:43], v[218:221], v[178:181], v[40:43]
	v_mfma_f32_16x16x32_bf16 v[36:39], v[226:229], v[170:173], v[36:39]
	v_mfma_f32_16x16x32_bf16 v[32:35], v[226:229], v[178:181], v[32:35]
	v_mfma_f32_16x16x32_bf16 v[28:31], v[202:205], v[186:189], v[28:31]
	v_mfma_f32_16x16x32_bf16 v[24:27], v[202:205], v[194:197], v[24:27]
	v_mfma_f32_16x16x32_bf16 v[20:23], v[210:213], v[186:189], v[20:23]
	v_mfma_f32_16x16x32_bf16 v[16:19], v[210:213], v[194:197], v[16:19]
	v_mfma_f32_16x16x32_bf16 v[12:15], v[218:221], v[186:189], v[12:15]
	v_mfma_f32_16x16x32_bf16 v[8:11], v[218:221], v[194:197], v[8:11]
	v_mfma_f32_16x16x32_bf16 v[4:7], v[226:229], v[186:189], v[4:7]
	v_mfma_f32_16x16x32_bf16 v[0:3], v[226:229], v[194:197], v[0:3]
	v_mfma_f32_16x16x32_bf16 v[60:63], v[206:209], v[174:177], v[60:63]
	v_mfma_f32_16x16x32_bf16 v[56:59], v[206:209], v[182:185], v[56:59]
	v_mfma_f32_16x16x32_bf16 v[52:55], v[214:217], v[174:177], v[52:55]
	v_mfma_f32_16x16x32_bf16 v[48:51], v[214:217], v[182:185], v[48:51]
	v_mfma_f32_16x16x32_bf16 v[44:47], v[222:225], v[174:177], v[44:47]
	v_mfma_f32_16x16x32_bf16 v[40:43], v[222:225], v[182:185], v[40:43]
	v_mfma_f32_16x16x32_bf16 v[36:39], v[230:233], v[174:177], v[36:39]
	v_mfma_f32_16x16x32_bf16 v[32:35], v[230:233], v[182:185], v[32:35]
	v_mfma_f32_16x16x32_bf16 v[28:31], v[206:209], v[190:193], v[28:31]
	v_mfma_f32_16x16x32_bf16 v[24:27], v[206:209], v[198:201], v[24:27]
	v_mfma_f32_16x16x32_bf16 v[20:23], v[214:217], v[190:193], v[20:23]
	v_mfma_f32_16x16x32_bf16 v[16:19], v[214:217], v[198:201], v[16:19]
	v_mfma_f32_16x16x32_bf16 v[12:15], v[222:225], v[190:193], v[12:15]
	v_mfma_f32_16x16x32_bf16 v[8:11], v[222:225], v[198:201], v[8:11]
	v_mfma_f32_16x16x32_bf16 v[4:7], v[230:233], v[190:193], v[4:7]
	v_mfma_f32_16x16x32_bf16 v[0:3], v[230:233], v[198:201], v[0:3]
	s_barrier
	s_setprio 0
	s_add_i32 s45, s45, 2
	s_add_u32 s62, s62, 0x100
	s_addc_u32 s63, s63, 0
	s_cmpk_lt_u32 s45, 0xa8
	s_cbranch_scc1 .LBB0_848
	s_add_u32 s60, s60, 0x5580
	v_readfirstlane_b32 s45, v167
	s_addc_u32 s61, s61, 0
	s_mov_b32 m0, s45
	v_readfirstlane_b32 s45, v168
	ds_read_b128 v[138:141], v151
	ds_read_b128 v[142:145], v151 offset:1024
	ds_read_b128 v[146:149], v151 offset:2048
	ds_read_b128 v[170:173], v151 offset:3072
	ds_read_b128 v[174:177], v151 offset:16384
	ds_read_b128 v[178:181], v151 offset:17408
	ds_read_b128 v[182:185], v151 offset:18432
	ds_read_b128 v[186:189], v151 offset:19456
	ds_read_b128 v[190:193], v150
	ds_read_b128 v[194:197], v150 offset:1024
	ds_read_b128 v[198:201], v150 offset:2048
	ds_read_b128 v[202:205], v150 offset:3072
	ds_read_b128 v[206:209], v150 offset:4096
	ds_read_b128 v[210:213], v150 offset:5120
	ds_read_b128 v[214:217], v150 offset:6144
	ds_read_b128 v[218:221], v150 offset:7168
	global_load_lds_dwordx4 v134, s[60:61]
	s_mov_b32 m0, s45
	s_nop 0
	global_load_lds_dwordx4 v136, s[60:61]
	s_waitcnt vmcnt(8)
	s_waitcnt lgkmcnt(0)
	s_setprio 1
	s_barrier
; #define STAGE(Pp, BASE, br, kt) do { const u16* _g = (BASE) + ((long)(br) * K + (long)(kt) * BK); \
;     __builtin_amdgcn_global_load_lds((const unsigned*)(_g + voff0), (unsigned*)((char*)(Pp) + tb16), 16, 0, 0); \
;     __builtin_amdgcn_global_load_lds((const unsigned*)(_g + voff1), (unsigned*)((char*)(Pp) + tb16 + 8192), 16, 0, 0); } while (0)
; #define LDA(dst, b, h) _Pragma("unroll") for (int m = 0; m < 4; ++m) _Pragma("unroll") for (int k = 0; k < 2; ++k) \
;     dst[m][k] = *reinterpret_cast<const bf16x8*>((const char*)shm + aB + (((b) * 2 + (h)) * 16384 + (m * 2 + k) * 1024))
; #define LDB(dst, b, h) _Pragma("unroll") for (int n = 0; n < 2; ++n) _Pragma("unroll") for (int k = 0; k < 2; ++k) \
;     dst[n][k] = *reinterpret_cast<const bf16x8*>((const char*)shm + bB + (((b) * 2 + (h)) * 16384 + (n * 2 + k) * 1024))
; #define WAIT_V(n) asm volatile("s_waitcnt vmcnt(" #n ")" ::: "memory")
; #define WAIT_L(n) asm volatile("s_waitcnt lgkmcnt(" #n ")" ::: "memory")
; #define BAR __builtin_amdgcn_s_barrier()
; #define SCHED __builtin_amdgcn_sched_barrier(0)
; template <int MODE> ...
;     ...
;       LDB(B0, 0, 0); LDB(B1, 0, 1); LDA(At, 0, 0); STAGE(SA(1, 1), A, brow + HALF, nt - 1);
;       WAIT_L(0); BAR; MMA2(0, 0, 0, 1); BAR; SCHED;
;       LDA(At, 0, 1); WAIT_V(0); WAIT_L(0); BAR; MMA2(1, 0, 1, 1); BAR; SCHED;
	v_mfma_f32_16x16x32_bf16 v[124:127], v[190:193], v[138:141], v[124:127]
	v_mfma_f32_16x16x32_bf16 v[116:119], v[198:201], v[138:141], v[116:119]
	v_mfma_f32_16x16x32_bf16 v[108:111], v[206:209], v[138:141], v[108:111]
	v_mfma_f32_16x16x32_bf16 v[100:103], v[214:217], v[138:141], v[100:103]
	v_mfma_f32_16x16x32_bf16 v[96:99], v[214:217], v[146:149], v[96:99]
	v_mfma_f32_16x16x32_bf16 v[92:95], v[190:193], v[174:177], v[92:95]
	v_mfma_f32_16x16x32_bf16 v[88:91], v[190:193], v[182:185], v[88:91]
	v_mfma_f32_16x16x32_bf16 v[80:83], v[198:201], v[182:185], v[80:83]
	v_mfma_f32_16x16x32_bf16 v[76:79], v[206:209], v[174:177], v[76:79]
	v_mfma_f32_16x16x32_bf16 v[124:127], v[194:197], v[142:145], v[124:127]
	v_mfma_f32_16x16x32_bf16 v[120:123], v[190:193], v[146:149], v[120:123]
	v_mfma_f32_16x16x32_bf16 v[116:119], v[202:205], v[142:145], v[116:119]
	v_mfma_f32_16x16x32_bf16 v[112:115], v[198:201], v[146:149], v[112:115]
	v_mfma_f32_16x16x32_bf16 v[108:111], v[210:213], v[142:145], v[108:111]
	v_mfma_f32_16x16x32_bf16 v[104:107], v[206:209], v[146:149], v[104:107]
	v_mfma_f32_16x16x32_bf16 v[100:103], v[218:221], v[142:145], v[100:103]
	v_mfma_f32_16x16x32_bf16 v[96:99], v[218:221], v[170:173], v[96:99]
	v_mfma_f32_16x16x32_bf16 v[92:95], v[194:197], v[178:181], v[92:95]
	v_mfma_f32_16x16x32_bf16 v[88:91], v[194:197], v[186:189], v[88:91]
	v_mfma_f32_16x16x32_bf16 v[84:87], v[198:201], v[174:177], v[84:87]
	v_mfma_f32_16x16x32_bf16 v[80:83], v[202:205], v[186:189], v[80:83]
	v_mfma_f32_16x16x32_bf16 v[76:79], v[210:213], v[178:181], v[76:79]
	v_mfma_f32_16x16x32_bf16 v[72:75], v[206:209], v[182:185], v[72:75]
	v_mfma_f32_16x16x32_bf16 v[68:71], v[214:217], v[174:177], v[68:71]
	v_mfma_f32_16x16x32_bf16 v[64:67], v[214:217], v[182:185], v[64:67]
	v_mfma_f32_16x16x32_bf16 v[222:225], v[194:197], v[170:173], v[120:123]
	v_mfma_f32_16x16x32_bf16 v[226:229], v[202:205], v[170:173], v[112:115]
	v_mfma_f32_16x16x32_bf16 v[230:233], v[210:213], v[170:173], v[104:107]
	v_mfma_f32_16x16x32_bf16 v[190:193], v[202:205], v[178:181], v[84:87]
	v_mfma_f32_16x16x32_bf16 v[194:197], v[210:213], v[186:189], v[72:75]
	v_mfma_f32_16x16x32_bf16 v[198:201], v[218:221], v[178:181], v[68:71]
	v_mfma_f32_16x16x32_bf16 v[202:205], v[218:221], v[186:189], v[64:67]
	s_barrier
	s_setprio 0
	s_nop 0
	ds_read_b128 v[64:67], v150 offset:16384
	ds_read_b128 v[68:71], v150 offset:17408
	ds_read_b128 v[72:75], v150 offset:18432
	ds_read_b128 v[84:87], v150 offset:19456
	ds_read_b128 v[104:107], v150 offset:20480
	ds_read_b128 v[112:115], v150 offset:21504
	ds_read_b128 v[120:123], v150 offset:22528
	ds_read_b128 v[206:209], v150 offset:23552
	s_waitcnt vmcnt(0)
	s_waitcnt lgkmcnt(0)
	s_setprio 1
	s_barrier
	v_mfma_f32_16x16x32_bf16 v[60:63], v[64:67], v[138:141], v[60:63]
	v_mfma_f32_16x16x32_bf16 v[56:59], v[64:67], v[146:149], v[56:59]
	v_mfma_f32_16x16x32_bf16 v[52:55], v[72:75], v[138:141], v[52:55]
	v_mfma_f32_16x16x32_bf16 v[48:51], v[72:75], v[146:149], v[48:51]
	v_mfma_f32_16x16x32_bf16 v[44:47], v[104:107], v[138:141], v[44:47]
	v_mfma_f32_16x16x32_bf16 v[40:43], v[104:107], v[146:149], v[40:43]
	v_mfma_f32_16x16x32_bf16 v[28:31], v[64:67], v[174:177], v[28:31]
	v_mfma_f32_16x16x32_bf16 v[24:27], v[64:67], v[182:185], v[24:27]
	v_mfma_f32_16x16x32_bf16 v[20:23], v[72:75], v[174:177], v[20:23]
	v_mfma_f32_16x16x32_bf16 v[60:63], v[68:71], v[142:145], v[60:63]
	v_mfma_f32_16x16x32_bf16 v[56:59], v[68:71], v[170:173], v[56:59]
	v_mfma_f32_16x16x32_bf16 v[52:55], v[84:87], v[142:145], v[52:55]
	v_mfma_f32_16x16x32_bf16 v[48:51], v[84:87], v[170:173], v[48:51]
	v_mfma_f32_16x16x32_bf16 v[44:47], v[112:115], v[142:145], v[44:47]
	v_mfma_f32_16x16x32_bf16 v[40:43], v[112:115], v[170:173], v[40:43]
	v_mfma_f32_16x16x32_bf16 v[36:39], v[120:123], v[138:141], v[36:39]
	v_mfma_f32_16x16x32_bf16 v[32:35], v[120:123], v[146:149], v[32:35]
	v_mfma_f32_16x16x32_bf16 v[28:31], v[68:71], v[178:181], v[28:31]
	v_mfma_f32_16x16x32_bf16 v[24:27], v[68:71], v[186:189], v[24:27]
	v_mfma_f32_16x16x32_bf16 v[20:23], v[84:87], v[178:181], v[20:23]
	v_mfma_f32_16x16x32_bf16 v[16:19], v[72:75], v[182:185], v[16:19]
	v_mfma_f32_16x16x32_bf16 v[12:15], v[104:107], v[174:177], v[12:15]
	v_mfma_f32_16x16x32_bf16 v[8:11], v[104:107], v[182:185], v[8:11]
	v_mfma_f32_16x16x32_bf16 v[4:7], v[120:123], v[174:177], v[4:7]
	v_mfma_f32_16x16x32_bf16 v[0:3], v[120:123], v[182:185], v[0:3]
	v_mfma_f32_16x16x32_bf16 v[138:141], v[206:209], v[142:145], v[36:39]
	v_mfma_f32_16x16x32_bf16 v[142:145], v[206:209], v[170:173], v[32:35]
	v_mfma_f32_16x16x32_bf16 v[146:149], v[84:87], v[186:189], v[16:19]
	v_mfma_f32_16x16x32_bf16 v[170:173], v[112:115], v[178:181], v[12:15]
	v_mfma_f32_16x16x32_bf16 v[210:213], v[112:115], v[186:189], v[8:11]
	v_mfma_f32_16x16x32_bf16 v[174:177], v[206:209], v[178:181], v[4:7]
	v_mfma_f32_16x16x32_bf16 v[178:181], v[206:209], v[186:189], v[0:3]
	s_barrier
; #define LDA(dst, b, h) _Pragma("unroll") for (int m = 0; m < 4; ++m) _Pragma("unroll") for (int k = 0; k < 2; ++k) \
;     dst[m][k] = *reinterpret_cast<const bf16x8*>((const char*)shm + aB + (((b) * 2 + (h)) * 16384 + (m * 2 + k) * 1024))
; #define LDB(dst, b, h) _Pragma("unroll") for (int n = 0; n < 2; ++n) _Pragma("unroll") for (int k = 0; k < 2; ++k) \
;     dst[n][k] = *reinterpret_cast<const bf16x8*>((const char*)shm + bB + (((b) * 2 + (h)) * 16384 + (n * 2 + k) * 1024))
; #define WAIT_L(n) asm volatile("s_waitcnt lgkmcnt(" #n ")" ::: "memory")
; #define BAR __builtin_amdgcn_s_barrier()
; #define SCHED __builtin_amdgcn_sched_barrier(0)
; template <int MODE> ...
;     ...
;       LDB(B0, 1, 0); LDB(B1, 1, 1); LDA(At, 1, 0); WAIT_L(0); BAR; MMA2(0, 0, 0, 1); BAR; SCHED;
;       LDA(At, 1, 1); WAIT_L(0); BAR; MMA2(1, 0, 1, 1); BAR; SCHED;
;     }
;     ...
;     if (wr == 0) BAR;
	s_setprio 0
	ds_read_b128 v[12:15], v151 offset:32768
	ds_read_b128 v[16:19], v151 offset:33792
	ds_read_b128 v[182:185], v151 offset:34816
	ds_read_b128 v[186:189], v151 offset:35840
	ds_read_b128 v[206:209], v151 offset:49152
	ds_read_b128 v[214:217], v151 offset:50176
	ds_read_b128 v[218:221], v151 offset:51200
	ds_read_b128 v[234:237], v151 offset:52224
	ds_read_b128 v[0:3], v150 offset:32768
	ds_read_b128 v[4:7], v150 offset:33792
	ds_read_b128 v[8:11], v150 offset:34816
	ds_read_b128 v[32:35], v150 offset:35840
	ds_read_b128 v[36:39], v150 offset:36864
	ds_read_b128 v[238:241], v150 offset:37888
	ds_read_b128 v[242:245], v150 offset:38912
	ds_read_b128 v[246:249], v150 offset:39936
	s_waitcnt lgkmcnt(0)
	s_setprio 1
	s_barrier
	v_mfma_f32_16x16x32_bf16 v[64:67], v[0:3], v[12:15], v[124:127]
	v_mfma_f32_16x16x32_bf16 v[68:71], v[242:245], v[182:185], v[96:99]
	v_mfma_f32_16x16x32_bf16 v[120:123], v[4:7], v[16:19], v[64:67]
	v_mfma_f32_16x16x32_bf16 v[64:67], v[0:3], v[182:185], v[222:225]
	v_mfma_f32_16x16x32_bf16 v[84:87], v[246:249], v[186:189], v[68:71]
	v_mfma_f32_16x16x32_bf16 v[68:71], v[0:3], v[206:209], v[92:95]
	v_mfma_f32_16x16x32_bf16 v[0:3], v[0:3], v[218:221], v[88:91]
	v_mfma_f32_16x16x32_bf16 v[88:91], v[4:7], v[234:237], v[0:3]
	v_mfma_f32_16x16x32_bf16 v[0:3], v[8:11], v[206:209], v[190:193]
	v_mfma_f32_16x16x32_bf16 v[124:127], v[4:7], v[186:189], v[64:67]
	v_mfma_f32_16x16x32_bf16 v[64:67], v[8:11], v[12:15], v[116:119]
	v_mfma_f32_16x16x32_bf16 v[72:75], v[32:35], v[214:217], v[0:3]
	v_mfma_f32_16x16x32_bf16 v[0:3], v[8:11], v[218:221], v[80:83]
	v_mfma_f32_16x16x32_bf16 v[112:115], v[32:35], v[16:19], v[64:67]
	v_mfma_f32_16x16x32_bf16 v[64:67], v[8:11], v[182:185], v[226:229]
	v_mfma_f32_16x16x32_bf16 v[92:95], v[32:35], v[234:237], v[0:3]
	v_mfma_f32_16x16x32_bf16 v[0:3], v[36:39], v[206:209], v[76:79]
	v_mfma_f32_16x16x32_bf16 v[116:119], v[32:35], v[186:189], v[64:67]
	v_mfma_f32_16x16x32_bf16 v[64:67], v[36:39], v[12:15], v[108:111]
	v_mfma_f32_16x16x32_bf16 v[76:79], v[238:241], v[214:217], v[0:3]
	v_mfma_f32_16x16x32_bf16 v[0:3], v[36:39], v[218:221], v[194:197]
	v_mfma_f32_16x16x32_bf16 v[104:107], v[238:241], v[16:19], v[64:67]
	v_mfma_f32_16x16x32_bf16 v[64:67], v[36:39], v[182:185], v[230:233]
	v_mfma_f32_16x16x32_bf16 v[96:99], v[238:241], v[234:237], v[0:3]
	v_mfma_f32_16x16x32_bf16 v[0:3], v[242:245], v[206:209], v[198:201]
	v_mfma_f32_16x16x32_bf16 v[108:111], v[238:241], v[186:189], v[64:67]
	v_mfma_f32_16x16x32_bf16 v[64:67], v[242:245], v[12:15], v[100:103]
	v_mfma_f32_16x16x32_bf16 v[80:83], v[246:249], v[214:217], v[0:3]
	v_mfma_f32_16x16x32_bf16 v[0:3], v[242:245], v[218:221], v[202:205]
	v_mfma_f32_16x16x32_bf16 v[64:67], v[246:249], v[16:19], v[64:67]
	v_mfma_f32_16x16x32_bf16 v[68:71], v[4:7], v[214:217], v[68:71]
	v_mfma_f32_16x16x32_bf16 v[100:103], v[246:249], v[234:237], v[0:3]
	s_barrier
	s_setprio 0
	ds_read_b128 v[190:193], v150 offset:49152
	ds_read_b128 v[194:197], v150 offset:50176
	ds_read_b128 v[198:201], v150 offset:51200
	ds_read_b128 v[202:205], v150 offset:52224
	ds_read_b128 v[222:225], v150 offset:53248
	ds_read_b128 v[226:229], v150 offset:54272
	ds_read_b128 v[230:233], v150 offset:55296
	ds_read_b128 v[238:241], v150 offset:56320
	s_waitcnt lgkmcnt(0)
	s_setprio 1
	s_barrier
	v_mfma_f32_16x16x32_bf16 v[4:7], v[190:193], v[182:185], v[56:59]
	v_mfma_f32_16x16x32_bf16 v[8:11], v[198:201], v[182:185], v[48:51]
	v_mfma_f32_16x16x32_bf16 v[0:3], v[190:193], v[12:15], v[60:63]
	v_mfma_f32_16x16x32_bf16 v[32:35], v[194:197], v[186:189], v[4:7]
	v_mfma_f32_16x16x32_bf16 v[4:7], v[198:201], v[12:15], v[52:55]
	v_mfma_f32_16x16x32_bf16 v[36:39], v[202:205], v[186:189], v[8:11]
	v_mfma_f32_16x16x32_bf16 v[8:11], v[222:225], v[12:15], v[44:47]
	v_mfma_f32_16x16x32_bf16 v[12:15], v[230:233], v[12:15], v[138:141]
	v_mfma_f32_16x16x32_bf16 v[0:3], v[194:197], v[16:19], v[0:3]
	v_mfma_f32_16x16x32_bf16 v[4:7], v[202:205], v[16:19], v[4:7]
	v_mfma_f32_16x16x32_bf16 v[8:11], v[226:229], v[16:19], v[8:11]
	v_mfma_f32_16x16x32_bf16 v[12:15], v[238:241], v[16:19], v[12:15]
	v_mfma_f32_16x16x32_bf16 v[16:19], v[230:233], v[182:185], v[142:145]
	v_mfma_f32_16x16x32_bf16 v[24:27], v[190:193], v[218:221], v[24:27]
	v_mfma_f32_16x16x32_bf16 v[44:47], v[238:241], v[186:189], v[16:19]
	v_mfma_f32_16x16x32_bf16 v[16:19], v[190:193], v[206:209], v[28:31]
	v_mfma_f32_16x16x32_bf16 v[48:51], v[194:197], v[234:237], v[24:27]
	v_mfma_f32_16x16x32_bf16 v[24:27], v[198:201], v[218:221], v[146:149]
	v_mfma_f32_16x16x32_bf16 v[28:31], v[222:225], v[218:221], v[210:213]
	v_mfma_f32_16x16x32_bf16 v[40:43], v[222:225], v[182:185], v[40:43]
	v_mfma_f32_16x16x32_bf16 v[20:23], v[198:201], v[206:209], v[20:23]
	v_mfma_f32_16x16x32_bf16 v[52:55], v[202:205], v[234:237], v[24:27]
	v_mfma_f32_16x16x32_bf16 v[24:27], v[222:225], v[206:209], v[170:173]
	v_mfma_f32_16x16x32_bf16 v[56:59], v[226:229], v[234:237], v[28:31]
	v_mfma_f32_16x16x32_bf16 v[28:31], v[230:233], v[206:209], v[174:177]
	v_mfma_f32_16x16x32_bf16 v[60:63], v[230:233], v[218:221], v[178:181]
	v_mfma_f32_16x16x32_bf16 v[40:43], v[226:229], v[186:189], v[40:43]
	v_mfma_f32_16x16x32_bf16 v[16:19], v[194:197], v[214:217], v[16:19]
	v_mfma_f32_16x16x32_bf16 v[20:23], v[202:205], v[214:217], v[20:23]
	v_mfma_f32_16x16x32_bf16 v[24:27], v[226:229], v[214:217], v[24:27]
	v_mfma_f32_16x16x32_bf16 v[28:31], v[238:241], v[214:217], v[28:31]
	v_mfma_f32_16x16x32_bf16 v[60:63], v[238:241], v[234:237], v[60:63]
	s_barrier
	s_setprio 0
	s_and_saveexec_b64 s[60:61], s[6:7]
	s_cbranch_execz .LBB0_851
	s_barrier
